# out-proj LayerNorm epilogue hand-written: 4 quarters of 16 rows with double-buffered residual in LDS (fetch of quarter q+2 under stats/LN/stores of q,q+1), SALU DMA addressing, permlane16_swap paired
# speedup vs baseline: 1.0078x; 1.0078x over previous
; template <int N> DI void wait_vm() { asm volatile("s_waitcnt vmcnt(%0)" ::"n"(N) : "memory"); }
; DI void raw_barrier() { asm volatile("" ::: "memory"); __builtin_amdgcn_s_barrier(); asm volatile("" ::: "memory"); }
;     ...
;     for (int kt = 0; kt < KT; ++kt) {
;         if (D > 1 && kt + D - 1 < KT) wait_vm<(D - 1) * NIT>(); else wait_vm<0>();
;         raw_barrier();
;         compute(cb, kt + D < KT, kt + D, ib);
;         cb = (cb + 1 == NST) ? 0 : cb + 1;
;         ib = (ib + 1 == NST) ? 0 : ib + 1;
;     }
;     __syncthreads();
; DI void unit_O(const Params& p, char* lds, int l, int tile, int glu_tiles, int tile_b) {
;     ...
;     const float* xres = (l == 0) ? p.x : WS_PTR(const float, OFF_X1);
;     const size_t r0 = (size_t)tile * 64;
;     char* XR = lds;
;     float* GB = (float*)(lds + 131072);
;     float* red = (float*)(lds + 139264);
;     const int xrot = (int)(((blockIdx.x >> 3) + (blockIdx.x & 7) * 4) & 31) * 4;
;     const bf16_t* xbres = WS_PTR(const bf16_t, OFF_XB1) + ((size_t)((tile >> 1) * 32) * 128 + (tile & 1) * 64) * 32;
;     auto issue_x = [&](int half) {
;         if (l == 0) {
; #pragma unroll 1
;             for (int i = 0; i < 16; ++i) {
;                 const int pc = (wid * 16 + i + xrot) & 127, row = pc >> 2, phys = (pc & 3) * 64 + lane, logical = phys ^ (row & 15);
;                 __builtin_amdgcn_global_load_lds((const unsigned*)(xres + (r0 + half * 32 + row) * 1024 + logical * 4), (unsigned*)(XR + pc * 1024 + lane * 16), 16, 0, 0);
;             }
;         } else {
; #pragma unroll 1
;             for (int i = 0; i < 8; ++i) {
;                 const int pc = (wid * 8 + i + (xrot >> 1)) & 63, kt = pc >> 1, sub = pc & 1;
;                 __builtin_amdgcn_global_load_lds((const unsigned*)(xbres + ((size_t)kt * 128 + half * 32) * 32 + sub * 512 + lane * 8), (unsigned*)(XR + pc * 1024 + lane * 16), 16, 0, 0);
;             }
;         }
;     };
;     issue_x(0);
;     {
;         const float* gsrc = (tid < 256) ? (p.ln_g + l * 1024 + tid * 4) : (p.ln_b + l * 1024 + (tid - 256) * 4);
;         *(f32x4*)(GB + tid * 4) = *(const f32x4*)gsrc;
;     }
;     float* xo = (l == 0) ? WS_PTR(float, OFF_X1) : p.out;
;     bf16_t* xbo = WS_PTR(bf16_t, OFF_XB1);
.Lpo1_join:
.LBB0_100:
	s_waitcnt vmcnt(0)
	v_add_u32_e32 v0, 0x11000, v140
	s_barrier
	v_add_u32_e32 v134, v0, v141
	v_add_u32_e32 v0, v0, v139
	ds_read_b128 v[130:133], v134 offset:4096
	ds_read_b128 v[138:141], v0
	ds_read_b128 v[142:145], v134 offset:5120
	ds_read_b128 v[146:149], v0 offset:1024
	ds_read_b128 v[150:153], v134 offset:6144
	ds_read_b128 v[154:157], v134 offset:7168
	ds_read_b128 v[158:161], v134 offset:8192
	ds_read_b128 v[162:165], v134 offset:9216
	ds_read_b128 v[166:169], v134 offset:10240
	ds_read_b128 v[170:173], v134 offset:11264
	ds_read_b128 v[174:177], v0 offset:2048
	ds_read_b128 v[178:181], v0 offset:3072
	s_waitcnt lgkmcnt(0)
	v_mfma_f32_16x16x32_bf16 v[98:101], v[130:133], v[138:141], v[98:101]
	v_and_b32_e32 v197, 63, v136
	v_ashrrev_i32_e32 v236, 6, v136
	v_mfma_f32_16x16x32_bf16 v[94:97], v[142:145], v[138:141], v[94:97]
	v_mfma_f32_16x16x32_bf16 v[90:93], v[150:153], v[138:141], v[90:93]
	v_mfma_f32_16x16x32_bf16 v[86:89], v[154:157], v[138:141], v[86:89]
	v_mfma_f32_16x16x32_bf16 v[82:85], v[158:161], v[138:141], v[82:85]
	v_mfma_f32_16x16x32_bf16 v[78:81], v[162:165], v[138:141], v[78:81]
	v_mfma_f32_16x16x32_bf16 v[74:77], v[166:169], v[138:141], v[74:77]
	v_mfma_f32_16x16x32_bf16 v[70:73], v[170:173], v[138:141], v[70:73]
	v_mfma_f32_16x16x32_bf16 v[126:129], v[130:133], v[146:149], v[126:129]
	v_mfma_f32_16x16x32_bf16 v[122:125], v[142:145], v[146:149], v[122:125]
	v_mfma_f32_16x16x32_bf16 v[118:121], v[150:153], v[146:149], v[118:121]
	v_mfma_f32_16x16x32_bf16 v[114:117], v[154:157], v[146:149], v[114:117]
	v_mfma_f32_16x16x32_bf16 v[110:113], v[158:161], v[146:149], v[110:113]
	v_mfma_f32_16x16x32_bf16 v[106:109], v[162:165], v[146:149], v[106:109]
	v_mfma_f32_16x16x32_bf16 v[102:105], v[166:169], v[146:149], v[102:105]
	v_mfma_f32_16x16x32_bf16 v[66:69], v[170:173], v[146:149], v[66:69]
	v_mfma_f32_16x16x32_bf16 v[34:37], v[130:133], v[174:177], v[34:37]
	v_mfma_f32_16x16x32_bf16 v[30:33], v[142:145], v[174:177], v[30:33]
	v_mfma_f32_16x16x32_bf16 v[26:29], v[150:153], v[174:177], v[26:29]
	v_mfma_f32_16x16x32_bf16 v[22:25], v[154:157], v[174:177], v[22:25]
	v_mfma_f32_16x16x32_bf16 v[18:21], v[158:161], v[174:177], v[18:21]
	v_mfma_f32_16x16x32_bf16 v[14:17], v[162:165], v[174:177], v[14:17]
	v_mfma_f32_16x16x32_bf16 v[10:13], v[166:169], v[174:177], v[10:13]
	v_mfma_f32_16x16x32_bf16 v[6:9], v[170:173], v[174:177], v[6:9]
	v_mfma_f32_16x16x32_bf16 v[62:65], v[130:133], v[178:181], v[62:65]
	v_mfma_f32_16x16x32_bf16 v[58:61], v[142:145], v[178:181], v[58:61]
	v_mfma_f32_16x16x32_bf16 v[54:57], v[150:153], v[178:181], v[54:57]
	v_mfma_f32_16x16x32_bf16 v[50:53], v[154:157], v[178:181], v[50:53]
	v_mfma_f32_16x16x32_bf16 v[46:49], v[158:161], v[178:181], v[46:49]
	v_mfma_f32_16x16x32_bf16 v[42:45], v[162:165], v[178:181], v[42:45]
	v_mfma_f32_16x16x32_bf16 v[38:41], v[166:169], v[178:181], v[38:41]
	v_mfma_f32_16x16x32_bf16 v[2:5], v[170:173], v[178:181], v[2:5]
	s_barrier
	s_not_b64 s[6:7], s[10:11]
	v_and_b32_e32 v138, 15, v212
	v_bfe_u32 v139, v212, 4, 2
	v_lshrrev_b32_e32 v140, 6, v212
	v_and_b32_e32 v141, 63, v212
	v_readfirstlane_b32 s90, v140
	v_and_b32_e32 v142, 0xff, v212
	v_lshlrev_b32_e32 v142, 4, v142
	s_cmp_lt_u32 s90, 4
	s_cselect_b32 s92, s14, s12
	s_cselect_b32 s93, s15, s13
	s_nop 3
	global_load_dwordx4 v[176:179], v142, s[92:93]
	v_lshlrev_b32_e32 v143, 4, v212
	v_add_u32_e32 v143, 0x20000, v143
	v_lshlrev_b32_e32 v134, 6, v138
	v_add_u32_e32 v135, 0x22000, v134
	v_lshl_add_u32 v134, v140, 3, v135
	v_lshlrev_b32_e32 v136, 9, v140
	v_lshl_add_u32 v136, v139, 4, v136
	v_add_u32_e32 v136, 0x20000, v136
	s_cmp_lg_u64 s[10:11], 0
	s_cbranch_scc1 .Le1_l1
	s_lshl_b32 s40, s34, 18
	s_lshl_b32 s91, s90, 13
	s_add_u32 s96, s52, s40
	s_addc_u32 s97, s53, 0
	s_add_u32 s96, s96, s91
	s_addc_u32 s97, s97, 0
	s_lshl_b32 s40, s90, 1
	v_xor_b32_e32 v131, s40, v141
	v_lshlrev_b32_e32 v131, 4, v131
	s_add_u32 s40, s40, 1
	v_xor_b32_e32 v132, s40, v141
	v_lshlrev_b32_e32 v132, 4, v132
	v_lshlrev_b32_e32 v133, 12, v138
	v_lshl_add_u32 v133, v140, 9, v133
	v_add_u32_e32 v200, 0, v139
	v_xor_b32_e32 v200, v200, v138
	v_lshl_add_u32 v200, v200, 4, v133
	v_add_u32_e32 v204, 0x10000, v200
	v_add_u32_e32 v201, 4, v139
	v_xor_b32_e32 v201, v201, v138
	v_lshl_add_u32 v201, v201, 4, v133
	v_add_u32_e32 v205, 0x10000, v201
	v_add_u32_e32 v202, 8, v139
	v_xor_b32_e32 v202, v202, v138
	v_lshl_add_u32 v202, v202, 4, v133
	v_add_u32_e32 v206, 0x10000, v202
	v_add_u32_e32 v203, 12, v139
	v_xor_b32_e32 v203, v203, v138
	v_lshl_add_u32 v203, v203, 4, v133
	v_add_u32_e32 v207, 0x10000, v203
	v_and_b32_e32 v137, 1, v139
	v_lshlrev_b32_e32 v137, 5, v137
	v_lshrrev_b32_e32 v130, 1, v139
	v_lshl_or_b32 v137, v130, 4, v137
	v_lshl_or_b32 v137, v138, 6, v137
	v_lshl_or_b32 v137, v140, 15, v137
	s_lshr_b32 s40, s34, 1
	s_lshl_b32 s40, s40, 18
	s_and_b32 s46, s34, 1
	s_lshl_b32 s46, s46, 12
	s_add_u32 s40, s40, s46
	s_add_u32 s78, s56, s40
	s_addc_u32 s79, s57, 0
	s_add_u32 s92, s96, 0x0
	s_addc_u32 s93, s97, 0
	s_add_u32 s40, s91, 0x0
	s_mov_b32 m0, s40
	s_nop 0
	global_load_lds_dwordx4 v131, s[92:93]
	global_load_lds_dwordx4 v131, s[92:93] offset:1024
	global_load_lds_dwordx4 v131, s[92:93] offset:2048
	global_load_lds_dwordx4 v131, s[92:93] offset:3072
	s_add_u32 s92, s96, 0x1000
	s_addc_u32 s93, s97, 0
	s_add_u32 s40, s91, 0x1000
	s_mov_b32 m0, s40
	s_nop 0
	global_load_lds_dwordx4 v132, s[92:93]
	global_load_lds_dwordx4 v132, s[92:93] offset:1024
	global_load_lds_dwordx4 v132, s[92:93] offset:2048
	global_load_lds_dwordx4 v132, s[92:93] offset:3072
	s_add_u32 s92, s96, 0x10000
	s_addc_u32 s93, s97, 0
	s_add_u32 s40, s91, 0x10000
	s_mov_b32 m0, s40
	s_nop 0
	global_load_lds_dwordx4 v131, s[92:93]
	global_load_lds_dwordx4 v131, s[92:93] offset:1024
	global_load_lds_dwordx4 v131, s[92:93] offset:2048
	global_load_lds_dwordx4 v131, s[92:93] offset:3072
	s_add_u32 s92, s96, 0x11000
	s_addc_u32 s93, s97, 0
	s_add_u32 s40, s91, 0x11000
	s_mov_b32 m0, s40
	s_nop 0
	global_load_lds_dwordx4 v132, s[92:93]
	global_load_lds_dwordx4 v132, s[92:93] offset:1024
	global_load_lds_dwordx4 v132, s[92:93] offset:2048
	global_load_lds_dwordx4 v132, s[92:93] offset:3072
	s_waitcnt vmcnt(16)
	ds_write_b128 v143, v[176:179]
	s_waitcnt vmcnt(8) lgkmcnt(0)
	s_barrier
; DI float bf2f(unsigned b) { return __uint_as_float(b << 16); }
; DI void unit_O(const Params& p, char* lds, int l, int tile, int glu_tiles, int tile_b) {
;     ...
;         float s2[2], ss2[2];
; #pragma unroll
;         for (int mh = 0; mh < 2; ++mh) {
;             const int mt = half * 2 + mh, rl = mh * 16 + l15;
;             float s = 0.f, ss = 0.f;
; #pragma unroll
;             for (int nt = 0; nt < 8; ++nt) {
;                 f32x4 xr;
;                 if (l == 0) {
;                     const int chunk = wid * 32 + nt * 4 + quad;
;                     xr = *(const f32x4*)(XR + rl * 4096 + ((chunk ^ l15) << 4));
;                 } else {
;                     const u32x2 hb = *(const u32x2*)(XR + ((wid * 4 + (nt >> 1)) * 32 + rl) * 64 + (nt & 1) * 32 + quad * 8);
;                     xr = (f32x4){bf2f(hb[0] & 0xffffu), bf2f(hb[0] >> 16), bf2f(hb[1] & 0xffffu), bf2f(hb[1] >> 16)};
;                 }
; #pragma unroll
;                 for (int i = 0; i < 4; ++i) { const float v = acc[mt][nt][i] + DN_ALPHA * xr[i]; acc[mt][nt][i] = v; s += v; ss += v * v; }
;             }
;             s2[mh] = s; ss2[mh] = ss;
;         }
; #pragma unroll
;         for (int mh = 0; mh < 2; ++mh) { s2[mh] += __shfl_xor(s2[mh], 16); ss2[mh] += __shfl_xor(ss2[mh], 16); }
; #pragma unroll
;         for (int mh = 0; mh < 2; ++mh) { s2[mh] += __shfl_xor(s2[mh], 32); ss2[mh] += __shfl_xor(ss2[mh], 32); }
;         if (quad == 0) {
; #pragma unroll
;             for (int mh = 0; mh < 2; ++mh) *(f32x2*)&red[((mh * 16 + l15) * 8 + wid) * 2] = (f32x2){s2[mh], ss2[mh]};
;         }
;         __syncthreads();
;         if (half == 0) issue_x(1);
; #pragma unroll
;         for (int mh = 0; mh < 2; ++mh) {
;             const int mt = half * 2 + mh, rl = mh * 16 + l15, row = mt * 16 + l15;
;             float s = 0.f, ss = 0.f;
; #pragma unroll
;             for (int w = 0; w < 4; ++w) { const f32x4 v = *(const f32x4*)&red[rl * 16 + 4 * w]; s += v[0] + v[2]; ss += v[1] + v[3]; }
;             const float mu = s * (1.f / 1024.f);
;             const float var = ss * (1.f / 1024.f) - mu * mu;
;             const float rs = rsqrtf(var + LN_EPS);
	ds_read_b128 v[144:147], v200
	ds_read_b128 v[148:151], v201
	ds_read_b128 v[152:155], v202
	ds_read_b128 v[156:159], v203
	ds_read_b128 v[160:163], v200 offset:256
	ds_read_b128 v[164:167], v201 offset:256
	ds_read_b128 v[168:171], v202 offset:256
	ds_read_b128 v[172:175], v203 offset:256
	s_waitcnt lgkmcnt(7)
	v_fmac_f32_e32 v98, s58, v144
	v_fmac_f32_e32 v99, s58, v145
	v_fmac_f32_e32 v100, s58, v146
	v_fmac_f32_e32 v101, s58, v147
	v_mov_b32_e32 v196, v98
	v_mul_f32_e32 v197, v98, v98
	v_mov_b32_e32 v130, v99
	v_mul_f32_e32 v142, v99, v99
	v_add_f32_e32 v196, v196, v100
	v_fmac_f32_e32 v197, v100, v100
	v_add_f32_e32 v130, v130, v101
	v_fmac_f32_e32 v142, v101, v101
	s_waitcnt lgkmcnt(6)
	v_fmac_f32_e32 v94, s58, v148
	v_fmac_f32_e32 v95, s58, v149
	v_fmac_f32_e32 v96, s58, v150
	v_fmac_f32_e32 v97, s58, v151
	v_add_f32_e32 v196, v196, v94
	v_fmac_f32_e32 v197, v94, v94
	v_add_f32_e32 v130, v130, v95
	v_fmac_f32_e32 v142, v95, v95
	v_add_f32_e32 v196, v196, v96
	v_fmac_f32_e32 v197, v96, v96
	v_add_f32_e32 v130, v130, v97
	v_fmac_f32_e32 v142, v97, v97
	s_waitcnt lgkmcnt(5)
	v_fmac_f32_e32 v90, s58, v152
	v_fmac_f32_e32 v91, s58, v153
	v_fmac_f32_e32 v92, s58, v154
	v_fmac_f32_e32 v93, s58, v155
	v_add_f32_e32 v196, v196, v90
	v_fmac_f32_e32 v197, v90, v90
	v_add_f32_e32 v130, v130, v91
	v_fmac_f32_e32 v142, v91, v91
	v_add_f32_e32 v196, v196, v92
	v_fmac_f32_e32 v197, v92, v92
	v_add_f32_e32 v130, v130, v93
	v_fmac_f32_e32 v142, v93, v93
	s_waitcnt lgkmcnt(4)
	v_fmac_f32_e32 v86, s58, v156
	v_fmac_f32_e32 v87, s58, v157
	v_fmac_f32_e32 v88, s58, v158
	v_fmac_f32_e32 v89, s58, v159
	v_add_f32_e32 v196, v196, v86
	v_fmac_f32_e32 v197, v86, v86
	v_add_f32_e32 v130, v130, v87
	v_fmac_f32_e32 v142, v87, v87
	v_add_f32_e32 v196, v196, v88
	v_fmac_f32_e32 v197, v88, v88
	v_add_f32_e32 v130, v130, v89
	v_fmac_f32_e32 v142, v89, v89
	s_waitcnt lgkmcnt(3)
	v_fmac_f32_e32 v82, s58, v160
	v_fmac_f32_e32 v83, s58, v161
	v_fmac_f32_e32 v84, s58, v162
	v_fmac_f32_e32 v85, s58, v163
	v_add_f32_e32 v196, v196, v82
	v_fmac_f32_e32 v197, v82, v82
	v_add_f32_e32 v130, v130, v83
	v_fmac_f32_e32 v142, v83, v83
	v_add_f32_e32 v196, v196, v84
	v_fmac_f32_e32 v197, v84, v84
	v_add_f32_e32 v130, v130, v85
	v_fmac_f32_e32 v142, v85, v85
	s_waitcnt lgkmcnt(2)
	v_fmac_f32_e32 v78, s58, v164
	v_fmac_f32_e32 v79, s58, v165
	v_fmac_f32_e32 v80, s58, v166
	v_fmac_f32_e32 v81, s58, v167
	v_add_f32_e32 v196, v196, v78
	v_fmac_f32_e32 v197, v78, v78
	v_add_f32_e32 v130, v130, v79
	v_fmac_f32_e32 v142, v79, v79
	v_add_f32_e32 v196, v196, v80
	v_fmac_f32_e32 v197, v80, v80
	v_add_f32_e32 v130, v130, v81
	v_fmac_f32_e32 v142, v81, v81
	s_waitcnt lgkmcnt(1)
	v_fmac_f32_e32 v74, s58, v168
	v_fmac_f32_e32 v75, s58, v169
	v_fmac_f32_e32 v76, s58, v170
	v_fmac_f32_e32 v77, s58, v171
	v_add_f32_e32 v196, v196, v74
	v_fmac_f32_e32 v197, v74, v74
	v_add_f32_e32 v130, v130, v75
	v_fmac_f32_e32 v142, v75, v75
	v_add_f32_e32 v196, v196, v76
	v_fmac_f32_e32 v197, v76, v76
	v_add_f32_e32 v130, v130, v77
	v_fmac_f32_e32 v142, v77, v77
	s_waitcnt lgkmcnt(0)
	v_fmac_f32_e32 v70, s58, v172
	v_fmac_f32_e32 v71, s58, v173
	v_fmac_f32_e32 v72, s58, v174
	v_fmac_f32_e32 v73, s58, v175
	v_add_f32_e32 v196, v196, v70
	v_fmac_f32_e32 v197, v70, v70
	v_add_f32_e32 v130, v130, v71
	v_fmac_f32_e32 v142, v71, v71
	v_add_f32_e32 v196, v196, v72
	v_fmac_f32_e32 v197, v72, v72
	v_add_f32_e32 v130, v130, v73
	v_fmac_f32_e32 v142, v73, v73
	v_add_f32_e32 v196, v196, v130
	v_add_f32_e32 v197, v197, v142
	v_mov_b32_e32 v198, v196
	v_mov_b32_e32 v199, v197
	s_nop 1
	v_permlane16_swap_b32 v198, v196
	v_permlane16_swap_b32 v199, v197
	v_add_f32_e32 v196, v196, v198
	v_add_f32_e32 v197, v197, v199
	v_mov_b32_e32 v198, v196
	v_mov_b32_e32 v199, v197
	s_nop 1
	v_permlane32_swap_b32 v198, v196
	v_permlane32_swap_b32 v199, v197
	v_add_f32_e32 v196, v196, v198
	v_add_f32_e32 v197, v197, v199
	s_mov_b64 exec, 0xffff
	ds_write_b64 v134, v[196:197]
	s_mov_b64 exec, -1
	s_waitcnt lgkmcnt(0)
	s_barrier
	s_add_u32 s92, s96, 0x20000
	s_addc_u32 s93, s97, 0
	s_add_u32 s40, s91, 0x0
	s_mov_b32 m0, s40
	s_nop 0
	global_load_lds_dwordx4 v131, s[92:93]
	global_load_lds_dwordx4 v131, s[92:93] offset:1024
	global_load_lds_dwordx4 v131, s[92:93] offset:2048
	global_load_lds_dwordx4 v131, s[92:93] offset:3072
	s_add_u32 s92, s96, 0x21000
	s_addc_u32 s93, s97, 0
	s_add_u32 s40, s91, 0x1000
	s_mov_b32 m0, s40
	s_nop 0
	global_load_lds_dwordx4 v132, s[92:93]
	global_load_lds_dwordx4 v132, s[92:93] offset:1024
	global_load_lds_dwordx4 v132, s[92:93] offset:2048
	global_load_lds_dwordx4 v132, s[92:93] offset:3072
	ds_read_b128 v[160:163], v135 offset:0
	ds_read_b128 v[164:167], v135 offset:16
	ds_read_b128 v[168:171], v135 offset:32
	ds_read_b128 v[172:175], v135 offset:48
	s_waitcnt lgkmcnt(0)
	v_add_f32_e32 v160, v160, v162
	v_add_f32_e32 v161, v161, v163
	v_add_f32_e32 v164, v164, v166
	v_add_f32_e32 v165, v165, v167
	v_add_f32_e32 v168, v168, v170
	v_add_f32_e32 v169, v169, v171
	v_add_f32_e32 v172, v172, v174
	v_add_f32_e32 v173, v173, v175
	v_add_f32_e32 v160, v160, v164
	v_add_f32_e32 v161, v161, v165
	v_add_f32_e32 v168, v168, v172
	v_add_f32_e32 v169, v169, v173
	v_add_f32_e32 v160, v160, v168
	v_add_f32_e32 v161, v161, v169
	v_mul_f32_e32 v192, 0x3a800000, v160
	v_mul_f32_e32 v193, 0x3a800000, v161
	v_fma_f32 v193, -v192, v192, v193
	v_add_f32_e32 v193, 0x3727c5ac, v193
	v_rsq_f32_e32 v193, v193
	s_nop 0
	s_add_u32 s94, s78, 0x0
	s_addc_u32 s95, s79, 0
	ds_read_b128 v[176:179], v136
	ds_read_b128 v[180:183], v136 offset:4096
	ds_read_b128 v[184:187], v136 offset:64
	ds_read_b128 v[188:191], v136 offset:4160
	s_waitcnt lgkmcnt(2)
; DI unsigned pk2(float lo, float hi) { const f32x2 v = {lo, hi}; const bf16x2_t b = __builtin_convertvector(v, bf16x2_t); return __builtin_bit_cast(unsigned, b); }
; DI size_t xb_off(int tok, int col) { return ((size_t)(((tok >> 7) * 32 + (col >> 5)) * 128 + (tok & 127))) * 32 + (col & 31); }
; DI void unit_O(const Params& p, char* lds, int l, int tile, int glu_tiles, int tile_b) {
;     ...
;             float* orow = xo + (r0 + row) * 1024 + wid * 128 + quad * 4;
;             bf16_t* brow = xbo + xb_off((int)r0 + row, wid * 128) + quad * 4;
;             const float* gp = GB + wid * 128 + quad * 4;
; #pragma unroll
;             for (int nt = 0; nt < 8; ++nt) {
;                 const f32x4 g = *(const f32x4*)(gp + nt * 16), bb = *(const f32x4*)(gp + 1024 + nt * 16);
;                 f32x4 o;
; #pragma unroll
;                 for (int i = 0; i < 4; ++i) o[i] = (acc[mt][nt][i] - mu) * rs * g[i] + bb[i];
;                 if (l == 0) *(u32x2*)(brow + (nt >> 1) * 4096 + (nt & 1) * 16) = (u32x2){pk2(o[0], o[1]), pk2(o[2], o[3])};
;                 else *(f32x4*)(orow + nt * 16) = o;
;             }
	v_sub_f32_e32 v98, v98, v192
	v_mul_f32_e32 v98, v98, v193
	v_fma_f32 v98, v176, v98, v180
	v_sub_f32_e32 v99, v99, v192
	v_mul_f32_e32 v99, v99, v193
	v_fma_f32 v99, v177, v99, v181
	v_sub_f32_e32 v100, v100, v192
	v_mul_f32_e32 v100, v100, v193
	v_fma_f32 v100, v178, v100, v182
	v_sub_f32_e32 v101, v101, v192
	v_mul_f32_e32 v101, v101, v193
	v_fma_f32 v101, v179, v101, v183
	v_cvt_pk_bf16_f32 v144, v98, v99
	v_cvt_pk_bf16_f32 v145, v100, v101
	ds_read_b128 v[176:179], v136 offset:128
	ds_read_b128 v[180:183], v136 offset:4224
	s_waitcnt lgkmcnt(2)
	v_sub_f32_e32 v94, v94, v192
	v_mul_f32_e32 v94, v94, v193
	v_fma_f32 v94, v184, v94, v188
	v_sub_f32_e32 v95, v95, v192
	v_mul_f32_e32 v95, v95, v193
	v_fma_f32 v95, v185, v95, v189
	v_sub_f32_e32 v96, v96, v192
	v_mul_f32_e32 v96, v96, v193
	v_fma_f32 v96, v186, v96, v190
	v_sub_f32_e32 v97, v97, v192
	v_mul_f32_e32 v97, v97, v193
	v_fma_f32 v97, v187, v97, v191
	v_cvt_pk_bf16_f32 v146, v94, v95
	v_cvt_pk_bf16_f32 v147, v96, v97
	s_nop 1
	v_permlane16_swap_b32 v144, v146
	v_permlane16_swap_b32 v145, v147
	global_store_dwordx4 v137, v[144:147], s[94:95]
	s_add_u32 s94, s94, 0x2000
	s_addc_u32 s95, s95, 0
	ds_read_b128 v[184:187], v136 offset:192
	ds_read_b128 v[188:191], v136 offset:4288
	s_waitcnt lgkmcnt(2)
	v_sub_f32_e32 v90, v90, v192
	v_mul_f32_e32 v90, v90, v193
	v_fma_f32 v90, v176, v90, v180
	v_sub_f32_e32 v91, v91, v192
	v_mul_f32_e32 v91, v91, v193
	v_fma_f32 v91, v177, v91, v181
	v_sub_f32_e32 v92, v92, v192
	v_mul_f32_e32 v92, v92, v193
	v_fma_f32 v92, v178, v92, v182
	v_sub_f32_e32 v93, v93, v192
	v_mul_f32_e32 v93, v93, v193
	v_fma_f32 v93, v179, v93, v183
	v_cvt_pk_bf16_f32 v152, v90, v91
	v_cvt_pk_bf16_f32 v153, v92, v93
	ds_read_b128 v[176:179], v136 offset:256
	ds_read_b128 v[180:183], v136 offset:4352
	s_waitcnt lgkmcnt(2)
	v_sub_f32_e32 v86, v86, v192
	v_mul_f32_e32 v86, v86, v193
	v_fma_f32 v86, v184, v86, v188
	v_sub_f32_e32 v87, v87, v192
	v_mul_f32_e32 v87, v87, v193
	v_fma_f32 v87, v185, v87, v189
	v_sub_f32_e32 v88, v88, v192
	v_mul_f32_e32 v88, v88, v193
	v_fma_f32 v88, v186, v88, v190
	v_sub_f32_e32 v89, v89, v192
	v_mul_f32_e32 v89, v89, v193
	v_fma_f32 v89, v187, v89, v191
	v_cvt_pk_bf16_f32 v154, v86, v87
	v_cvt_pk_bf16_f32 v155, v88, v89
	s_nop 1
	v_permlane16_swap_b32 v152, v154
	v_permlane16_swap_b32 v153, v155
	global_store_dwordx4 v137, v[152:155], s[94:95]
	s_add_u32 s94, s94, 0x2000
	s_addc_u32 s95, s95, 0
	ds_read_b128 v[184:187], v136 offset:320
	ds_read_b128 v[188:191], v136 offset:4416
	s_waitcnt lgkmcnt(2)
	v_sub_f32_e32 v82, v82, v192
	v_mul_f32_e32 v82, v82, v193
	v_fma_f32 v82, v176, v82, v180
	v_sub_f32_e32 v83, v83, v192
	v_mul_f32_e32 v83, v83, v193
	v_fma_f32 v83, v177, v83, v181
	v_sub_f32_e32 v84, v84, v192
	v_mul_f32_e32 v84, v84, v193
	v_fma_f32 v84, v178, v84, v182
	v_sub_f32_e32 v85, v85, v192
	v_mul_f32_e32 v85, v85, v193
	v_fma_f32 v85, v179, v85, v183
	v_cvt_pk_bf16_f32 v144, v82, v83
	v_cvt_pk_bf16_f32 v145, v84, v85
	ds_read_b128 v[176:179], v136 offset:384
	ds_read_b128 v[180:183], v136 offset:4480
	s_waitcnt lgkmcnt(2)
	v_sub_f32_e32 v78, v78, v192
	v_mul_f32_e32 v78, v78, v193
	v_fma_f32 v78, v184, v78, v188
	v_sub_f32_e32 v79, v79, v192
	v_mul_f32_e32 v79, v79, v193
	v_fma_f32 v79, v185, v79, v189
	v_sub_f32_e32 v80, v80, v192
	v_mul_f32_e32 v80, v80, v193
	v_fma_f32 v80, v186, v80, v190
	v_sub_f32_e32 v81, v81, v192
	v_mul_f32_e32 v81, v81, v193
	v_fma_f32 v81, v187, v81, v191
	v_cvt_pk_bf16_f32 v146, v78, v79
	v_cvt_pk_bf16_f32 v147, v80, v81
	s_nop 1
	v_permlane16_swap_b32 v144, v146
	v_permlane16_swap_b32 v145, v147
	global_store_dwordx4 v137, v[144:147], s[94:95]
	s_add_u32 s94, s94, 0x2000
	s_addc_u32 s95, s95, 0
	ds_read_b128 v[184:187], v136 offset:448
	ds_read_b128 v[188:191], v136 offset:4544
	s_waitcnt lgkmcnt(2)
	v_sub_f32_e32 v74, v74, v192
	v_mul_f32_e32 v74, v74, v193
	v_fma_f32 v74, v176, v74, v180
	v_sub_f32_e32 v75, v75, v192
	v_mul_f32_e32 v75, v75, v193
	v_fma_f32 v75, v177, v75, v181
	v_sub_f32_e32 v76, v76, v192
	v_mul_f32_e32 v76, v76, v193
	v_fma_f32 v76, v178, v76, v182
	v_sub_f32_e32 v77, v77, v192
	v_mul_f32_e32 v77, v77, v193
	v_fma_f32 v77, v179, v77, v183
	v_cvt_pk_bf16_f32 v152, v74, v75
	v_cvt_pk_bf16_f32 v153, v76, v77
	s_waitcnt lgkmcnt(0)
	v_sub_f32_e32 v70, v70, v192
	v_mul_f32_e32 v70, v70, v193
	v_fma_f32 v70, v184, v70, v188
	v_sub_f32_e32 v71, v71, v192
	v_mul_f32_e32 v71, v71, v193
	v_fma_f32 v71, v185, v71, v189
	v_sub_f32_e32 v72, v72, v192
	v_mul_f32_e32 v72, v72, v193
	v_fma_f32 v72, v186, v72, v190
	v_sub_f32_e32 v73, v73, v192
	v_mul_f32_e32 v73, v73, v193
	v_fma_f32 v73, v187, v73, v191
	v_cvt_pk_bf16_f32 v154, v70, v71
	v_cvt_pk_bf16_f32 v155, v72, v73
	s_nop 1
	v_permlane16_swap_b32 v152, v154
	v_permlane16_swap_b32 v153, v155
	global_store_dwordx4 v137, v[152:155], s[94:95]
	s_waitcnt vmcnt(12) lgkmcnt(0)
	s_barrier
; DI float bf2f(unsigned b) { return __uint_as_float(b << 16); }
; DI void unit_O(const Params& p, char* lds, int l, int tile, int glu_tiles, int tile_b) {
;     ...
;         float s2[2], ss2[2];
; #pragma unroll
;         for (int mh = 0; mh < 2; ++mh) {
;             const int mt = half * 2 + mh, rl = mh * 16 + l15;
;             float s = 0.f, ss = 0.f;
; #pragma unroll
;             for (int nt = 0; nt < 8; ++nt) {
;                 f32x4 xr;
;                 if (l == 0) {
;                     const int chunk = wid * 32 + nt * 4 + quad;
;                     xr = *(const f32x4*)(XR + rl * 4096 + ((chunk ^ l15) << 4));
;                 } else {
;                     const u32x2 hb = *(const u32x2*)(XR + ((wid * 4 + (nt >> 1)) * 32 + rl) * 64 + (nt & 1) * 32 + quad * 8);
;                     xr = (f32x4){bf2f(hb[0] & 0xffffu), bf2f(hb[0] >> 16), bf2f(hb[1] & 0xffffu), bf2f(hb[1] >> 16)};
;                 }
; #pragma unroll
;                 for (int i = 0; i < 4; ++i) { const float v = acc[mt][nt][i] + DN_ALPHA * xr[i]; acc[mt][nt][i] = v; s += v; ss += v * v; }
;             }
;             s2[mh] = s; ss2[mh] = ss;
;         }
; #pragma unroll
;         for (int mh = 0; mh < 2; ++mh) { s2[mh] += __shfl_xor(s2[mh], 16); ss2[mh] += __shfl_xor(ss2[mh], 16); }
; #pragma unroll
;         for (int mh = 0; mh < 2; ++mh) { s2[mh] += __shfl_xor(s2[mh], 32); ss2[mh] += __shfl_xor(ss2[mh], 32); }
;         if (quad == 0) {
; #pragma unroll
;             for (int mh = 0; mh < 2; ++mh) *(f32x2*)&red[((mh * 16 + l15) * 8 + wid) * 2] = (f32x2){s2[mh], ss2[mh]};
;         }
;         __syncthreads();
;         if (half == 0) issue_x(1);
; #pragma unroll
;         for (int mh = 0; mh < 2; ++mh) {
;             const int mt = half * 2 + mh, rl = mh * 16 + l15, row = mt * 16 + l15;
;             float s = 0.f, ss = 0.f;
; #pragma unroll
;             for (int w = 0; w < 4; ++w) { const f32x4 v = *(const f32x4*)&red[rl * 16 + 4 * w]; s += v[0] + v[2]; ss += v[1] + v[3]; }
;             const float mu = s * (1.f / 1024.f);
;             const float var = ss * (1.f / 1024.f) - mu * mu;
;             const float rs = rsqrtf(var + LN_EPS);
	ds_read_b128 v[144:147], v204
	ds_read_b128 v[148:151], v205
	ds_read_b128 v[152:155], v206
	ds_read_b128 v[156:159], v207
	ds_read_b128 v[160:163], v204 offset:256
	ds_read_b128 v[164:167], v205 offset:256
	ds_read_b128 v[168:171], v206 offset:256
	ds_read_b128 v[172:175], v207 offset:256
	s_waitcnt lgkmcnt(7)
	v_fmac_f32_e32 v126, s58, v144
	v_fmac_f32_e32 v127, s58, v145
	v_fmac_f32_e32 v128, s58, v146
	v_fmac_f32_e32 v129, s58, v147
	v_mov_b32_e32 v196, v126
	v_mul_f32_e32 v197, v126, v126
	v_mov_b32_e32 v130, v127
	v_mul_f32_e32 v142, v127, v127
	v_add_f32_e32 v196, v196, v128
	v_fmac_f32_e32 v197, v128, v128
	v_add_f32_e32 v130, v130, v129
	v_fmac_f32_e32 v142, v129, v129
	s_waitcnt lgkmcnt(6)
	v_fmac_f32_e32 v122, s58, v148
	v_fmac_f32_e32 v123, s58, v149
	v_fmac_f32_e32 v124, s58, v150
	v_fmac_f32_e32 v125, s58, v151
	v_add_f32_e32 v196, v196, v122
	v_fmac_f32_e32 v197, v122, v122
	v_add_f32_e32 v130, v130, v123
	v_fmac_f32_e32 v142, v123, v123
	v_add_f32_e32 v196, v196, v124
	v_fmac_f32_e32 v197, v124, v124
	v_add_f32_e32 v130, v130, v125
	v_fmac_f32_e32 v142, v125, v125
	s_waitcnt lgkmcnt(5)
	v_fmac_f32_e32 v118, s58, v152
	v_fmac_f32_e32 v119, s58, v153
	v_fmac_f32_e32 v120, s58, v154
	v_fmac_f32_e32 v121, s58, v155
	v_add_f32_e32 v196, v196, v118
	v_fmac_f32_e32 v197, v118, v118
	v_add_f32_e32 v130, v130, v119
	v_fmac_f32_e32 v142, v119, v119
	v_add_f32_e32 v196, v196, v120
	v_fmac_f32_e32 v197, v120, v120
	v_add_f32_e32 v130, v130, v121
	v_fmac_f32_e32 v142, v121, v121
	s_waitcnt lgkmcnt(4)
	v_fmac_f32_e32 v114, s58, v156
	v_fmac_f32_e32 v115, s58, v157
	v_fmac_f32_e32 v116, s58, v158
	v_fmac_f32_e32 v117, s58, v159
	v_add_f32_e32 v196, v196, v114
	v_fmac_f32_e32 v197, v114, v114
	v_add_f32_e32 v130, v130, v115
	v_fmac_f32_e32 v142, v115, v115
	v_add_f32_e32 v196, v196, v116
	v_fmac_f32_e32 v197, v116, v116
	v_add_f32_e32 v130, v130, v117
	v_fmac_f32_e32 v142, v117, v117
	s_waitcnt lgkmcnt(3)
	v_fmac_f32_e32 v110, s58, v160
	v_fmac_f32_e32 v111, s58, v161
	v_fmac_f32_e32 v112, s58, v162
	v_fmac_f32_e32 v113, s58, v163
	v_add_f32_e32 v196, v196, v110
	v_fmac_f32_e32 v197, v110, v110
	v_add_f32_e32 v130, v130, v111
	v_fmac_f32_e32 v142, v111, v111
	v_add_f32_e32 v196, v196, v112
	v_fmac_f32_e32 v197, v112, v112
	v_add_f32_e32 v130, v130, v113
	v_fmac_f32_e32 v142, v113, v113
	s_waitcnt lgkmcnt(2)
	v_fmac_f32_e32 v106, s58, v164
	v_fmac_f32_e32 v107, s58, v165
	v_fmac_f32_e32 v108, s58, v166
	v_fmac_f32_e32 v109, s58, v167
	v_add_f32_e32 v196, v196, v106
	v_fmac_f32_e32 v197, v106, v106
	v_add_f32_e32 v130, v130, v107
	v_fmac_f32_e32 v142, v107, v107
	v_add_f32_e32 v196, v196, v108
	v_fmac_f32_e32 v197, v108, v108
	v_add_f32_e32 v130, v130, v109
	v_fmac_f32_e32 v142, v109, v109
	s_waitcnt lgkmcnt(1)
	v_fmac_f32_e32 v102, s58, v168
	v_fmac_f32_e32 v103, s58, v169
	v_fmac_f32_e32 v104, s58, v170
	v_fmac_f32_e32 v105, s58, v171
	v_add_f32_e32 v196, v196, v102
	v_fmac_f32_e32 v197, v102, v102
	v_add_f32_e32 v130, v130, v103
	v_fmac_f32_e32 v142, v103, v103
	v_add_f32_e32 v196, v196, v104
	v_fmac_f32_e32 v197, v104, v104
	v_add_f32_e32 v130, v130, v105
	v_fmac_f32_e32 v142, v105, v105
	s_waitcnt lgkmcnt(0)
	v_fmac_f32_e32 v66, s58, v172
	v_fmac_f32_e32 v67, s58, v173
	v_fmac_f32_e32 v68, s58, v174
	v_fmac_f32_e32 v69, s58, v175
	v_add_f32_e32 v196, v196, v66
	v_fmac_f32_e32 v197, v66, v66
	v_add_f32_e32 v130, v130, v67
	v_fmac_f32_e32 v142, v67, v67
	v_add_f32_e32 v196, v196, v68
	v_fmac_f32_e32 v197, v68, v68
	v_add_f32_e32 v130, v130, v69
	v_fmac_f32_e32 v142, v69, v69
	v_add_f32_e32 v196, v196, v130
	v_add_f32_e32 v197, v197, v142
	v_mov_b32_e32 v198, v196
	v_mov_b32_e32 v199, v197
	s_nop 1
	v_permlane16_swap_b32 v198, v196
	v_permlane16_swap_b32 v199, v197
	v_add_f32_e32 v196, v196, v198
	v_add_f32_e32 v197, v197, v199
	v_mov_b32_e32 v198, v196
	v_mov_b32_e32 v199, v197
	s_nop 1
	v_permlane32_swap_b32 v198, v196
	v_permlane32_swap_b32 v199, v197
	v_add_f32_e32 v196, v196, v198
	v_add_f32_e32 v197, v197, v199
	s_mov_b64 exec, 0xffff
	ds_write_b64 v134, v[196:197]
	s_mov_b64 exec, -1
	s_waitcnt lgkmcnt(0)
	s_barrier
	s_add_u32 s92, s96, 0x30000
	s_addc_u32 s93, s97, 0
	s_add_u32 s40, s91, 0x10000
	s_mov_b32 m0, s40
	s_nop 0
	global_load_lds_dwordx4 v131, s[92:93]
	global_load_lds_dwordx4 v131, s[92:93] offset:1024
	global_load_lds_dwordx4 v131, s[92:93] offset:2048
	global_load_lds_dwordx4 v131, s[92:93] offset:3072
	s_add_u32 s92, s96, 0x31000
	s_addc_u32 s93, s97, 0
	s_add_u32 s40, s91, 0x11000
	s_mov_b32 m0, s40
	s_nop 0
	global_load_lds_dwordx4 v132, s[92:93]
	global_load_lds_dwordx4 v132, s[92:93] offset:1024
	global_load_lds_dwordx4 v132, s[92:93] offset:2048
	global_load_lds_dwordx4 v132, s[92:93] offset:3072
	ds_read_b128 v[160:163], v135 offset:0
	ds_read_b128 v[164:167], v135 offset:16
	ds_read_b128 v[168:171], v135 offset:32
	ds_read_b128 v[172:175], v135 offset:48
	s_waitcnt lgkmcnt(0)
	v_add_f32_e32 v160, v160, v162
	v_add_f32_e32 v161, v161, v163
	v_add_f32_e32 v164, v164, v166
	v_add_f32_e32 v165, v165, v167
	v_add_f32_e32 v168, v168, v170
	v_add_f32_e32 v169, v169, v171
	v_add_f32_e32 v172, v172, v174
	v_add_f32_e32 v173, v173, v175
	v_add_f32_e32 v160, v160, v164
	v_add_f32_e32 v161, v161, v165
	v_add_f32_e32 v168, v168, v172
	v_add_f32_e32 v169, v169, v173
	v_add_f32_e32 v160, v160, v168
	v_add_f32_e32 v161, v161, v169
	v_mul_f32_e32 v192, 0x3a800000, v160
	v_mul_f32_e32 v193, 0x3a800000, v161
	v_fma_f32 v193, -v192, v192, v193
	v_add_f32_e32 v193, 0x3727c5ac, v193
	v_rsq_f32_e32 v193, v193
	s_nop 0
	s_add_u32 s94, s78, 0x400
	s_addc_u32 s95, s79, 0
	ds_read_b128 v[176:179], v136
	ds_read_b128 v[180:183], v136 offset:4096
	ds_read_b128 v[184:187], v136 offset:64
	ds_read_b128 v[188:191], v136 offset:4160
	s_waitcnt lgkmcnt(2)
; DI unsigned pk2(float lo, float hi) { const f32x2 v = {lo, hi}; const bf16x2_t b = __builtin_convertvector(v, bf16x2_t); return __builtin_bit_cast(unsigned, b); }
; DI size_t xb_off(int tok, int col) { return ((size_t)(((tok >> 7) * 32 + (col >> 5)) * 128 + (tok & 127))) * 32 + (col & 31); }
; DI void unit_O(const Params& p, char* lds, int l, int tile, int glu_tiles, int tile_b) {
;     ...
;             float* orow = xo + (r0 + row) * 1024 + wid * 128 + quad * 4;
;             bf16_t* brow = xbo + xb_off((int)r0 + row, wid * 128) + quad * 4;
;             const float* gp = GB + wid * 128 + quad * 4;
; #pragma unroll
;             for (int nt = 0; nt < 8; ++nt) {
;                 const f32x4 g = *(const f32x4*)(gp + nt * 16), bb = *(const f32x4*)(gp + 1024 + nt * 16);
;                 f32x4 o;
; #pragma unroll
;                 for (int i = 0; i < 4; ++i) o[i] = (acc[mt][nt][i] - mu) * rs * g[i] + bb[i];
;                 if (l == 0) *(u32x2*)(brow + (nt >> 1) * 4096 + (nt & 1) * 16) = (u32x2){pk2(o[0], o[1]), pk2(o[2], o[3])};
;                 else *(f32x4*)(orow + nt * 16) = o;
;             }
	v_sub_f32_e32 v126, v126, v192
	v_mul_f32_e32 v126, v126, v193
	v_fma_f32 v126, v176, v126, v180
	v_sub_f32_e32 v127, v127, v192
	v_mul_f32_e32 v127, v127, v193
	v_fma_f32 v127, v177, v127, v181
	v_sub_f32_e32 v128, v128, v192
	v_mul_f32_e32 v128, v128, v193
	v_fma_f32 v128, v178, v128, v182
	v_sub_f32_e32 v129, v129, v192
	v_mul_f32_e32 v129, v129, v193
	v_fma_f32 v129, v179, v129, v183
	v_cvt_pk_bf16_f32 v144, v126, v127
	v_cvt_pk_bf16_f32 v145, v128, v129
	ds_read_b128 v[176:179], v136 offset:128
	ds_read_b128 v[180:183], v136 offset:4224
	s_waitcnt lgkmcnt(2)
	v_sub_f32_e32 v122, v122, v192
	v_mul_f32_e32 v122, v122, v193
	v_fma_f32 v122, v184, v122, v188
	v_sub_f32_e32 v123, v123, v192
	v_mul_f32_e32 v123, v123, v193
	v_fma_f32 v123, v185, v123, v189
	v_sub_f32_e32 v124, v124, v192
	v_mul_f32_e32 v124, v124, v193
	v_fma_f32 v124, v186, v124, v190
	v_sub_f32_e32 v125, v125, v192
	v_mul_f32_e32 v125, v125, v193
	v_fma_f32 v125, v187, v125, v191
	v_cvt_pk_bf16_f32 v146, v122, v123
	v_cvt_pk_bf16_f32 v147, v124, v125
	s_nop 1
	v_permlane16_swap_b32 v144, v146
	v_permlane16_swap_b32 v145, v147
	global_store_dwordx4 v137, v[144:147], s[94:95]
	s_add_u32 s94, s94, 0x2000
	s_addc_u32 s95, s95, 0
	ds_read_b128 v[184:187], v136 offset:192
	ds_read_b128 v[188:191], v136 offset:4288
	s_waitcnt lgkmcnt(2)
	v_sub_f32_e32 v118, v118, v192
	v_mul_f32_e32 v118, v118, v193
	v_fma_f32 v118, v176, v118, v180
	v_sub_f32_e32 v119, v119, v192
	v_mul_f32_e32 v119, v119, v193
	v_fma_f32 v119, v177, v119, v181
	v_sub_f32_e32 v120, v120, v192
	v_mul_f32_e32 v120, v120, v193
	v_fma_f32 v120, v178, v120, v182
	v_sub_f32_e32 v121, v121, v192
	v_mul_f32_e32 v121, v121, v193
	v_fma_f32 v121, v179, v121, v183
	v_cvt_pk_bf16_f32 v152, v118, v119
	v_cvt_pk_bf16_f32 v153, v120, v121
	ds_read_b128 v[176:179], v136 offset:256
	ds_read_b128 v[180:183], v136 offset:4352
	s_waitcnt lgkmcnt(2)
	v_sub_f32_e32 v114, v114, v192
	v_mul_f32_e32 v114, v114, v193
	v_fma_f32 v114, v184, v114, v188
	v_sub_f32_e32 v115, v115, v192
	v_mul_f32_e32 v115, v115, v193
	v_fma_f32 v115, v185, v115, v189
	v_sub_f32_e32 v116, v116, v192
	v_mul_f32_e32 v116, v116, v193
	v_fma_f32 v116, v186, v116, v190
	v_sub_f32_e32 v117, v117, v192
	v_mul_f32_e32 v117, v117, v193
	v_fma_f32 v117, v187, v117, v191
	v_cvt_pk_bf16_f32 v154, v114, v115
	v_cvt_pk_bf16_f32 v155, v116, v117
	s_nop 1
	v_permlane16_swap_b32 v152, v154
	v_permlane16_swap_b32 v153, v155
	global_store_dwordx4 v137, v[152:155], s[94:95]
	s_add_u32 s94, s94, 0x2000
	s_addc_u32 s95, s95, 0
	ds_read_b128 v[184:187], v136 offset:320
	ds_read_b128 v[188:191], v136 offset:4416
	s_waitcnt lgkmcnt(2)
	v_sub_f32_e32 v110, v110, v192
	v_mul_f32_e32 v110, v110, v193
	v_fma_f32 v110, v176, v110, v180
	v_sub_f32_e32 v111, v111, v192
	v_mul_f32_e32 v111, v111, v193
	v_fma_f32 v111, v177, v111, v181
	v_sub_f32_e32 v112, v112, v192
	v_mul_f32_e32 v112, v112, v193
	v_fma_f32 v112, v178, v112, v182
	v_sub_f32_e32 v113, v113, v192
	v_mul_f32_e32 v113, v113, v193
	v_fma_f32 v113, v179, v113, v183
	v_cvt_pk_bf16_f32 v144, v110, v111
	v_cvt_pk_bf16_f32 v145, v112, v113
	ds_read_b128 v[176:179], v136 offset:384
	ds_read_b128 v[180:183], v136 offset:4480
	s_waitcnt lgkmcnt(2)
	v_sub_f32_e32 v106, v106, v192
	v_mul_f32_e32 v106, v106, v193
	v_fma_f32 v106, v184, v106, v188
	v_sub_f32_e32 v107, v107, v192
	v_mul_f32_e32 v107, v107, v193
	v_fma_f32 v107, v185, v107, v189
	v_sub_f32_e32 v108, v108, v192
	v_mul_f32_e32 v108, v108, v193
	v_fma_f32 v108, v186, v108, v190
	v_sub_f32_e32 v109, v109, v192
	v_mul_f32_e32 v109, v109, v193
	v_fma_f32 v109, v187, v109, v191
	v_cvt_pk_bf16_f32 v146, v106, v107
	v_cvt_pk_bf16_f32 v147, v108, v109
	s_nop 1
	v_permlane16_swap_b32 v144, v146
	v_permlane16_swap_b32 v145, v147
	global_store_dwordx4 v137, v[144:147], s[94:95]
	s_add_u32 s94, s94, 0x2000
	s_addc_u32 s95, s95, 0
	ds_read_b128 v[184:187], v136 offset:448
	ds_read_b128 v[188:191], v136 offset:4544
	s_waitcnt lgkmcnt(2)
	v_sub_f32_e32 v102, v102, v192
	v_mul_f32_e32 v102, v102, v193
	v_fma_f32 v102, v176, v102, v180
	v_sub_f32_e32 v103, v103, v192
	v_mul_f32_e32 v103, v103, v193
	v_fma_f32 v103, v177, v103, v181
	v_sub_f32_e32 v104, v104, v192
	v_mul_f32_e32 v104, v104, v193
	v_fma_f32 v104, v178, v104, v182
	v_sub_f32_e32 v105, v105, v192
	v_mul_f32_e32 v105, v105, v193
	v_fma_f32 v105, v179, v105, v183
	v_cvt_pk_bf16_f32 v152, v102, v103
	v_cvt_pk_bf16_f32 v153, v104, v105
	s_waitcnt lgkmcnt(0)
	v_sub_f32_e32 v66, v66, v192
	v_mul_f32_e32 v66, v66, v193
	v_fma_f32 v66, v184, v66, v188
	v_sub_f32_e32 v67, v67, v192
	v_mul_f32_e32 v67, v67, v193
	v_fma_f32 v67, v185, v67, v189
	v_sub_f32_e32 v68, v68, v192
	v_mul_f32_e32 v68, v68, v193
	v_fma_f32 v68, v186, v68, v190
	v_sub_f32_e32 v69, v69, v192
	v_mul_f32_e32 v69, v69, v193
	v_fma_f32 v69, v187, v69, v191
	v_cvt_pk_bf16_f32 v154, v66, v67
	v_cvt_pk_bf16_f32 v155, v68, v69
	s_nop 1
	v_permlane16_swap_b32 v152, v154
	v_permlane16_swap_b32 v153, v155
	global_store_dwordx4 v137, v[152:155], s[94:95]
	s_waitcnt vmcnt(16) lgkmcnt(0)
	s_barrier
; DI void unit_O(const Params& p, char* lds, int l, int tile, int glu_tiles, int tile_b) {
;     ...
;         float s2[2], ss2[2];
; #pragma unroll
;         for (int mh = 0; mh < 2; ++mh) {
;             const int mt = half * 2 + mh, rl = mh * 16 + l15;
;             float s = 0.f, ss = 0.f;
; #pragma unroll
;             for (int nt = 0; nt < 8; ++nt) {
;                 f32x4 xr;
;                 if (l == 0) {
;                     const int chunk = wid * 32 + nt * 4 + quad;
;                     xr = *(const f32x4*)(XR + rl * 4096 + ((chunk ^ l15) << 4));
;                 } else {
;                     const u32x2 hb = *(const u32x2*)(XR + ((wid * 4 + (nt >> 1)) * 32 + rl) * 64 + (nt & 1) * 32 + quad * 8);
;                     xr = (f32x4){bf2f(hb[0] & 0xffffu), bf2f(hb[0] >> 16), bf2f(hb[1] & 0xffffu), bf2f(hb[1] >> 16)};
;                 }
; #pragma unroll
;                 for (int i = 0; i < 4; ++i) { const float v = acc[mt][nt][i] + DN_ALPHA * xr[i]; acc[mt][nt][i] = v; s += v; ss += v * v; }
;             }
;             s2[mh] = s; ss2[mh] = ss;
;         }
; #pragma unroll
;         for (int mh = 0; mh < 2; ++mh) { s2[mh] += __shfl_xor(s2[mh], 16); ss2[mh] += __shfl_xor(ss2[mh], 16); }
; #pragma unroll
;         for (int mh = 0; mh < 2; ++mh) { s2[mh] += __shfl_xor(s2[mh], 32); ss2[mh] += __shfl_xor(ss2[mh], 32); }
;         if (quad == 0) {
; #pragma unroll
;             for (int mh = 0; mh < 2; ++mh) *(f32x2*)&red[((mh * 16 + l15) * 8 + wid) * 2] = (f32x2){s2[mh], ss2[mh]};
;         }
;         __syncthreads();
;         if (half == 0) issue_x(1);
; #pragma unroll
;         for (int mh = 0; mh < 2; ++mh) {
;             const int mt = half * 2 + mh, rl = mh * 16 + l15, row = mt * 16 + l15;
;             float s = 0.f, ss = 0.f;
; #pragma unroll
;             for (int w = 0; w < 4; ++w) { const f32x4 v = *(const f32x4*)&red[rl * 16 + 4 * w]; s += v[0] + v[2]; ss += v[1] + v[3]; }
;             const float mu = s * (1.f / 1024.f);
;             const float var = ss * (1.f / 1024.f) - mu * mu;
;             const float rs = rsqrtf(var + LN_EPS);
;             float* orow = xo + (r0 + row) * 1024 + wid * 128 + quad * 4;
;             bf16_t* brow = xbo + xb_off((int)r0 + row, wid * 128) + quad * 4;
;             const float* gp = GB + wid * 128 + quad * 4;
; #pragma unroll
;             for (int nt = 0; nt < 8; ++nt) {
	ds_read_b128 v[144:147], v200
	ds_read_b128 v[148:151], v201
	ds_read_b128 v[152:155], v202
	ds_read_b128 v[156:159], v203
	ds_read_b128 v[160:163], v200 offset:256
	ds_read_b128 v[164:167], v201 offset:256
	ds_read_b128 v[168:171], v202 offset:256
	ds_read_b128 v[172:175], v203 offset:256
	s_waitcnt lgkmcnt(7)
	v_fmac_f32_e32 v34, s58, v144
	v_fmac_f32_e32 v35, s58, v145
	v_fmac_f32_e32 v36, s58, v146
	v_fmac_f32_e32 v37, s58, v147
	v_mov_b32_e32 v196, v34
	v_mul_f32_e32 v197, v34, v34
	v_mov_b32_e32 v130, v35
	v_mul_f32_e32 v142, v35, v35
	v_add_f32_e32 v196, v196, v36
	v_fmac_f32_e32 v197, v36, v36
	v_add_f32_e32 v130, v130, v37
	v_fmac_f32_e32 v142, v37, v37
	s_waitcnt lgkmcnt(6)
	v_fmac_f32_e32 v30, s58, v148
	v_fmac_f32_e32 v31, s58, v149
	v_fmac_f32_e32 v32, s58, v150
	v_fmac_f32_e32 v33, s58, v151
	v_add_f32_e32 v196, v196, v30
	v_fmac_f32_e32 v197, v30, v30
	v_add_f32_e32 v130, v130, v31
	v_fmac_f32_e32 v142, v31, v31
	v_add_f32_e32 v196, v196, v32
	v_fmac_f32_e32 v197, v32, v32
	v_add_f32_e32 v130, v130, v33
	v_fmac_f32_e32 v142, v33, v33
	s_waitcnt lgkmcnt(5)
	v_fmac_f32_e32 v26, s58, v152
	v_fmac_f32_e32 v27, s58, v153
	v_fmac_f32_e32 v28, s58, v154
	v_fmac_f32_e32 v29, s58, v155
	v_add_f32_e32 v196, v196, v26
	v_fmac_f32_e32 v197, v26, v26
	v_add_f32_e32 v130, v130, v27
	v_fmac_f32_e32 v142, v27, v27
	v_add_f32_e32 v196, v196, v28
	v_fmac_f32_e32 v197, v28, v28
	v_add_f32_e32 v130, v130, v29
	v_fmac_f32_e32 v142, v29, v29
	s_waitcnt lgkmcnt(4)
	v_fmac_f32_e32 v22, s58, v156
	v_fmac_f32_e32 v23, s58, v157
	v_fmac_f32_e32 v24, s58, v158
	v_fmac_f32_e32 v25, s58, v159
	v_add_f32_e32 v196, v196, v22
	v_fmac_f32_e32 v197, v22, v22
	v_add_f32_e32 v130, v130, v23
	v_fmac_f32_e32 v142, v23, v23
	v_add_f32_e32 v196, v196, v24
	v_fmac_f32_e32 v197, v24, v24
	v_add_f32_e32 v130, v130, v25
	v_fmac_f32_e32 v142, v25, v25
	s_waitcnt lgkmcnt(3)
	v_fmac_f32_e32 v18, s58, v160
	v_fmac_f32_e32 v19, s58, v161
	v_fmac_f32_e32 v20, s58, v162
	v_fmac_f32_e32 v21, s58, v163
	v_add_f32_e32 v196, v196, v18
	v_fmac_f32_e32 v197, v18, v18
	v_add_f32_e32 v130, v130, v19
	v_fmac_f32_e32 v142, v19, v19
	v_add_f32_e32 v196, v196, v20
	v_fmac_f32_e32 v197, v20, v20
	v_add_f32_e32 v130, v130, v21
	v_fmac_f32_e32 v142, v21, v21
	s_waitcnt lgkmcnt(2)
	v_fmac_f32_e32 v14, s58, v164
	v_fmac_f32_e32 v15, s58, v165
	v_fmac_f32_e32 v16, s58, v166
	v_fmac_f32_e32 v17, s58, v167
	v_add_f32_e32 v196, v196, v14
	v_fmac_f32_e32 v197, v14, v14
	v_add_f32_e32 v130, v130, v15
	v_fmac_f32_e32 v142, v15, v15
	v_add_f32_e32 v196, v196, v16
	v_fmac_f32_e32 v197, v16, v16
	v_add_f32_e32 v130, v130, v17
	v_fmac_f32_e32 v142, v17, v17
	s_waitcnt lgkmcnt(1)
	v_fmac_f32_e32 v10, s58, v168
	v_fmac_f32_e32 v11, s58, v169
	v_fmac_f32_e32 v12, s58, v170
	v_fmac_f32_e32 v13, s58, v171
	v_add_f32_e32 v196, v196, v10
	v_fmac_f32_e32 v197, v10, v10
	v_add_f32_e32 v130, v130, v11
	v_fmac_f32_e32 v142, v11, v11
	v_add_f32_e32 v196, v196, v12
	v_fmac_f32_e32 v197, v12, v12
	v_add_f32_e32 v130, v130, v13
	v_fmac_f32_e32 v142, v13, v13
	s_waitcnt lgkmcnt(0)
	v_fmac_f32_e32 v6, s58, v172
	v_fmac_f32_e32 v7, s58, v173
	v_fmac_f32_e32 v8, s58, v174
	v_fmac_f32_e32 v9, s58, v175
	v_add_f32_e32 v196, v196, v6
	v_fmac_f32_e32 v197, v6, v6
	v_add_f32_e32 v130, v130, v7
	v_fmac_f32_e32 v142, v7, v7
	v_add_f32_e32 v196, v196, v8
	v_fmac_f32_e32 v197, v8, v8
	v_add_f32_e32 v130, v130, v9
	v_fmac_f32_e32 v142, v9, v9
	v_add_f32_e32 v196, v196, v130
	v_add_f32_e32 v197, v197, v142
	v_mov_b32_e32 v198, v196
	v_mov_b32_e32 v199, v197
	s_nop 1
	v_permlane16_swap_b32 v198, v196
	v_permlane16_swap_b32 v199, v197
	v_add_f32_e32 v196, v196, v198
	v_add_f32_e32 v197, v197, v199
	v_mov_b32_e32 v198, v196
	v_mov_b32_e32 v199, v197
	s_nop 1
	v_permlane32_swap_b32 v198, v196
	v_permlane32_swap_b32 v199, v197
	v_add_f32_e32 v196, v196, v198
	v_add_f32_e32 v197, v197, v199
	s_mov_b64 exec, 0xffff
	ds_write_b64 v134, v[196:197]
	s_mov_b64 exec, -1
	s_waitcnt lgkmcnt(0)
	s_barrier
	ds_read_b128 v[160:163], v135 offset:0
	ds_read_b128 v[164:167], v135 offset:16
	ds_read_b128 v[168:171], v135 offset:32
	ds_read_b128 v[172:175], v135 offset:48
	s_waitcnt lgkmcnt(0)
	v_add_f32_e32 v160, v160, v162
	v_add_f32_e32 v161, v161, v163
	v_add_f32_e32 v164, v164, v166
	v_add_f32_e32 v165, v165, v167
	v_add_f32_e32 v168, v168, v170
	v_add_f32_e32 v169, v169, v171
	v_add_f32_e32 v172, v172, v174
	v_add_f32_e32 v173, v173, v175
	v_add_f32_e32 v160, v160, v164
	v_add_f32_e32 v161, v161, v165
	v_add_f32_e32 v168, v168, v172
	v_add_f32_e32 v169, v169, v173
	v_add_f32_e32 v160, v160, v168
	v_add_f32_e32 v161, v161, v169
	v_mul_f32_e32 v192, 0x3a800000, v160
	v_mul_f32_e32 v193, 0x3a800000, v161
	v_fma_f32 v193, -v192, v192, v193
	v_add_f32_e32 v193, 0x3727c5ac, v193
	v_rsq_f32_e32 v193, v193
	s_nop 0
	s_add_u32 s94, s78, 0x800
	s_addc_u32 s95, s79, 0
	ds_read_b128 v[176:179], v136
	ds_read_b128 v[180:183], v136 offset:4096
	ds_read_b128 v[184:187], v136 offset:64
	ds_read_b128 v[188:191], v136 offset:4160
	s_waitcnt lgkmcnt(2)
	v_sub_f32_e32 v34, v34, v192
	v_mul_f32_e32 v34, v34, v193
	v_fma_f32 v34, v176, v34, v180
	v_sub_f32_e32 v35, v35, v192
	v_mul_f32_e32 v35, v35, v193
	v_fma_f32 v35, v177, v35, v181
	v_sub_f32_e32 v36, v36, v192
	v_mul_f32_e32 v36, v36, v193
	v_fma_f32 v36, v178, v36, v182
	v_sub_f32_e32 v37, v37, v192
	v_mul_f32_e32 v37, v37, v193
	v_fma_f32 v37, v179, v37, v183
	v_cvt_pk_bf16_f32 v144, v34, v35
	v_cvt_pk_bf16_f32 v145, v36, v37
	ds_read_b128 v[176:179], v136 offset:128
	ds_read_b128 v[180:183], v136 offset:4224
	s_waitcnt lgkmcnt(2)
; DI unsigned pk2(float lo, float hi) { const f32x2 v = {lo, hi}; const bf16x2_t b = __builtin_convertvector(v, bf16x2_t); return __builtin_bit_cast(unsigned, b); }
; DI size_t xb_off(int tok, int col) { return ((size_t)(((tok >> 7) * 32 + (col >> 5)) * 128 + (tok & 127))) * 32 + (col & 31); }
; DI void unit_O(const Params& p, char* lds, int l, int tile, int glu_tiles, int tile_b) {
;     ...
;             float* orow = xo + (r0 + row) * 1024 + wid * 128 + quad * 4;
;             bf16_t* brow = xbo + xb_off((int)r0 + row, wid * 128) + quad * 4;
;             const float* gp = GB + wid * 128 + quad * 4;
; #pragma unroll
;             for (int nt = 0; nt < 8; ++nt) {
;                 const f32x4 g = *(const f32x4*)(gp + nt * 16), bb = *(const f32x4*)(gp + 1024 + nt * 16);
;                 f32x4 o;
; #pragma unroll
;                 for (int i = 0; i < 4; ++i) o[i] = (acc[mt][nt][i] - mu) * rs * g[i] + bb[i];
;                 if (l == 0) *(u32x2*)(brow + (nt >> 1) * 4096 + (nt & 1) * 16) = (u32x2){pk2(o[0], o[1]), pk2(o[2], o[3])};
;                 else *(f32x4*)(orow + nt * 16) = o;
;             }
	v_sub_f32_e32 v30, v30, v192
	v_mul_f32_e32 v30, v30, v193
	v_fma_f32 v30, v184, v30, v188
	v_sub_f32_e32 v31, v31, v192
	v_mul_f32_e32 v31, v31, v193
	v_fma_f32 v31, v185, v31, v189
	v_sub_f32_e32 v32, v32, v192
	v_mul_f32_e32 v32, v32, v193
	v_fma_f32 v32, v186, v32, v190
	v_sub_f32_e32 v33, v33, v192
	v_mul_f32_e32 v33, v33, v193
	v_fma_f32 v33, v187, v33, v191
	v_cvt_pk_bf16_f32 v146, v30, v31
	v_cvt_pk_bf16_f32 v147, v32, v33
	s_nop 1
	v_permlane16_swap_b32 v144, v146
	v_permlane16_swap_b32 v145, v147
	global_store_dwordx4 v137, v[144:147], s[94:95]
	s_add_u32 s94, s94, 0x2000
	s_addc_u32 s95, s95, 0
	ds_read_b128 v[184:187], v136 offset:192
	ds_read_b128 v[188:191], v136 offset:4288
	s_waitcnt lgkmcnt(2)
	v_sub_f32_e32 v26, v26, v192
	v_mul_f32_e32 v26, v26, v193
	v_fma_f32 v26, v176, v26, v180
	v_sub_f32_e32 v27, v27, v192
	v_mul_f32_e32 v27, v27, v193
	v_fma_f32 v27, v177, v27, v181
	v_sub_f32_e32 v28, v28, v192
	v_mul_f32_e32 v28, v28, v193
	v_fma_f32 v28, v178, v28, v182
	v_sub_f32_e32 v29, v29, v192
	v_mul_f32_e32 v29, v29, v193
	v_fma_f32 v29, v179, v29, v183
	v_cvt_pk_bf16_f32 v152, v26, v27
	v_cvt_pk_bf16_f32 v153, v28, v29
	ds_read_b128 v[176:179], v136 offset:256
	ds_read_b128 v[180:183], v136 offset:4352
	s_waitcnt lgkmcnt(2)
	v_sub_f32_e32 v22, v22, v192
	v_mul_f32_e32 v22, v22, v193
	v_fma_f32 v22, v184, v22, v188
	v_sub_f32_e32 v23, v23, v192
	v_mul_f32_e32 v23, v23, v193
	v_fma_f32 v23, v185, v23, v189
	v_sub_f32_e32 v24, v24, v192
	v_mul_f32_e32 v24, v24, v193
	v_fma_f32 v24, v186, v24, v190
	v_sub_f32_e32 v25, v25, v192
	v_mul_f32_e32 v25, v25, v193
	v_fma_f32 v25, v187, v25, v191
	v_cvt_pk_bf16_f32 v154, v22, v23
	v_cvt_pk_bf16_f32 v155, v24, v25
	s_nop 1
	v_permlane16_swap_b32 v152, v154
	v_permlane16_swap_b32 v153, v155
	global_store_dwordx4 v137, v[152:155], s[94:95]
	s_add_u32 s94, s94, 0x2000
	s_addc_u32 s95, s95, 0
	ds_read_b128 v[184:187], v136 offset:320
	ds_read_b128 v[188:191], v136 offset:4416
	s_waitcnt lgkmcnt(2)
	v_sub_f32_e32 v18, v18, v192
	v_mul_f32_e32 v18, v18, v193
	v_fma_f32 v18, v176, v18, v180
	v_sub_f32_e32 v19, v19, v192
	v_mul_f32_e32 v19, v19, v193
	v_fma_f32 v19, v177, v19, v181
	v_sub_f32_e32 v20, v20, v192
	v_mul_f32_e32 v20, v20, v193
	v_fma_f32 v20, v178, v20, v182
	v_sub_f32_e32 v21, v21, v192
	v_mul_f32_e32 v21, v21, v193
	v_fma_f32 v21, v179, v21, v183
	v_cvt_pk_bf16_f32 v144, v18, v19
	v_cvt_pk_bf16_f32 v145, v20, v21
	ds_read_b128 v[176:179], v136 offset:384
	ds_read_b128 v[180:183], v136 offset:4480
	s_waitcnt lgkmcnt(2)
	v_sub_f32_e32 v14, v14, v192
	v_mul_f32_e32 v14, v14, v193
	v_fma_f32 v14, v184, v14, v188
	v_sub_f32_e32 v15, v15, v192
	v_mul_f32_e32 v15, v15, v193
	v_fma_f32 v15, v185, v15, v189
	v_sub_f32_e32 v16, v16, v192
	v_mul_f32_e32 v16, v16, v193
	v_fma_f32 v16, v186, v16, v190
	v_sub_f32_e32 v17, v17, v192
	v_mul_f32_e32 v17, v17, v193
	v_fma_f32 v17, v187, v17, v191
	v_cvt_pk_bf16_f32 v146, v14, v15
	v_cvt_pk_bf16_f32 v147, v16, v17
	s_nop 1
	v_permlane16_swap_b32 v144, v146
	v_permlane16_swap_b32 v145, v147
	global_store_dwordx4 v137, v[144:147], s[94:95]
	s_add_u32 s94, s94, 0x2000
	s_addc_u32 s95, s95, 0
	ds_read_b128 v[184:187], v136 offset:448
	ds_read_b128 v[188:191], v136 offset:4544
	s_waitcnt lgkmcnt(2)
	v_sub_f32_e32 v10, v10, v192
	v_mul_f32_e32 v10, v10, v193
	v_fma_f32 v10, v176, v10, v180
	v_sub_f32_e32 v11, v11, v192
	v_mul_f32_e32 v11, v11, v193
	v_fma_f32 v11, v177, v11, v181
	v_sub_f32_e32 v12, v12, v192
	v_mul_f32_e32 v12, v12, v193
	v_fma_f32 v12, v178, v12, v182
	v_sub_f32_e32 v13, v13, v192
	v_mul_f32_e32 v13, v13, v193
	v_fma_f32 v13, v179, v13, v183
	v_cvt_pk_bf16_f32 v152, v10, v11
	v_cvt_pk_bf16_f32 v153, v12, v13
	s_waitcnt lgkmcnt(0)
	v_sub_f32_e32 v6, v6, v192
	v_mul_f32_e32 v6, v6, v193
	v_fma_f32 v6, v184, v6, v188
	v_sub_f32_e32 v7, v7, v192
	v_mul_f32_e32 v7, v7, v193
	v_fma_f32 v7, v185, v7, v189
	v_sub_f32_e32 v8, v8, v192
	v_mul_f32_e32 v8, v8, v193
	v_fma_f32 v8, v186, v8, v190
	v_sub_f32_e32 v9, v9, v192
	v_mul_f32_e32 v9, v9, v193
	v_fma_f32 v9, v187, v9, v191
	v_cvt_pk_bf16_f32 v154, v6, v7
	v_cvt_pk_bf16_f32 v155, v8, v9
	s_nop 1
	v_permlane16_swap_b32 v152, v154
	v_permlane16_swap_b32 v153, v155
	global_store_dwordx4 v137, v[152:155], s[94:95]
	s_waitcnt vmcnt(8) lgkmcnt(0)
	s_barrier
; DI void unit_O(const Params& p, char* lds, int l, int tile, int glu_tiles, int tile_b) {
;     ...
;         float s2[2], ss2[2];
; #pragma unroll
;         for (int mh = 0; mh < 2; ++mh) {
;             const int mt = half * 2 + mh, rl = mh * 16 + l15;
;             float s = 0.f, ss = 0.f;
; #pragma unroll
;             for (int nt = 0; nt < 8; ++nt) {
;                 f32x4 xr;
;                 if (l == 0) {
;                     const int chunk = wid * 32 + nt * 4 + quad;
;                     xr = *(const f32x4*)(XR + rl * 4096 + ((chunk ^ l15) << 4));
;                 } else {
;                     const u32x2 hb = *(const u32x2*)(XR + ((wid * 4 + (nt >> 1)) * 32 + rl) * 64 + (nt & 1) * 32 + quad * 8);
;                     xr = (f32x4){bf2f(hb[0] & 0xffffu), bf2f(hb[0] >> 16), bf2f(hb[1] & 0xffffu), bf2f(hb[1] >> 16)};
;                 }
; #pragma unroll
;                 for (int i = 0; i < 4; ++i) { const float v = acc[mt][nt][i] + DN_ALPHA * xr[i]; acc[mt][nt][i] = v; s += v; ss += v * v; }
;             }
;             s2[mh] = s; ss2[mh] = ss;
;         }
; #pragma unroll
;         for (int mh = 0; mh < 2; ++mh) { s2[mh] += __shfl_xor(s2[mh], 16); ss2[mh] += __shfl_xor(ss2[mh], 16); }
; #pragma unroll
;         for (int mh = 0; mh < 2; ++mh) { s2[mh] += __shfl_xor(s2[mh], 32); ss2[mh] += __shfl_xor(ss2[mh], 32); }
;         if (quad == 0) {
; #pragma unroll
;             for (int mh = 0; mh < 2; ++mh) *(f32x2*)&red[((mh * 16 + l15) * 8 + wid) * 2] = (f32x2){s2[mh], ss2[mh]};
;         }
;         __syncthreads();
;         if (half == 0) issue_x(1);
; #pragma unroll
;         for (int mh = 0; mh < 2; ++mh) {
;             const int mt = half * 2 + mh, rl = mh * 16 + l15, row = mt * 16 + l15;
;             float s = 0.f, ss = 0.f;
; #pragma unroll
;             for (int w = 0; w < 4; ++w) { const f32x4 v = *(const f32x4*)&red[rl * 16 + 4 * w]; s += v[0] + v[2]; ss += v[1] + v[3]; }
;             const float mu = s * (1.f / 1024.f);
;             const float var = ss * (1.f / 1024.f) - mu * mu;
;             const float rs = rsqrtf(var + LN_EPS);
;             float* orow = xo + (r0 + row) * 1024 + wid * 128 + quad * 4;
;             bf16_t* brow = xbo + xb_off((int)r0 + row, wid * 128) + quad * 4;
;             const float* gp = GB + wid * 128 + quad * 4;
; #pragma unroll
;             for (int nt = 0; nt < 8; ++nt) {
	ds_read_b128 v[144:147], v204
	ds_read_b128 v[148:151], v205
	ds_read_b128 v[152:155], v206
	ds_read_b128 v[156:159], v207
	ds_read_b128 v[160:163], v204 offset:256
	ds_read_b128 v[164:167], v205 offset:256
	ds_read_b128 v[168:171], v206 offset:256
	ds_read_b128 v[172:175], v207 offset:256
	s_waitcnt lgkmcnt(7)
	v_fmac_f32_e32 v62, s58, v144
	v_fmac_f32_e32 v63, s58, v145
	v_fmac_f32_e32 v64, s58, v146
	v_fmac_f32_e32 v65, s58, v147
	v_mov_b32_e32 v196, v62
	v_mul_f32_e32 v197, v62, v62
	v_mov_b32_e32 v130, v63
	v_mul_f32_e32 v142, v63, v63
	v_add_f32_e32 v196, v196, v64
	v_fmac_f32_e32 v197, v64, v64
	v_add_f32_e32 v130, v130, v65
	v_fmac_f32_e32 v142, v65, v65
	s_waitcnt lgkmcnt(6)
	v_fmac_f32_e32 v58, s58, v148
	v_fmac_f32_e32 v59, s58, v149
	v_fmac_f32_e32 v60, s58, v150
	v_fmac_f32_e32 v61, s58, v151
	v_add_f32_e32 v196, v196, v58
	v_fmac_f32_e32 v197, v58, v58
	v_add_f32_e32 v130, v130, v59
	v_fmac_f32_e32 v142, v59, v59
	v_add_f32_e32 v196, v196, v60
	v_fmac_f32_e32 v197, v60, v60
	v_add_f32_e32 v130, v130, v61
	v_fmac_f32_e32 v142, v61, v61
	s_waitcnt lgkmcnt(5)
	v_fmac_f32_e32 v54, s58, v152
	v_fmac_f32_e32 v55, s58, v153
	v_fmac_f32_e32 v56, s58, v154
	v_fmac_f32_e32 v57, s58, v155
	v_add_f32_e32 v196, v196, v54
	v_fmac_f32_e32 v197, v54, v54
	v_add_f32_e32 v130, v130, v55
	v_fmac_f32_e32 v142, v55, v55
	v_add_f32_e32 v196, v196, v56
	v_fmac_f32_e32 v197, v56, v56
	v_add_f32_e32 v130, v130, v57
	v_fmac_f32_e32 v142, v57, v57
	s_waitcnt lgkmcnt(4)
	v_fmac_f32_e32 v50, s58, v156
	v_fmac_f32_e32 v51, s58, v157
	v_fmac_f32_e32 v52, s58, v158
	v_fmac_f32_e32 v53, s58, v159
	v_add_f32_e32 v196, v196, v50
	v_fmac_f32_e32 v197, v50, v50
	v_add_f32_e32 v130, v130, v51
	v_fmac_f32_e32 v142, v51, v51
	v_add_f32_e32 v196, v196, v52
	v_fmac_f32_e32 v197, v52, v52
	v_add_f32_e32 v130, v130, v53
	v_fmac_f32_e32 v142, v53, v53
	s_waitcnt lgkmcnt(3)
	v_fmac_f32_e32 v46, s58, v160
	v_fmac_f32_e32 v47, s58, v161
	v_fmac_f32_e32 v48, s58, v162
	v_fmac_f32_e32 v49, s58, v163
	v_add_f32_e32 v196, v196, v46
	v_fmac_f32_e32 v197, v46, v46
	v_add_f32_e32 v130, v130, v47
	v_fmac_f32_e32 v142, v47, v47
	v_add_f32_e32 v196, v196, v48
	v_fmac_f32_e32 v197, v48, v48
	v_add_f32_e32 v130, v130, v49
	v_fmac_f32_e32 v142, v49, v49
	s_waitcnt lgkmcnt(2)
	v_fmac_f32_e32 v42, s58, v164
	v_fmac_f32_e32 v43, s58, v165
	v_fmac_f32_e32 v44, s58, v166
	v_fmac_f32_e32 v45, s58, v167
	v_add_f32_e32 v196, v196, v42
	v_fmac_f32_e32 v197, v42, v42
	v_add_f32_e32 v130, v130, v43
	v_fmac_f32_e32 v142, v43, v43
	v_add_f32_e32 v196, v196, v44
	v_fmac_f32_e32 v197, v44, v44
	v_add_f32_e32 v130, v130, v45
	v_fmac_f32_e32 v142, v45, v45
	s_waitcnt lgkmcnt(1)
	v_fmac_f32_e32 v38, s58, v168
	v_fmac_f32_e32 v39, s58, v169
	v_fmac_f32_e32 v40, s58, v170
	v_fmac_f32_e32 v41, s58, v171
	v_add_f32_e32 v196, v196, v38
	v_fmac_f32_e32 v197, v38, v38
	v_add_f32_e32 v130, v130, v39
	v_fmac_f32_e32 v142, v39, v39
	v_add_f32_e32 v196, v196, v40
	v_fmac_f32_e32 v197, v40, v40
	v_add_f32_e32 v130, v130, v41
	v_fmac_f32_e32 v142, v41, v41
	s_waitcnt lgkmcnt(0)
	v_fmac_f32_e32 v2, s58, v172
	v_fmac_f32_e32 v3, s58, v173
	v_fmac_f32_e32 v4, s58, v174
	v_fmac_f32_e32 v5, s58, v175
	v_add_f32_e32 v196, v196, v2
	v_fmac_f32_e32 v197, v2, v2
	v_add_f32_e32 v130, v130, v3
	v_fmac_f32_e32 v142, v3, v3
	v_add_f32_e32 v196, v196, v4
	v_fmac_f32_e32 v197, v4, v4
	v_add_f32_e32 v130, v130, v5
	v_fmac_f32_e32 v142, v5, v5
	v_add_f32_e32 v196, v196, v130
	v_add_f32_e32 v197, v197, v142
	v_mov_b32_e32 v198, v196
	v_mov_b32_e32 v199, v197
	s_nop 1
	v_permlane16_swap_b32 v198, v196
	v_permlane16_swap_b32 v199, v197
	v_add_f32_e32 v196, v196, v198
	v_add_f32_e32 v197, v197, v199
	v_mov_b32_e32 v198, v196
	v_mov_b32_e32 v199, v197
	s_nop 1
	v_permlane32_swap_b32 v198, v196
	v_permlane32_swap_b32 v199, v197
	v_add_f32_e32 v196, v196, v198
	v_add_f32_e32 v197, v197, v199
	s_mov_b64 exec, 0xffff
	ds_write_b64 v134, v[196:197]
	s_mov_b64 exec, -1
	s_waitcnt lgkmcnt(0)
	s_barrier
	ds_read_b128 v[160:163], v135 offset:0
	ds_read_b128 v[164:167], v135 offset:16
	ds_read_b128 v[168:171], v135 offset:32
	ds_read_b128 v[172:175], v135 offset:48
	s_waitcnt lgkmcnt(0)
	v_add_f32_e32 v160, v160, v162
	v_add_f32_e32 v161, v161, v163
	v_add_f32_e32 v164, v164, v166
	v_add_f32_e32 v165, v165, v167
	v_add_f32_e32 v168, v168, v170
	v_add_f32_e32 v169, v169, v171
	v_add_f32_e32 v172, v172, v174
	v_add_f32_e32 v173, v173, v175
	v_add_f32_e32 v160, v160, v164
	v_add_f32_e32 v161, v161, v165
	v_add_f32_e32 v168, v168, v172
	v_add_f32_e32 v169, v169, v173
	v_add_f32_e32 v160, v160, v168
	v_add_f32_e32 v161, v161, v169
	v_mul_f32_e32 v192, 0x3a800000, v160
	v_mul_f32_e32 v193, 0x3a800000, v161
	v_fma_f32 v193, -v192, v192, v193
	v_add_f32_e32 v193, 0x3727c5ac, v193
	v_rsq_f32_e32 v193, v193
	s_nop 0
	s_add_u32 s94, s78, 0xc00
	s_addc_u32 s95, s79, 0
	ds_read_b128 v[176:179], v136
	ds_read_b128 v[180:183], v136 offset:4096
	ds_read_b128 v[184:187], v136 offset:64
	ds_read_b128 v[188:191], v136 offset:4160
	s_waitcnt lgkmcnt(2)
	v_sub_f32_e32 v62, v62, v192
	v_mul_f32_e32 v62, v62, v193
	v_fma_f32 v62, v176, v62, v180
	v_sub_f32_e32 v63, v63, v192
	v_mul_f32_e32 v63, v63, v193
	v_fma_f32 v63, v177, v63, v181
	v_sub_f32_e32 v64, v64, v192
	v_mul_f32_e32 v64, v64, v193
	v_fma_f32 v64, v178, v64, v182
	v_sub_f32_e32 v65, v65, v192
	v_mul_f32_e32 v65, v65, v193
	v_fma_f32 v65, v179, v65, v183
	v_cvt_pk_bf16_f32 v144, v62, v63
	v_cvt_pk_bf16_f32 v145, v64, v65
	ds_read_b128 v[176:179], v136 offset:128
	ds_read_b128 v[180:183], v136 offset:4224
	s_waitcnt lgkmcnt(2)
; DI unsigned pk2(float lo, float hi) { const f32x2 v = {lo, hi}; const bf16x2_t b = __builtin_convertvector(v, bf16x2_t); return __builtin_bit_cast(unsigned, b); }
; DI size_t xb_off(int tok, int col) { return ((size_t)(((tok >> 7) * 32 + (col >> 5)) * 128 + (tok & 127))) * 32 + (col & 31); }
; DI void unit_O(const Params& p, char* lds, int l, int tile, int glu_tiles, int tile_b) {
;     ...
;             float* orow = xo + (r0 + row) * 1024 + wid * 128 + quad * 4;
;             bf16_t* brow = xbo + xb_off((int)r0 + row, wid * 128) + quad * 4;
;             const float* gp = GB + wid * 128 + quad * 4;
; #pragma unroll
;             for (int nt = 0; nt < 8; ++nt) {
;                 const f32x4 g = *(const f32x4*)(gp + nt * 16), bb = *(const f32x4*)(gp + 1024 + nt * 16);
;                 f32x4 o;
; #pragma unroll
;                 for (int i = 0; i < 4; ++i) o[i] = (acc[mt][nt][i] - mu) * rs * g[i] + bb[i];
;                 if (l == 0) *(u32x2*)(brow + (nt >> 1) * 4096 + (nt & 1) * 16) = (u32x2){pk2(o[0], o[1]), pk2(o[2], o[3])};
;                 else *(f32x4*)(orow + nt * 16) = o;
;             }
	v_sub_f32_e32 v58, v58, v192
	v_mul_f32_e32 v58, v58, v193
	v_fma_f32 v58, v184, v58, v188
	v_sub_f32_e32 v59, v59, v192
	v_mul_f32_e32 v59, v59, v193
	v_fma_f32 v59, v185, v59, v189
	v_sub_f32_e32 v60, v60, v192
	v_mul_f32_e32 v60, v60, v193
	v_fma_f32 v60, v186, v60, v190
	v_sub_f32_e32 v61, v61, v192
	v_mul_f32_e32 v61, v61, v193
	v_fma_f32 v61, v187, v61, v191
	v_cvt_pk_bf16_f32 v146, v58, v59
	v_cvt_pk_bf16_f32 v147, v60, v61
	s_nop 1
	v_permlane16_swap_b32 v144, v146
	v_permlane16_swap_b32 v145, v147
	global_store_dwordx4 v137, v[144:147], s[94:95]
	s_add_u32 s94, s94, 0x2000
	s_addc_u32 s95, s95, 0
	ds_read_b128 v[184:187], v136 offset:192
	ds_read_b128 v[188:191], v136 offset:4288
	s_waitcnt lgkmcnt(2)
	v_sub_f32_e32 v54, v54, v192
	v_mul_f32_e32 v54, v54, v193
	v_fma_f32 v54, v176, v54, v180
	v_sub_f32_e32 v55, v55, v192
	v_mul_f32_e32 v55, v55, v193
	v_fma_f32 v55, v177, v55, v181
	v_sub_f32_e32 v56, v56, v192
	v_mul_f32_e32 v56, v56, v193
	v_fma_f32 v56, v178, v56, v182
	v_sub_f32_e32 v57, v57, v192
	v_mul_f32_e32 v57, v57, v193
	v_fma_f32 v57, v179, v57, v183
	v_cvt_pk_bf16_f32 v152, v54, v55
	v_cvt_pk_bf16_f32 v153, v56, v57
	ds_read_b128 v[176:179], v136 offset:256
	ds_read_b128 v[180:183], v136 offset:4352
	s_waitcnt lgkmcnt(2)
	v_sub_f32_e32 v50, v50, v192
	v_mul_f32_e32 v50, v50, v193
	v_fma_f32 v50, v184, v50, v188
	v_sub_f32_e32 v51, v51, v192
	v_mul_f32_e32 v51, v51, v193
	v_fma_f32 v51, v185, v51, v189
	v_sub_f32_e32 v52, v52, v192
	v_mul_f32_e32 v52, v52, v193
	v_fma_f32 v52, v186, v52, v190
	v_sub_f32_e32 v53, v53, v192
	v_mul_f32_e32 v53, v53, v193
	v_fma_f32 v53, v187, v53, v191
	v_cvt_pk_bf16_f32 v154, v50, v51
	v_cvt_pk_bf16_f32 v155, v52, v53
	s_nop 1
	v_permlane16_swap_b32 v152, v154
	v_permlane16_swap_b32 v153, v155
	global_store_dwordx4 v137, v[152:155], s[94:95]
	s_add_u32 s94, s94, 0x2000
	s_addc_u32 s95, s95, 0
	ds_read_b128 v[184:187], v136 offset:320
	ds_read_b128 v[188:191], v136 offset:4416
	s_waitcnt lgkmcnt(2)
	v_sub_f32_e32 v46, v46, v192
	v_mul_f32_e32 v46, v46, v193
	v_fma_f32 v46, v176, v46, v180
	v_sub_f32_e32 v47, v47, v192
	v_mul_f32_e32 v47, v47, v193
	v_fma_f32 v47, v177, v47, v181
	v_sub_f32_e32 v48, v48, v192
	v_mul_f32_e32 v48, v48, v193
	v_fma_f32 v48, v178, v48, v182
	v_sub_f32_e32 v49, v49, v192
	v_mul_f32_e32 v49, v49, v193
	v_fma_f32 v49, v179, v49, v183
	v_cvt_pk_bf16_f32 v144, v46, v47
	v_cvt_pk_bf16_f32 v145, v48, v49
	ds_read_b128 v[176:179], v136 offset:384
	ds_read_b128 v[180:183], v136 offset:4480
	s_waitcnt lgkmcnt(2)
	v_sub_f32_e32 v42, v42, v192
	v_mul_f32_e32 v42, v42, v193
	v_fma_f32 v42, v184, v42, v188
	v_sub_f32_e32 v43, v43, v192
	v_mul_f32_e32 v43, v43, v193
	v_fma_f32 v43, v185, v43, v189
	v_sub_f32_e32 v44, v44, v192
	v_mul_f32_e32 v44, v44, v193
	v_fma_f32 v44, v186, v44, v190
	v_sub_f32_e32 v45, v45, v192
	v_mul_f32_e32 v45, v45, v193
	v_fma_f32 v45, v187, v45, v191
	v_cvt_pk_bf16_f32 v146, v42, v43
	v_cvt_pk_bf16_f32 v147, v44, v45
	s_nop 1
	v_permlane16_swap_b32 v144, v146
	v_permlane16_swap_b32 v145, v147
	global_store_dwordx4 v137, v[144:147], s[94:95]
	s_add_u32 s94, s94, 0x2000
	s_addc_u32 s95, s95, 0
	ds_read_b128 v[184:187], v136 offset:448
	ds_read_b128 v[188:191], v136 offset:4544
	s_waitcnt lgkmcnt(2)
	v_sub_f32_e32 v38, v38, v192
	v_mul_f32_e32 v38, v38, v193
	v_fma_f32 v38, v176, v38, v180
	v_sub_f32_e32 v39, v39, v192
	v_mul_f32_e32 v39, v39, v193
	v_fma_f32 v39, v177, v39, v181
	v_sub_f32_e32 v40, v40, v192
	v_mul_f32_e32 v40, v40, v193
	v_fma_f32 v40, v178, v40, v182
	v_sub_f32_e32 v41, v41, v192
	v_mul_f32_e32 v41, v41, v193
	v_fma_f32 v41, v179, v41, v183
	v_cvt_pk_bf16_f32 v152, v38, v39
	v_cvt_pk_bf16_f32 v153, v40, v41
	s_waitcnt lgkmcnt(0)
	v_sub_f32_e32 v2, v2, v192
	v_mul_f32_e32 v2, v2, v193
	v_fma_f32 v2, v184, v2, v188
	v_sub_f32_e32 v3, v3, v192
	v_mul_f32_e32 v3, v3, v193
	v_fma_f32 v3, v185, v3, v189
	v_sub_f32_e32 v4, v4, v192
	v_mul_f32_e32 v4, v4, v193
	v_fma_f32 v4, v186, v4, v190
	v_sub_f32_e32 v5, v5, v192
	v_mul_f32_e32 v5, v5, v193
	v_fma_f32 v5, v187, v5, v191
	v_cvt_pk_bf16_f32 v154, v2, v3
	v_cvt_pk_bf16_f32 v155, v4, v5
	s_nop 1
	v_permlane16_swap_b32 v152, v154
	v_permlane16_swap_b32 v153, v155
	global_store_dwordx4 v137, v[152:155], s[94:95]
	s_branch .Le1_done
; DI void unit_O(const Params& p, char* lds, int l, int tile, int glu_tiles, int tile_b) {
;     ...
; #pragma unroll 1
;             for (int i = 0; i < 8; ++i) {
;                 const int pc = (wid * 8 + i + (xrot >> 1)) & 63, kt = pc >> 1, sub = pc & 1;
;                 __builtin_amdgcn_global_load_lds((const unsigned*)(xbres + ((size_t)kt * 128 + half * 32) * 32 + sub * 512 + lane * 8), (unsigned*)(XR + pc * 1024 + lane * 16), 16, 0, 0);
;             }
;         }
;     };
;     issue_x(0);
;     {
;         const float* gsrc = (tid < 256) ? (p.ln_g + l * 1024 + tid * 4) : (p.ln_b + l * 1024 + (tid - 256) * 4);
;         *(f32x4*)(GB + tid * 4) = *(const f32x4*)gsrc;
;     }
;     float* xo = (l == 0) ? WS_PTR(float, OFF_X1) : p.out;
;     bf16_t* xbo = WS_PTR(bf16_t, OFF_XB1);
; #pragma unroll
;     for (int half = 0; half < 2; ++half) {
;         if (half == 0) wait_vm<0>();
;         else wait_vm<8>();
;         __syncthreads();
;         float s2[2], ss2[2];
; #pragma unroll
;         for (int mh = 0; mh < 2; ++mh) {
;             const int mt = half * 2 + mh, rl = mh * 16 + l15;
;             float s = 0.f, ss = 0.f;
; #pragma unroll
;             for (int nt = 0; nt < 8; ++nt) {
;                 f32x4 xr;
;                 if (l == 0) {
;                     const int chunk = wid * 32 + nt * 4 + quad;
;                     xr = *(const f32x4*)(XR + rl * 4096 + ((chunk ^ l15) << 4));
;                 } else {
;                     const u32x2 hb = *(const u32x2*)(XR + ((wid * 4 + (nt >> 1)) * 32 + rl) * 64 + (nt & 1) * 32 + quad * 8);
;                     xr = (f32x4){bf2f(hb[0] & 0xffffu), bf2f(hb[0] >> 16), bf2f(hb[1] & 0xffffu), bf2f(hb[1] >> 16)};
;                 }
; #pragma unroll
;                 for (int i = 0; i < 4; ++i) { const float v = acc[mt][nt][i] + DN_ALPHA * xr[i]; acc[mt][nt][i] = v; s += v; ss += v * v; }
;             }
;             s2[mh] = s; ss2[mh] = ss;
;         }
; #pragma unroll
;         for (int mh = 0; mh < 2; ++mh) { s2[mh] += __shfl_xor(s2[mh], 16); ss2[mh] += __shfl_xor(ss2[mh], 16); }
; #pragma unroll
;         for (int mh = 0; mh < 2; ++mh) { s2[mh] += __shfl_xor(s2[mh], 32); ss2[mh] += __shfl_xor(ss2[mh], 32); }
;         if (quad == 0) {
; #pragma unroll
;             for (int mh = 0; mh < 2; ++mh) *(f32x2*)&red[((mh * 16 + l15) * 8 + wid) * 2] = (f32x2){s2[mh], ss2[mh]};
;         }
;         __syncthreads();
.Le1_l1:
	s_lshr_b32 s40, s34, 1
	s_lshl_b32 s40, s40, 18
	s_and_b32 s46, s34, 1
	s_lshl_b32 s46, s46, 12
	s_add_u32 s40, s40, s46
	s_lshl_b32 s91, s90, 12
	s_lshl_b32 s46, s90, 15
	s_add_u32 s96, s56, s40
	s_addc_u32 s97, s57, 0
	s_add_u32 s96, s96, s46
	s_addc_u32 s97, s97, 0
	v_lshlrev_b32_e32 v131, 4, v141
	v_lshlrev_b32_e32 v133, 12, v140
	v_lshl_add_u32 v133, v138, 6, v133
	v_lshl_add_u32 v133, v139, 3, v133
	v_lshlrev_b32_e32 v137, 12, v138
	v_lshl_add_u32 v137, v140, 9, v137
	v_lshl_add_u32 v137, v139, 4, v137
	s_lshl_b32 s40, s34, 18
	s_add_u32 s78, s16, s40
	s_addc_u32 s79, s17, 0
	s_add_u32 s92, s96, 0x0
	s_addc_u32 s93, s97, 0
	s_add_u32 s40, s91, 0x0
	s_mov_b32 m0, s40
	s_nop 0
	global_load_lds_dwordx4 v131, s[92:93]
	s_add_u32 s92, s92, 0x2000
	s_addc_u32 s93, s93, 0
	s_add_u32 m0, m0, 0x400
	s_nop 0
	global_load_lds_dwordx4 v131, s[92:93]
	s_add_u32 s92, s92, 0x2000
	s_addc_u32 s93, s93, 0
	s_add_u32 m0, m0, 0x400
	s_nop 0
	global_load_lds_dwordx4 v131, s[92:93]
	s_add_u32 s92, s92, 0x2000
	s_addc_u32 s93, s93, 0
	s_add_u32 m0, m0, 0x400
	s_nop 0
	global_load_lds_dwordx4 v131, s[92:93]
	s_add_u32 s92, s96, 0x400
	s_addc_u32 s93, s97, 0
	s_add_u32 s40, s91, 0x8000
	s_mov_b32 m0, s40
	s_nop 0
	global_load_lds_dwordx4 v131, s[92:93]
	s_add_u32 s92, s92, 0x2000
	s_addc_u32 s93, s93, 0
	s_add_u32 m0, m0, 0x400
	s_nop 0
	global_load_lds_dwordx4 v131, s[92:93]
	s_add_u32 s92, s92, 0x2000
	s_addc_u32 s93, s93, 0
	s_add_u32 m0, m0, 0x400
	s_nop 0
	global_load_lds_dwordx4 v131, s[92:93]
	s_add_u32 s92, s92, 0x2000
	s_addc_u32 s93, s93, 0
	s_add_u32 m0, m0, 0x400
	s_nop 0
	global_load_lds_dwordx4 v131, s[92:93]
	s_waitcnt vmcnt(8)
	ds_write_b128 v143, v[176:179]
	s_waitcnt vmcnt(4) lgkmcnt(0)
	s_barrier
	ds_read_b64 v[180:181], v133 offset:0
	ds_read_b64 v[182:183], v133 offset:32
	ds_read_b64 v[184:185], v133 offset:1024
	ds_read_b64 v[186:187], v133 offset:1056
	ds_read_b64 v[188:189], v133 offset:2048
	ds_read_b64 v[190:191], v133 offset:2080
	ds_read_b64 v[192:193], v133 offset:3072
	ds_read_b64 v[194:195], v133 offset:3104
	s_waitcnt lgkmcnt(7)
	v_lshlrev_b32_e32 v144, 16, v180
	v_and_b32_e32 v145, 0xffff0000, v180
	v_lshlrev_b32_e32 v146, 16, v181
	v_and_b32_e32 v147, 0xffff0000, v181
	v_fmac_f32_e32 v98, s58, v144
	v_fmac_f32_e32 v99, s58, v145
	v_fmac_f32_e32 v100, s58, v146
	v_fmac_f32_e32 v101, s58, v147
	v_mov_b32_e32 v196, v98
	v_mul_f32_e32 v197, v98, v98
	v_mov_b32_e32 v130, v99
	v_mul_f32_e32 v142, v99, v99
	v_add_f32_e32 v196, v196, v100
	v_fmac_f32_e32 v197, v100, v100
	v_add_f32_e32 v130, v130, v101
	v_fmac_f32_e32 v142, v101, v101
	s_waitcnt lgkmcnt(6)
	v_lshlrev_b32_e32 v148, 16, v182
	v_and_b32_e32 v149, 0xffff0000, v182
	v_lshlrev_b32_e32 v150, 16, v183
	v_and_b32_e32 v151, 0xffff0000, v183
	v_fmac_f32_e32 v94, s58, v148
	v_fmac_f32_e32 v95, s58, v149
	v_fmac_f32_e32 v96, s58, v150
	v_fmac_f32_e32 v97, s58, v151
	v_add_f32_e32 v196, v196, v94
	v_fmac_f32_e32 v197, v94, v94
	v_add_f32_e32 v130, v130, v95
	v_fmac_f32_e32 v142, v95, v95
	v_add_f32_e32 v196, v196, v96
	v_fmac_f32_e32 v197, v96, v96
	v_add_f32_e32 v130, v130, v97
	v_fmac_f32_e32 v142, v97, v97
	s_waitcnt lgkmcnt(5)
	v_lshlrev_b32_e32 v152, 16, v184
	v_and_b32_e32 v153, 0xffff0000, v184
	v_lshlrev_b32_e32 v154, 16, v185
	v_and_b32_e32 v155, 0xffff0000, v185
	v_fmac_f32_e32 v90, s58, v152
	v_fmac_f32_e32 v91, s58, v153
	v_fmac_f32_e32 v92, s58, v154
	v_fmac_f32_e32 v93, s58, v155
	v_add_f32_e32 v196, v196, v90
	v_fmac_f32_e32 v197, v90, v90
	v_add_f32_e32 v130, v130, v91
	v_fmac_f32_e32 v142, v91, v91
	v_add_f32_e32 v196, v196, v92
	v_fmac_f32_e32 v197, v92, v92
	v_add_f32_e32 v130, v130, v93
	v_fmac_f32_e32 v142, v93, v93
	s_waitcnt lgkmcnt(4)
	v_lshlrev_b32_e32 v156, 16, v186
	v_and_b32_e32 v157, 0xffff0000, v186
	v_lshlrev_b32_e32 v158, 16, v187
	v_and_b32_e32 v159, 0xffff0000, v187
	v_fmac_f32_e32 v86, s58, v156
	v_fmac_f32_e32 v87, s58, v157
	v_fmac_f32_e32 v88, s58, v158
	v_fmac_f32_e32 v89, s58, v159
	v_add_f32_e32 v196, v196, v86
	v_fmac_f32_e32 v197, v86, v86
	v_add_f32_e32 v130, v130, v87
	v_fmac_f32_e32 v142, v87, v87
	v_add_f32_e32 v196, v196, v88
	v_fmac_f32_e32 v197, v88, v88
	v_add_f32_e32 v130, v130, v89
	v_fmac_f32_e32 v142, v89, v89
	s_waitcnt lgkmcnt(3)
	v_lshlrev_b32_e32 v160, 16, v188
	v_and_b32_e32 v161, 0xffff0000, v188
	v_lshlrev_b32_e32 v162, 16, v189
	v_and_b32_e32 v163, 0xffff0000, v189
	v_fmac_f32_e32 v82, s58, v160
	v_fmac_f32_e32 v83, s58, v161
	v_fmac_f32_e32 v84, s58, v162
	v_fmac_f32_e32 v85, s58, v163
	v_add_f32_e32 v196, v196, v82
	v_fmac_f32_e32 v197, v82, v82
	v_add_f32_e32 v130, v130, v83
	v_fmac_f32_e32 v142, v83, v83
	v_add_f32_e32 v196, v196, v84
	v_fmac_f32_e32 v197, v84, v84
	v_add_f32_e32 v130, v130, v85
	v_fmac_f32_e32 v142, v85, v85
	s_waitcnt lgkmcnt(2)
	v_lshlrev_b32_e32 v164, 16, v190
	v_and_b32_e32 v165, 0xffff0000, v190
	v_lshlrev_b32_e32 v166, 16, v191
	v_and_b32_e32 v167, 0xffff0000, v191
	v_fmac_f32_e32 v78, s58, v164
	v_fmac_f32_e32 v79, s58, v165
	v_fmac_f32_e32 v80, s58, v166
	v_fmac_f32_e32 v81, s58, v167
	v_add_f32_e32 v196, v196, v78
	v_fmac_f32_e32 v197, v78, v78
	v_add_f32_e32 v130, v130, v79
	v_fmac_f32_e32 v142, v79, v79
	v_add_f32_e32 v196, v196, v80
	v_fmac_f32_e32 v197, v80, v80
	v_add_f32_e32 v130, v130, v81
	v_fmac_f32_e32 v142, v81, v81
	s_waitcnt lgkmcnt(1)
	v_lshlrev_b32_e32 v168, 16, v192
	v_and_b32_e32 v169, 0xffff0000, v192
	v_lshlrev_b32_e32 v170, 16, v193
	v_and_b32_e32 v171, 0xffff0000, v193
	v_fmac_f32_e32 v74, s58, v168
	v_fmac_f32_e32 v75, s58, v169
	v_fmac_f32_e32 v76, s58, v170
	v_fmac_f32_e32 v77, s58, v171
	v_add_f32_e32 v196, v196, v74
	v_fmac_f32_e32 v197, v74, v74
	v_add_f32_e32 v130, v130, v75
	v_fmac_f32_e32 v142, v75, v75
	v_add_f32_e32 v196, v196, v76
	v_fmac_f32_e32 v197, v76, v76
	v_add_f32_e32 v130, v130, v77
	v_fmac_f32_e32 v142, v77, v77
	s_waitcnt lgkmcnt(0)
	v_lshlrev_b32_e32 v172, 16, v194
	v_and_b32_e32 v173, 0xffff0000, v194
	v_lshlrev_b32_e32 v174, 16, v195
	v_and_b32_e32 v175, 0xffff0000, v195
	v_fmac_f32_e32 v70, s58, v172
	v_fmac_f32_e32 v71, s58, v173
	v_fmac_f32_e32 v72, s58, v174
	v_fmac_f32_e32 v73, s58, v175
	v_add_f32_e32 v196, v196, v70
	v_fmac_f32_e32 v197, v70, v70
	v_add_f32_e32 v130, v130, v71
	v_fmac_f32_e32 v142, v71, v71
	v_add_f32_e32 v196, v196, v72
	v_fmac_f32_e32 v197, v72, v72
	v_add_f32_e32 v130, v130, v73
	v_fmac_f32_e32 v142, v73, v73
	v_add_f32_e32 v196, v196, v130
	v_add_f32_e32 v197, v197, v142
	v_mov_b32_e32 v198, v196
	v_mov_b32_e32 v199, v197
	s_nop 1
	v_permlane16_swap_b32 v198, v196
	v_permlane16_swap_b32 v199, v197
	v_add_f32_e32 v196, v196, v198
	v_add_f32_e32 v197, v197, v199
	v_mov_b32_e32 v198, v196
	v_mov_b32_e32 v199, v197
	s_nop 1
	v_permlane32_swap_b32 v198, v196
	v_permlane32_swap_b32 v199, v197
	v_add_f32_e32 v196, v196, v198
	v_add_f32_e32 v197, v197, v199
	s_mov_b64 exec, 0xffff
	ds_write_b64 v134, v[196:197]
	s_mov_b64 exec, -1
	s_waitcnt lgkmcnt(0)
	s_barrier
; DI unsigned pk2(float lo, float hi) { const f32x2 v = {lo, hi}; const bf16x2_t b = __builtin_convertvector(v, bf16x2_t); return __builtin_bit_cast(unsigned, b); }
; DI size_t xb_off(int tok, int col) { return ((size_t)(((tok >> 7) * 32 + (col >> 5)) * 128 + (tok & 127))) * 32 + (col & 31); }
; DI void unit_O(const Params& p, char* lds, int l, int tile, int glu_tiles, int tile_b) {
;     ...
;         if (half == 0) issue_x(1);
; #pragma unroll
;         for (int mh = 0; mh < 2; ++mh) {
;             const int mt = half * 2 + mh, rl = mh * 16 + l15, row = mt * 16 + l15;
;             float s = 0.f, ss = 0.f;
; #pragma unroll
;             for (int w = 0; w < 4; ++w) { const f32x4 v = *(const f32x4*)&red[rl * 16 + 4 * w]; s += v[0] + v[2]; ss += v[1] + v[3]; }
;             const float mu = s * (1.f / 1024.f);
;             const float var = ss * (1.f / 1024.f) - mu * mu;
;             const float rs = rsqrtf(var + LN_EPS);
;             float* orow = xo + (r0 + row) * 1024 + wid * 128 + quad * 4;
;             bf16_t* brow = xbo + xb_off((int)r0 + row, wid * 128) + quad * 4;
;             const float* gp = GB + wid * 128 + quad * 4;
; #pragma unroll
;             for (int nt = 0; nt < 8; ++nt) {
;                 const f32x4 g = *(const f32x4*)(gp + nt * 16), bb = *(const f32x4*)(gp + 1024 + nt * 16);
;                 f32x4 o;
; #pragma unroll
;                 for (int i = 0; i < 4; ++i) o[i] = (acc[mt][nt][i] - mu) * rs * g[i] + bb[i];
;                 if (l == 0) *(u32x2*)(brow + (nt >> 1) * 4096 + (nt & 1) * 16) = (u32x2){pk2(o[0], o[1]), pk2(o[2], o[3])};
;                 else *(f32x4*)(orow + nt * 16) = o;
;             }
;         }
	s_add_u32 s92, s96, 0x800
	s_addc_u32 s93, s97, 0
	s_add_u32 s40, s91, 0x0
	s_mov_b32 m0, s40
	s_nop 0
	global_load_lds_dwordx4 v131, s[92:93]
	s_add_u32 s92, s92, 0x2000
	s_addc_u32 s93, s93, 0
	s_add_u32 m0, m0, 0x400
	s_nop 0
	global_load_lds_dwordx4 v131, s[92:93]
	s_add_u32 s92, s92, 0x2000
	s_addc_u32 s93, s93, 0
	s_add_u32 m0, m0, 0x400
	s_nop 0
	global_load_lds_dwordx4 v131, s[92:93]
	s_add_u32 s92, s92, 0x2000
	s_addc_u32 s93, s93, 0
	s_add_u32 m0, m0, 0x400
	s_nop 0
	global_load_lds_dwordx4 v131, s[92:93]
	ds_read_b128 v[160:163], v135 offset:0
	ds_read_b128 v[164:167], v135 offset:16
	ds_read_b128 v[168:171], v135 offset:32
	ds_read_b128 v[172:175], v135 offset:48
	s_waitcnt lgkmcnt(0)
	v_add_f32_e32 v160, v160, v162
	v_add_f32_e32 v161, v161, v163
	v_add_f32_e32 v164, v164, v166
	v_add_f32_e32 v165, v165, v167
	v_add_f32_e32 v168, v168, v170
	v_add_f32_e32 v169, v169, v171
	v_add_f32_e32 v172, v172, v174
	v_add_f32_e32 v173, v173, v175
	v_add_f32_e32 v160, v160, v164
	v_add_f32_e32 v161, v161, v165
	v_add_f32_e32 v168, v168, v172
	v_add_f32_e32 v169, v169, v173
	v_add_f32_e32 v160, v160, v168
	v_add_f32_e32 v161, v161, v169
	v_mul_f32_e32 v192, 0x3a800000, v160
	v_mul_f32_e32 v193, 0x3a800000, v161
	v_fma_f32 v193, -v192, v192, v193
	v_add_f32_e32 v193, 0x3727c5ac, v193
	v_rsq_f32_e32 v193, v193
	s_nop 0
	s_add_u32 s94, s78, 0x0
	s_addc_u32 s95, s79, 0
	ds_read_b128 v[176:179], v136
	ds_read_b128 v[180:183], v136 offset:4096
	ds_read_b128 v[184:187], v136 offset:64
	ds_read_b128 v[188:191], v136 offset:4160
	s_waitcnt lgkmcnt(2)
	v_sub_f32_e32 v98, v98, v192
	v_mul_f32_e32 v98, v98, v193
	v_fma_f32 v98, v176, v98, v180
	v_sub_f32_e32 v99, v99, v192
	v_mul_f32_e32 v99, v99, v193
	v_fma_f32 v99, v177, v99, v181
	v_sub_f32_e32 v100, v100, v192
	v_mul_f32_e32 v100, v100, v193
	v_fma_f32 v100, v178, v100, v182
	v_sub_f32_e32 v101, v101, v192
	v_mul_f32_e32 v101, v101, v193
	v_fma_f32 v101, v179, v101, v183
	global_store_dwordx4 v137, v[98:101], s[94:95]
	ds_read_b128 v[176:179], v136 offset:128
	ds_read_b128 v[180:183], v136 offset:4224
	s_waitcnt lgkmcnt(2)
	v_sub_f32_e32 v94, v94, v192
	v_mul_f32_e32 v94, v94, v193
	v_fma_f32 v94, v184, v94, v188
	v_sub_f32_e32 v95, v95, v192
	v_mul_f32_e32 v95, v95, v193
	v_fma_f32 v95, v185, v95, v189
	v_sub_f32_e32 v96, v96, v192
	v_mul_f32_e32 v96, v96, v193
	v_fma_f32 v96, v186, v96, v190
	v_sub_f32_e32 v97, v97, v192
	v_mul_f32_e32 v97, v97, v193
	v_fma_f32 v97, v187, v97, v191
	global_store_dwordx4 v137, v[94:97], s[94:95] offset:64
	ds_read_b128 v[184:187], v136 offset:192
	ds_read_b128 v[188:191], v136 offset:4288
	s_waitcnt lgkmcnt(2)
	v_sub_f32_e32 v90, v90, v192
	v_mul_f32_e32 v90, v90, v193
	v_fma_f32 v90, v176, v90, v180
	v_sub_f32_e32 v91, v91, v192
	v_mul_f32_e32 v91, v91, v193
	v_fma_f32 v91, v177, v91, v181
	v_sub_f32_e32 v92, v92, v192
	v_mul_f32_e32 v92, v92, v193
	v_fma_f32 v92, v178, v92, v182
	v_sub_f32_e32 v93, v93, v192
	v_mul_f32_e32 v93, v93, v193
	v_fma_f32 v93, v179, v93, v183
	global_store_dwordx4 v137, v[90:93], s[94:95] offset:128
	ds_read_b128 v[176:179], v136 offset:256
	ds_read_b128 v[180:183], v136 offset:4352
	s_waitcnt lgkmcnt(2)
	v_sub_f32_e32 v86, v86, v192
	v_mul_f32_e32 v86, v86, v193
	v_fma_f32 v86, v184, v86, v188
	v_sub_f32_e32 v87, v87, v192
	v_mul_f32_e32 v87, v87, v193
	v_fma_f32 v87, v185, v87, v189
	v_sub_f32_e32 v88, v88, v192
	v_mul_f32_e32 v88, v88, v193
	v_fma_f32 v88, v186, v88, v190
	v_sub_f32_e32 v89, v89, v192
	v_mul_f32_e32 v89, v89, v193
	v_fma_f32 v89, v187, v89, v191
	global_store_dwordx4 v137, v[86:89], s[94:95] offset:192
	ds_read_b128 v[184:187], v136 offset:320
	ds_read_b128 v[188:191], v136 offset:4416
	s_waitcnt lgkmcnt(2)
	v_sub_f32_e32 v82, v82, v192
	v_mul_f32_e32 v82, v82, v193
	v_fma_f32 v82, v176, v82, v180
	v_sub_f32_e32 v83, v83, v192
	v_mul_f32_e32 v83, v83, v193
	v_fma_f32 v83, v177, v83, v181
	v_sub_f32_e32 v84, v84, v192
	v_mul_f32_e32 v84, v84, v193
	v_fma_f32 v84, v178, v84, v182
	v_sub_f32_e32 v85, v85, v192
	v_mul_f32_e32 v85, v85, v193
	v_fma_f32 v85, v179, v85, v183
	global_store_dwordx4 v137, v[82:85], s[94:95] offset:256
	ds_read_b128 v[176:179], v136 offset:384
	ds_read_b128 v[180:183], v136 offset:4480
	s_waitcnt lgkmcnt(2)
	v_sub_f32_e32 v78, v78, v192
	v_mul_f32_e32 v78, v78, v193
	v_fma_f32 v78, v184, v78, v188
	v_sub_f32_e32 v79, v79, v192
	v_mul_f32_e32 v79, v79, v193
	v_fma_f32 v79, v185, v79, v189
	v_sub_f32_e32 v80, v80, v192
	v_mul_f32_e32 v80, v80, v193
	v_fma_f32 v80, v186, v80, v190
	v_sub_f32_e32 v81, v81, v192
	v_mul_f32_e32 v81, v81, v193
	v_fma_f32 v81, v187, v81, v191
	global_store_dwordx4 v137, v[78:81], s[94:95] offset:320
	ds_read_b128 v[184:187], v136 offset:448
	ds_read_b128 v[188:191], v136 offset:4544
	s_waitcnt lgkmcnt(2)
	v_sub_f32_e32 v74, v74, v192
	v_mul_f32_e32 v74, v74, v193
	v_fma_f32 v74, v176, v74, v180
	v_sub_f32_e32 v75, v75, v192
	v_mul_f32_e32 v75, v75, v193
	v_fma_f32 v75, v177, v75, v181
	v_sub_f32_e32 v76, v76, v192
	v_mul_f32_e32 v76, v76, v193
	v_fma_f32 v76, v178, v76, v182
	v_sub_f32_e32 v77, v77, v192
	v_mul_f32_e32 v77, v77, v193
	v_fma_f32 v77, v179, v77, v183
	global_store_dwordx4 v137, v[74:77], s[94:95] offset:384
	s_waitcnt lgkmcnt(0)
	v_sub_f32_e32 v70, v70, v192
	v_mul_f32_e32 v70, v70, v193
	v_fma_f32 v70, v184, v70, v188
	v_sub_f32_e32 v71, v71, v192
	v_mul_f32_e32 v71, v71, v193
	v_fma_f32 v71, v185, v71, v189
	v_sub_f32_e32 v72, v72, v192
	v_mul_f32_e32 v72, v72, v193
	v_fma_f32 v72, v186, v72, v190
	v_sub_f32_e32 v73, v73, v192
	v_mul_f32_e32 v73, v73, v193
	v_fma_f32 v73, v187, v73, v191
	global_store_dwordx4 v137, v[70:73], s[94:95] offset:448
	s_waitcnt vmcnt(12) lgkmcnt(0)
	s_barrier
; DI float bf2f(unsigned b) { return __uint_as_float(b << 16); }
; DI void unit_O(const Params& p, char* lds, int l, int tile, int glu_tiles, int tile_b) {
;     ...
;         float s2[2], ss2[2];
; #pragma unroll
;         for (int mh = 0; mh < 2; ++mh) {
;             const int mt = half * 2 + mh, rl = mh * 16 + l15;
;             float s = 0.f, ss = 0.f;
; #pragma unroll
;             for (int nt = 0; nt < 8; ++nt) {
;                 f32x4 xr;
;                 if (l == 0) {
;                     const int chunk = wid * 32 + nt * 4 + quad;
;                     xr = *(const f32x4*)(XR + rl * 4096 + ((chunk ^ l15) << 4));
;                 } else {
;                     const u32x2 hb = *(const u32x2*)(XR + ((wid * 4 + (nt >> 1)) * 32 + rl) * 64 + (nt & 1) * 32 + quad * 8);
;                     xr = (f32x4){bf2f(hb[0] & 0xffffu), bf2f(hb[0] >> 16), bf2f(hb[1] & 0xffffu), bf2f(hb[1] >> 16)};
;                 }
; #pragma unroll
;                 for (int i = 0; i < 4; ++i) { const float v = acc[mt][nt][i] + DN_ALPHA * xr[i]; acc[mt][nt][i] = v; s += v; ss += v * v; }
;             }
;             s2[mh] = s; ss2[mh] = ss;
;         }
; #pragma unroll
;         for (int mh = 0; mh < 2; ++mh) { s2[mh] += __shfl_xor(s2[mh], 16); ss2[mh] += __shfl_xor(ss2[mh], 16); }
; #pragma unroll
;         for (int mh = 0; mh < 2; ++mh) { s2[mh] += __shfl_xor(s2[mh], 32); ss2[mh] += __shfl_xor(ss2[mh], 32); }
;         if (quad == 0) {
; #pragma unroll
;             for (int mh = 0; mh < 2; ++mh) *(f32x2*)&red[((mh * 16 + l15) * 8 + wid) * 2] = (f32x2){s2[mh], ss2[mh]};
;         }
;         __syncthreads();
	ds_read_b64 v[180:181], v133 offset:32768
	ds_read_b64 v[182:183], v133 offset:32800
	ds_read_b64 v[184:185], v133 offset:33792
	ds_read_b64 v[186:187], v133 offset:33824
	ds_read_b64 v[188:189], v133 offset:34816
	ds_read_b64 v[190:191], v133 offset:34848
	ds_read_b64 v[192:193], v133 offset:35840
	ds_read_b64 v[194:195], v133 offset:35872
	s_waitcnt lgkmcnt(7)
	v_lshlrev_b32_e32 v144, 16, v180
	v_and_b32_e32 v145, 0xffff0000, v180
	v_lshlrev_b32_e32 v146, 16, v181
	v_and_b32_e32 v147, 0xffff0000, v181
	v_fmac_f32_e32 v126, s58, v144
	v_fmac_f32_e32 v127, s58, v145
	v_fmac_f32_e32 v128, s58, v146
	v_fmac_f32_e32 v129, s58, v147
	v_mov_b32_e32 v196, v126
	v_mul_f32_e32 v197, v126, v126
	v_mov_b32_e32 v130, v127
	v_mul_f32_e32 v142, v127, v127
	v_add_f32_e32 v196, v196, v128
	v_fmac_f32_e32 v197, v128, v128
	v_add_f32_e32 v130, v130, v129
	v_fmac_f32_e32 v142, v129, v129
	s_waitcnt lgkmcnt(6)
	v_lshlrev_b32_e32 v148, 16, v182
	v_and_b32_e32 v149, 0xffff0000, v182
	v_lshlrev_b32_e32 v150, 16, v183
	v_and_b32_e32 v151, 0xffff0000, v183
	v_fmac_f32_e32 v122, s58, v148
	v_fmac_f32_e32 v123, s58, v149
	v_fmac_f32_e32 v124, s58, v150
	v_fmac_f32_e32 v125, s58, v151
	v_add_f32_e32 v196, v196, v122
	v_fmac_f32_e32 v197, v122, v122
	v_add_f32_e32 v130, v130, v123
	v_fmac_f32_e32 v142, v123, v123
	v_add_f32_e32 v196, v196, v124
	v_fmac_f32_e32 v197, v124, v124
	v_add_f32_e32 v130, v130, v125
	v_fmac_f32_e32 v142, v125, v125
	s_waitcnt lgkmcnt(5)
	v_lshlrev_b32_e32 v152, 16, v184
	v_and_b32_e32 v153, 0xffff0000, v184
	v_lshlrev_b32_e32 v154, 16, v185
	v_and_b32_e32 v155, 0xffff0000, v185
	v_fmac_f32_e32 v118, s58, v152
	v_fmac_f32_e32 v119, s58, v153
	v_fmac_f32_e32 v120, s58, v154
	v_fmac_f32_e32 v121, s58, v155
	v_add_f32_e32 v196, v196, v118
	v_fmac_f32_e32 v197, v118, v118
	v_add_f32_e32 v130, v130, v119
	v_fmac_f32_e32 v142, v119, v119
	v_add_f32_e32 v196, v196, v120
	v_fmac_f32_e32 v197, v120, v120
	v_add_f32_e32 v130, v130, v121
	v_fmac_f32_e32 v142, v121, v121
	s_waitcnt lgkmcnt(4)
	v_lshlrev_b32_e32 v156, 16, v186
	v_and_b32_e32 v157, 0xffff0000, v186
	v_lshlrev_b32_e32 v158, 16, v187
	v_and_b32_e32 v159, 0xffff0000, v187
	v_fmac_f32_e32 v114, s58, v156
	v_fmac_f32_e32 v115, s58, v157
	v_fmac_f32_e32 v116, s58, v158
	v_fmac_f32_e32 v117, s58, v159
	v_add_f32_e32 v196, v196, v114
	v_fmac_f32_e32 v197, v114, v114
	v_add_f32_e32 v130, v130, v115
	v_fmac_f32_e32 v142, v115, v115
	v_add_f32_e32 v196, v196, v116
	v_fmac_f32_e32 v197, v116, v116
	v_add_f32_e32 v130, v130, v117
	v_fmac_f32_e32 v142, v117, v117
	s_waitcnt lgkmcnt(3)
	v_lshlrev_b32_e32 v160, 16, v188
	v_and_b32_e32 v161, 0xffff0000, v188
	v_lshlrev_b32_e32 v162, 16, v189
	v_and_b32_e32 v163, 0xffff0000, v189
	v_fmac_f32_e32 v110, s58, v160
	v_fmac_f32_e32 v111, s58, v161
	v_fmac_f32_e32 v112, s58, v162
	v_fmac_f32_e32 v113, s58, v163
	v_add_f32_e32 v196, v196, v110
	v_fmac_f32_e32 v197, v110, v110
	v_add_f32_e32 v130, v130, v111
	v_fmac_f32_e32 v142, v111, v111
	v_add_f32_e32 v196, v196, v112
	v_fmac_f32_e32 v197, v112, v112
	v_add_f32_e32 v130, v130, v113
	v_fmac_f32_e32 v142, v113, v113
	s_waitcnt lgkmcnt(2)
	v_lshlrev_b32_e32 v164, 16, v190
	v_and_b32_e32 v165, 0xffff0000, v190
	v_lshlrev_b32_e32 v166, 16, v191
	v_and_b32_e32 v167, 0xffff0000, v191
	v_fmac_f32_e32 v106, s58, v164
	v_fmac_f32_e32 v107, s58, v165
	v_fmac_f32_e32 v108, s58, v166
	v_fmac_f32_e32 v109, s58, v167
	v_add_f32_e32 v196, v196, v106
	v_fmac_f32_e32 v197, v106, v106
	v_add_f32_e32 v130, v130, v107
	v_fmac_f32_e32 v142, v107, v107
	v_add_f32_e32 v196, v196, v108
	v_fmac_f32_e32 v197, v108, v108
	v_add_f32_e32 v130, v130, v109
	v_fmac_f32_e32 v142, v109, v109
	s_waitcnt lgkmcnt(1)
	v_lshlrev_b32_e32 v168, 16, v192
	v_and_b32_e32 v169, 0xffff0000, v192
	v_lshlrev_b32_e32 v170, 16, v193
	v_and_b32_e32 v171, 0xffff0000, v193
	v_fmac_f32_e32 v102, s58, v168
	v_fmac_f32_e32 v103, s58, v169
	v_fmac_f32_e32 v104, s58, v170
	v_fmac_f32_e32 v105, s58, v171
	v_add_f32_e32 v196, v196, v102
	v_fmac_f32_e32 v197, v102, v102
	v_add_f32_e32 v130, v130, v103
	v_fmac_f32_e32 v142, v103, v103
	v_add_f32_e32 v196, v196, v104
	v_fmac_f32_e32 v197, v104, v104
	v_add_f32_e32 v130, v130, v105
	v_fmac_f32_e32 v142, v105, v105
	s_waitcnt lgkmcnt(0)
	v_lshlrev_b32_e32 v172, 16, v194
	v_and_b32_e32 v173, 0xffff0000, v194
	v_lshlrev_b32_e32 v174, 16, v195
	v_and_b32_e32 v175, 0xffff0000, v195
	v_fmac_f32_e32 v66, s58, v172
	v_fmac_f32_e32 v67, s58, v173
	v_fmac_f32_e32 v68, s58, v174
	v_fmac_f32_e32 v69, s58, v175
	v_add_f32_e32 v196, v196, v66
	v_fmac_f32_e32 v197, v66, v66
	v_add_f32_e32 v130, v130, v67
	v_fmac_f32_e32 v142, v67, v67
	v_add_f32_e32 v196, v196, v68
	v_fmac_f32_e32 v197, v68, v68
	v_add_f32_e32 v130, v130, v69
	v_fmac_f32_e32 v142, v69, v69
	v_add_f32_e32 v196, v196, v130
	v_add_f32_e32 v197, v197, v142
	v_mov_b32_e32 v198, v196
	v_mov_b32_e32 v199, v197
	s_nop 1
	v_permlane16_swap_b32 v198, v196
	v_permlane16_swap_b32 v199, v197
	v_add_f32_e32 v196, v196, v198
	v_add_f32_e32 v197, v197, v199
	v_mov_b32_e32 v198, v196
	v_mov_b32_e32 v199, v197
	s_nop 1
	v_permlane32_swap_b32 v198, v196
	v_permlane32_swap_b32 v199, v197
	v_add_f32_e32 v196, v196, v198
	v_add_f32_e32 v197, v197, v199
	s_mov_b64 exec, 0xffff
	ds_write_b64 v134, v[196:197]
	s_mov_b64 exec, -1
	s_waitcnt lgkmcnt(0)
	s_barrier
; DI unsigned pk2(float lo, float hi) { const f32x2 v = {lo, hi}; const bf16x2_t b = __builtin_convertvector(v, bf16x2_t); return __builtin_bit_cast(unsigned, b); }
; DI size_t xb_off(int tok, int col) { return ((size_t)(((tok >> 7) * 32 + (col >> 5)) * 128 + (tok & 127))) * 32 + (col & 31); }
; DI void unit_O(const Params& p, char* lds, int l, int tile, int glu_tiles, int tile_b) {
;     ...
;         if (half == 0) issue_x(1);
; #pragma unroll
;         for (int mh = 0; mh < 2; ++mh) {
;             const int mt = half * 2 + mh, rl = mh * 16 + l15, row = mt * 16 + l15;
;             float s = 0.f, ss = 0.f;
; #pragma unroll
;             for (int w = 0; w < 4; ++w) { const f32x4 v = *(const f32x4*)&red[rl * 16 + 4 * w]; s += v[0] + v[2]; ss += v[1] + v[3]; }
;             const float mu = s * (1.f / 1024.f);
;             const float var = ss * (1.f / 1024.f) - mu * mu;
;             const float rs = rsqrtf(var + LN_EPS);
;             float* orow = xo + (r0 + row) * 1024 + wid * 128 + quad * 4;
;             bf16_t* brow = xbo + xb_off((int)r0 + row, wid * 128) + quad * 4;
;             const float* gp = GB + wid * 128 + quad * 4;
; #pragma unroll
;             for (int nt = 0; nt < 8; ++nt) {
;                 const f32x4 g = *(const f32x4*)(gp + nt * 16), bb = *(const f32x4*)(gp + 1024 + nt * 16);
;                 f32x4 o;
; #pragma unroll
;                 for (int i = 0; i < 4; ++i) o[i] = (acc[mt][nt][i] - mu) * rs * g[i] + bb[i];
;                 if (l == 0) *(u32x2*)(brow + (nt >> 1) * 4096 + (nt & 1) * 16) = (u32x2){pk2(o[0], o[1]), pk2(o[2], o[3])};
;                 else *(f32x4*)(orow + nt * 16) = o;
;             }
;         }
	s_add_u32 s92, s96, 0xc00
	s_addc_u32 s93, s97, 0
	s_add_u32 s40, s91, 0x8000
	s_mov_b32 m0, s40
	s_nop 0
	global_load_lds_dwordx4 v131, s[92:93]
	s_add_u32 s92, s92, 0x2000
	s_addc_u32 s93, s93, 0
	s_add_u32 m0, m0, 0x400
	s_nop 0
	global_load_lds_dwordx4 v131, s[92:93]
	s_add_u32 s92, s92, 0x2000
	s_addc_u32 s93, s93, 0
	s_add_u32 m0, m0, 0x400
	s_nop 0
	global_load_lds_dwordx4 v131, s[92:93]
	s_add_u32 s92, s92, 0x2000
	s_addc_u32 s93, s93, 0
	s_add_u32 m0, m0, 0x400
	s_nop 0
	global_load_lds_dwordx4 v131, s[92:93]
	ds_read_b128 v[160:163], v135 offset:0
	ds_read_b128 v[164:167], v135 offset:16
	ds_read_b128 v[168:171], v135 offset:32
	ds_read_b128 v[172:175], v135 offset:48
	s_waitcnt lgkmcnt(0)
	v_add_f32_e32 v160, v160, v162
	v_add_f32_e32 v161, v161, v163
	v_add_f32_e32 v164, v164, v166
	v_add_f32_e32 v165, v165, v167
	v_add_f32_e32 v168, v168, v170
	v_add_f32_e32 v169, v169, v171
	v_add_f32_e32 v172, v172, v174
	v_add_f32_e32 v173, v173, v175
	v_add_f32_e32 v160, v160, v164
	v_add_f32_e32 v161, v161, v165
	v_add_f32_e32 v168, v168, v172
	v_add_f32_e32 v169, v169, v173
	v_add_f32_e32 v160, v160, v168
	v_add_f32_e32 v161, v161, v169
	v_mul_f32_e32 v192, 0x3a800000, v160
	v_mul_f32_e32 v193, 0x3a800000, v161
	v_fma_f32 v193, -v192, v192, v193
	v_add_f32_e32 v193, 0x3727c5ac, v193
	v_rsq_f32_e32 v193, v193
	s_nop 0
	s_add_u32 s94, s78, 0x10000
	s_addc_u32 s95, s79, 0
	ds_read_b128 v[176:179], v136
	ds_read_b128 v[180:183], v136 offset:4096
	ds_read_b128 v[184:187], v136 offset:64
	ds_read_b128 v[188:191], v136 offset:4160
	s_waitcnt lgkmcnt(2)
	v_sub_f32_e32 v126, v126, v192
	v_mul_f32_e32 v126, v126, v193
	v_fma_f32 v126, v176, v126, v180
	v_sub_f32_e32 v127, v127, v192
	v_mul_f32_e32 v127, v127, v193
	v_fma_f32 v127, v177, v127, v181
	v_sub_f32_e32 v128, v128, v192
	v_mul_f32_e32 v128, v128, v193
	v_fma_f32 v128, v178, v128, v182
	v_sub_f32_e32 v129, v129, v192
	v_mul_f32_e32 v129, v129, v193
	v_fma_f32 v129, v179, v129, v183
	global_store_dwordx4 v137, v[126:129], s[94:95]
	ds_read_b128 v[176:179], v136 offset:128
	ds_read_b128 v[180:183], v136 offset:4224
	s_waitcnt lgkmcnt(2)
	v_sub_f32_e32 v122, v122, v192
	v_mul_f32_e32 v122, v122, v193
	v_fma_f32 v122, v184, v122, v188
	v_sub_f32_e32 v123, v123, v192
	v_mul_f32_e32 v123, v123, v193
	v_fma_f32 v123, v185, v123, v189
	v_sub_f32_e32 v124, v124, v192
	v_mul_f32_e32 v124, v124, v193
	v_fma_f32 v124, v186, v124, v190
	v_sub_f32_e32 v125, v125, v192
	v_mul_f32_e32 v125, v125, v193
	v_fma_f32 v125, v187, v125, v191
	global_store_dwordx4 v137, v[122:125], s[94:95] offset:64
	ds_read_b128 v[184:187], v136 offset:192
	ds_read_b128 v[188:191], v136 offset:4288
	s_waitcnt lgkmcnt(2)
	v_sub_f32_e32 v118, v118, v192
	v_mul_f32_e32 v118, v118, v193
	v_fma_f32 v118, v176, v118, v180
	v_sub_f32_e32 v119, v119, v192
	v_mul_f32_e32 v119, v119, v193
	v_fma_f32 v119, v177, v119, v181
	v_sub_f32_e32 v120, v120, v192
	v_mul_f32_e32 v120, v120, v193
	v_fma_f32 v120, v178, v120, v182
	v_sub_f32_e32 v121, v121, v192
	v_mul_f32_e32 v121, v121, v193
	v_fma_f32 v121, v179, v121, v183
	global_store_dwordx4 v137, v[118:121], s[94:95] offset:128
	ds_read_b128 v[176:179], v136 offset:256
	ds_read_b128 v[180:183], v136 offset:4352
	s_waitcnt lgkmcnt(2)
	v_sub_f32_e32 v114, v114, v192
	v_mul_f32_e32 v114, v114, v193
	v_fma_f32 v114, v184, v114, v188
	v_sub_f32_e32 v115, v115, v192
	v_mul_f32_e32 v115, v115, v193
	v_fma_f32 v115, v185, v115, v189
	v_sub_f32_e32 v116, v116, v192
	v_mul_f32_e32 v116, v116, v193
	v_fma_f32 v116, v186, v116, v190
	v_sub_f32_e32 v117, v117, v192
	v_mul_f32_e32 v117, v117, v193
	v_fma_f32 v117, v187, v117, v191
	global_store_dwordx4 v137, v[114:117], s[94:95] offset:192
	ds_read_b128 v[184:187], v136 offset:320
	ds_read_b128 v[188:191], v136 offset:4416
	s_waitcnt lgkmcnt(2)
	v_sub_f32_e32 v110, v110, v192
	v_mul_f32_e32 v110, v110, v193
	v_fma_f32 v110, v176, v110, v180
	v_sub_f32_e32 v111, v111, v192
	v_mul_f32_e32 v111, v111, v193
	v_fma_f32 v111, v177, v111, v181
	v_sub_f32_e32 v112, v112, v192
	v_mul_f32_e32 v112, v112, v193
	v_fma_f32 v112, v178, v112, v182
	v_sub_f32_e32 v113, v113, v192
	v_mul_f32_e32 v113, v113, v193
	v_fma_f32 v113, v179, v113, v183
	global_store_dwordx4 v137, v[110:113], s[94:95] offset:256
	ds_read_b128 v[176:179], v136 offset:384
	ds_read_b128 v[180:183], v136 offset:4480
	s_waitcnt lgkmcnt(2)
	v_sub_f32_e32 v106, v106, v192
	v_mul_f32_e32 v106, v106, v193
	v_fma_f32 v106, v184, v106, v188
	v_sub_f32_e32 v107, v107, v192
	v_mul_f32_e32 v107, v107, v193
	v_fma_f32 v107, v185, v107, v189
	v_sub_f32_e32 v108, v108, v192
	v_mul_f32_e32 v108, v108, v193
	v_fma_f32 v108, v186, v108, v190
	v_sub_f32_e32 v109, v109, v192
	v_mul_f32_e32 v109, v109, v193
	v_fma_f32 v109, v187, v109, v191
	global_store_dwordx4 v137, v[106:109], s[94:95] offset:320
	ds_read_b128 v[184:187], v136 offset:448
	ds_read_b128 v[188:191], v136 offset:4544
	s_waitcnt lgkmcnt(2)
	v_sub_f32_e32 v102, v102, v192
	v_mul_f32_e32 v102, v102, v193
	v_fma_f32 v102, v176, v102, v180
	v_sub_f32_e32 v103, v103, v192
	v_mul_f32_e32 v103, v103, v193
	v_fma_f32 v103, v177, v103, v181
	v_sub_f32_e32 v104, v104, v192
	v_mul_f32_e32 v104, v104, v193
	v_fma_f32 v104, v178, v104, v182
	v_sub_f32_e32 v105, v105, v192
	v_mul_f32_e32 v105, v105, v193
	v_fma_f32 v105, v179, v105, v183
	global_store_dwordx4 v137, v[102:105], s[94:95] offset:384
	s_waitcnt lgkmcnt(0)
	v_sub_f32_e32 v66, v66, v192
	v_mul_f32_e32 v66, v66, v193
	v_fma_f32 v66, v184, v66, v188
	v_sub_f32_e32 v67, v67, v192
	v_mul_f32_e32 v67, v67, v193
	v_fma_f32 v67, v185, v67, v189
	v_sub_f32_e32 v68, v68, v192
	v_mul_f32_e32 v68, v68, v193
	v_fma_f32 v68, v186, v68, v190
	v_sub_f32_e32 v69, v69, v192
	v_mul_f32_e32 v69, v69, v193
	v_fma_f32 v69, v187, v69, v191
	global_store_dwordx4 v137, v[66:69], s[94:95] offset:448
	s_waitcnt vmcnt(20) lgkmcnt(0)
	s_barrier
; DI float bf2f(unsigned b) { return __uint_as_float(b << 16); }
; DI void unit_O(const Params& p, char* lds, int l, int tile, int glu_tiles, int tile_b) {
;     ...
;         float s2[2], ss2[2];
; #pragma unroll
;         for (int mh = 0; mh < 2; ++mh) {
;             const int mt = half * 2 + mh, rl = mh * 16 + l15;
;             float s = 0.f, ss = 0.f;
; #pragma unroll
;             for (int nt = 0; nt < 8; ++nt) {
;                 f32x4 xr;
;                 if (l == 0) {
;                     const int chunk = wid * 32 + nt * 4 + quad;
;                     xr = *(const f32x4*)(XR + rl * 4096 + ((chunk ^ l15) << 4));
;                 } else {
;                     const u32x2 hb = *(const u32x2*)(XR + ((wid * 4 + (nt >> 1)) * 32 + rl) * 64 + (nt & 1) * 32 + quad * 8);
;                     xr = (f32x4){bf2f(hb[0] & 0xffffu), bf2f(hb[0] >> 16), bf2f(hb[1] & 0xffffu), bf2f(hb[1] >> 16)};
;                 }
; #pragma unroll
;                 for (int i = 0; i < 4; ++i) { const float v = acc[mt][nt][i] + DN_ALPHA * xr[i]; acc[mt][nt][i] = v; s += v; ss += v * v; }
;             }
;             s2[mh] = s; ss2[mh] = ss;
;         }
; #pragma unroll
;         for (int mh = 0; mh < 2; ++mh) { s2[mh] += __shfl_xor(s2[mh], 16); ss2[mh] += __shfl_xor(ss2[mh], 16); }
; #pragma unroll
;         for (int mh = 0; mh < 2; ++mh) { s2[mh] += __shfl_xor(s2[mh], 32); ss2[mh] += __shfl_xor(ss2[mh], 32); }
;         if (quad == 0) {
; #pragma unroll
;             for (int mh = 0; mh < 2; ++mh) *(f32x2*)&red[((mh * 16 + l15) * 8 + wid) * 2] = (f32x2){s2[mh], ss2[mh]};
;         }
;         __syncthreads();
	ds_read_b64 v[180:181], v133 offset:0
	ds_read_b64 v[182:183], v133 offset:32
	ds_read_b64 v[184:185], v133 offset:1024
	ds_read_b64 v[186:187], v133 offset:1056
	ds_read_b64 v[188:189], v133 offset:2048
	ds_read_b64 v[190:191], v133 offset:2080
	ds_read_b64 v[192:193], v133 offset:3072
	ds_read_b64 v[194:195], v133 offset:3104
	s_waitcnt lgkmcnt(7)
	v_lshlrev_b32_e32 v144, 16, v180
	v_and_b32_e32 v145, 0xffff0000, v180
	v_lshlrev_b32_e32 v146, 16, v181
	v_and_b32_e32 v147, 0xffff0000, v181
	v_fmac_f32_e32 v34, s58, v144
	v_fmac_f32_e32 v35, s58, v145
	v_fmac_f32_e32 v36, s58, v146
	v_fmac_f32_e32 v37, s58, v147
	v_mov_b32_e32 v196, v34
	v_mul_f32_e32 v197, v34, v34
	v_mov_b32_e32 v130, v35
	v_mul_f32_e32 v142, v35, v35
	v_add_f32_e32 v196, v196, v36
	v_fmac_f32_e32 v197, v36, v36
	v_add_f32_e32 v130, v130, v37
	v_fmac_f32_e32 v142, v37, v37
	s_waitcnt lgkmcnt(6)
	v_lshlrev_b32_e32 v148, 16, v182
	v_and_b32_e32 v149, 0xffff0000, v182
	v_lshlrev_b32_e32 v150, 16, v183
	v_and_b32_e32 v151, 0xffff0000, v183
	v_fmac_f32_e32 v30, s58, v148
	v_fmac_f32_e32 v31, s58, v149
	v_fmac_f32_e32 v32, s58, v150
	v_fmac_f32_e32 v33, s58, v151
	v_add_f32_e32 v196, v196, v30
	v_fmac_f32_e32 v197, v30, v30
	v_add_f32_e32 v130, v130, v31
	v_fmac_f32_e32 v142, v31, v31
	v_add_f32_e32 v196, v196, v32
	v_fmac_f32_e32 v197, v32, v32
	v_add_f32_e32 v130, v130, v33
	v_fmac_f32_e32 v142, v33, v33
	s_waitcnt lgkmcnt(5)
	v_lshlrev_b32_e32 v152, 16, v184
	v_and_b32_e32 v153, 0xffff0000, v184
	v_lshlrev_b32_e32 v154, 16, v185
	v_and_b32_e32 v155, 0xffff0000, v185
	v_fmac_f32_e32 v26, s58, v152
	v_fmac_f32_e32 v27, s58, v153
	v_fmac_f32_e32 v28, s58, v154
	v_fmac_f32_e32 v29, s58, v155
	v_add_f32_e32 v196, v196, v26
	v_fmac_f32_e32 v197, v26, v26
	v_add_f32_e32 v130, v130, v27
	v_fmac_f32_e32 v142, v27, v27
	v_add_f32_e32 v196, v196, v28
	v_fmac_f32_e32 v197, v28, v28
	v_add_f32_e32 v130, v130, v29
	v_fmac_f32_e32 v142, v29, v29
	s_waitcnt lgkmcnt(4)
	v_lshlrev_b32_e32 v156, 16, v186
	v_and_b32_e32 v157, 0xffff0000, v186
	v_lshlrev_b32_e32 v158, 16, v187
	v_and_b32_e32 v159, 0xffff0000, v187
	v_fmac_f32_e32 v22, s58, v156
	v_fmac_f32_e32 v23, s58, v157
	v_fmac_f32_e32 v24, s58, v158
	v_fmac_f32_e32 v25, s58, v159
	v_add_f32_e32 v196, v196, v22
	v_fmac_f32_e32 v197, v22, v22
	v_add_f32_e32 v130, v130, v23
	v_fmac_f32_e32 v142, v23, v23
	v_add_f32_e32 v196, v196, v24
	v_fmac_f32_e32 v197, v24, v24
	v_add_f32_e32 v130, v130, v25
	v_fmac_f32_e32 v142, v25, v25
	s_waitcnt lgkmcnt(3)
	v_lshlrev_b32_e32 v160, 16, v188
	v_and_b32_e32 v161, 0xffff0000, v188
	v_lshlrev_b32_e32 v162, 16, v189
	v_and_b32_e32 v163, 0xffff0000, v189
	v_fmac_f32_e32 v18, s58, v160
	v_fmac_f32_e32 v19, s58, v161
	v_fmac_f32_e32 v20, s58, v162
	v_fmac_f32_e32 v21, s58, v163
	v_add_f32_e32 v196, v196, v18
	v_fmac_f32_e32 v197, v18, v18
	v_add_f32_e32 v130, v130, v19
	v_fmac_f32_e32 v142, v19, v19
	v_add_f32_e32 v196, v196, v20
	v_fmac_f32_e32 v197, v20, v20
	v_add_f32_e32 v130, v130, v21
	v_fmac_f32_e32 v142, v21, v21
	s_waitcnt lgkmcnt(2)
	v_lshlrev_b32_e32 v164, 16, v190
	v_and_b32_e32 v165, 0xffff0000, v190
	v_lshlrev_b32_e32 v166, 16, v191
	v_and_b32_e32 v167, 0xffff0000, v191
	v_fmac_f32_e32 v14, s58, v164
	v_fmac_f32_e32 v15, s58, v165
	v_fmac_f32_e32 v16, s58, v166
	v_fmac_f32_e32 v17, s58, v167
	v_add_f32_e32 v196, v196, v14
	v_fmac_f32_e32 v197, v14, v14
	v_add_f32_e32 v130, v130, v15
	v_fmac_f32_e32 v142, v15, v15
	v_add_f32_e32 v196, v196, v16
	v_fmac_f32_e32 v197, v16, v16
	v_add_f32_e32 v130, v130, v17
	v_fmac_f32_e32 v142, v17, v17
	s_waitcnt lgkmcnt(1)
	v_lshlrev_b32_e32 v168, 16, v192
	v_and_b32_e32 v169, 0xffff0000, v192
	v_lshlrev_b32_e32 v170, 16, v193
	v_and_b32_e32 v171, 0xffff0000, v193
	v_fmac_f32_e32 v10, s58, v168
	v_fmac_f32_e32 v11, s58, v169
	v_fmac_f32_e32 v12, s58, v170
	v_fmac_f32_e32 v13, s58, v171
	v_add_f32_e32 v196, v196, v10
	v_fmac_f32_e32 v197, v10, v10
	v_add_f32_e32 v130, v130, v11
	v_fmac_f32_e32 v142, v11, v11
	v_add_f32_e32 v196, v196, v12
	v_fmac_f32_e32 v197, v12, v12
	v_add_f32_e32 v130, v130, v13
	v_fmac_f32_e32 v142, v13, v13
	s_waitcnt lgkmcnt(0)
	v_lshlrev_b32_e32 v172, 16, v194
	v_and_b32_e32 v173, 0xffff0000, v194
	v_lshlrev_b32_e32 v174, 16, v195
	v_and_b32_e32 v175, 0xffff0000, v195
	v_fmac_f32_e32 v6, s58, v172
	v_fmac_f32_e32 v7, s58, v173
	v_fmac_f32_e32 v8, s58, v174
	v_fmac_f32_e32 v9, s58, v175
	v_add_f32_e32 v196, v196, v6
	v_fmac_f32_e32 v197, v6, v6
	v_add_f32_e32 v130, v130, v7
	v_fmac_f32_e32 v142, v7, v7
	v_add_f32_e32 v196, v196, v8
	v_fmac_f32_e32 v197, v8, v8
	v_add_f32_e32 v130, v130, v9
	v_fmac_f32_e32 v142, v9, v9
	v_add_f32_e32 v196, v196, v130
	v_add_f32_e32 v197, v197, v142
	v_mov_b32_e32 v198, v196
	v_mov_b32_e32 v199, v197
	s_nop 1
	v_permlane16_swap_b32 v198, v196
	v_permlane16_swap_b32 v199, v197
	v_add_f32_e32 v196, v196, v198
	v_add_f32_e32 v197, v197, v199
	v_mov_b32_e32 v198, v196
	v_mov_b32_e32 v199, v197
	s_nop 1
	v_permlane32_swap_b32 v198, v196
	v_permlane32_swap_b32 v199, v197
	v_add_f32_e32 v196, v196, v198
	v_add_f32_e32 v197, v197, v199
	s_mov_b64 exec, 0xffff
	ds_write_b64 v134, v[196:197]
	s_mov_b64 exec, -1
	s_waitcnt lgkmcnt(0)
	s_barrier
; DI unsigned pk2(float lo, float hi) { const f32x2 v = {lo, hi}; const bf16x2_t b = __builtin_convertvector(v, bf16x2_t); return __builtin_bit_cast(unsigned, b); }
; DI size_t xb_off(int tok, int col) { return ((size_t)(((tok >> 7) * 32 + (col >> 5)) * 128 + (tok & 127))) * 32 + (col & 31); }
; DI void unit_O(const Params& p, char* lds, int l, int tile, int glu_tiles, int tile_b) {
;     ...
;         for (int mh = 0; mh < 2; ++mh) {
;             const int mt = half * 2 + mh, rl = mh * 16 + l15, row = mt * 16 + l15;
;             float s = 0.f, ss = 0.f;
; #pragma unroll
;             for (int w = 0; w < 4; ++w) { const f32x4 v = *(const f32x4*)&red[rl * 16 + 4 * w]; s += v[0] + v[2]; ss += v[1] + v[3]; }
;             const float mu = s * (1.f / 1024.f);
;             const float var = ss * (1.f / 1024.f) - mu * mu;
;             const float rs = rsqrtf(var + LN_EPS);
;             float* orow = xo + (r0 + row) * 1024 + wid * 128 + quad * 4;
;             bf16_t* brow = xbo + xb_off((int)r0 + row, wid * 128) + quad * 4;
;             const float* gp = GB + wid * 128 + quad * 4;
; #pragma unroll
;             for (int nt = 0; nt < 8; ++nt) {
;                 const f32x4 g = *(const f32x4*)(gp + nt * 16), bb = *(const f32x4*)(gp + 1024 + nt * 16);
;                 f32x4 o;
; #pragma unroll
;                 for (int i = 0; i < 4; ++i) o[i] = (acc[mt][nt][i] - mu) * rs * g[i] + bb[i];
;                 if (l == 0) *(u32x2*)(brow + (nt >> 1) * 4096 + (nt & 1) * 16) = (u32x2){pk2(o[0], o[1]), pk2(o[2], o[3])};
;                 else *(f32x4*)(orow + nt * 16) = o;
	ds_read_b128 v[160:163], v135 offset:0
	ds_read_b128 v[164:167], v135 offset:16
	ds_read_b128 v[168:171], v135 offset:32
	ds_read_b128 v[172:175], v135 offset:48
	s_waitcnt lgkmcnt(0)
	v_add_f32_e32 v160, v160, v162
	v_add_f32_e32 v161, v161, v163
	v_add_f32_e32 v164, v164, v166
	v_add_f32_e32 v165, v165, v167
	v_add_f32_e32 v168, v168, v170
	v_add_f32_e32 v169, v169, v171
	v_add_f32_e32 v172, v172, v174
	v_add_f32_e32 v173, v173, v175
	v_add_f32_e32 v160, v160, v164
	v_add_f32_e32 v161, v161, v165
	v_add_f32_e32 v168, v168, v172
	v_add_f32_e32 v169, v169, v173
	v_add_f32_e32 v160, v160, v168
	v_add_f32_e32 v161, v161, v169
	v_mul_f32_e32 v192, 0x3a800000, v160
	v_mul_f32_e32 v193, 0x3a800000, v161
	v_fma_f32 v193, -v192, v192, v193
	v_add_f32_e32 v193, 0x3727c5ac, v193
	v_rsq_f32_e32 v193, v193
	s_nop 0
	s_add_u32 s94, s78, 0x20000
	s_addc_u32 s95, s79, 0
	ds_read_b128 v[176:179], v136
	ds_read_b128 v[180:183], v136 offset:4096
	ds_read_b128 v[184:187], v136 offset:64
	ds_read_b128 v[188:191], v136 offset:4160
	s_waitcnt lgkmcnt(2)
	v_sub_f32_e32 v34, v34, v192
	v_mul_f32_e32 v34, v34, v193
	v_fma_f32 v34, v176, v34, v180
	v_sub_f32_e32 v35, v35, v192
	v_mul_f32_e32 v35, v35, v193
	v_fma_f32 v35, v177, v35, v181
	v_sub_f32_e32 v36, v36, v192
	v_mul_f32_e32 v36, v36, v193
	v_fma_f32 v36, v178, v36, v182
	v_sub_f32_e32 v37, v37, v192
	v_mul_f32_e32 v37, v37, v193
	v_fma_f32 v37, v179, v37, v183
	global_store_dwordx4 v137, v[34:37], s[94:95]
	ds_read_b128 v[176:179], v136 offset:128
	ds_read_b128 v[180:183], v136 offset:4224
	s_waitcnt lgkmcnt(2)
	v_sub_f32_e32 v30, v30, v192
	v_mul_f32_e32 v30, v30, v193
	v_fma_f32 v30, v184, v30, v188
	v_sub_f32_e32 v31, v31, v192
	v_mul_f32_e32 v31, v31, v193
	v_fma_f32 v31, v185, v31, v189
	v_sub_f32_e32 v32, v32, v192
	v_mul_f32_e32 v32, v32, v193
	v_fma_f32 v32, v186, v32, v190
	v_sub_f32_e32 v33, v33, v192
	v_mul_f32_e32 v33, v33, v193
	v_fma_f32 v33, v187, v33, v191
	global_store_dwordx4 v137, v[30:33], s[94:95] offset:64
	ds_read_b128 v[184:187], v136 offset:192
	ds_read_b128 v[188:191], v136 offset:4288
	s_waitcnt lgkmcnt(2)
	v_sub_f32_e32 v26, v26, v192
	v_mul_f32_e32 v26, v26, v193
	v_fma_f32 v26, v176, v26, v180
	v_sub_f32_e32 v27, v27, v192
	v_mul_f32_e32 v27, v27, v193
	v_fma_f32 v27, v177, v27, v181
	v_sub_f32_e32 v28, v28, v192
	v_mul_f32_e32 v28, v28, v193
	v_fma_f32 v28, v178, v28, v182
	v_sub_f32_e32 v29, v29, v192
	v_mul_f32_e32 v29, v29, v193
	v_fma_f32 v29, v179, v29, v183
	global_store_dwordx4 v137, v[26:29], s[94:95] offset:128
	ds_read_b128 v[176:179], v136 offset:256
	ds_read_b128 v[180:183], v136 offset:4352
	s_waitcnt lgkmcnt(2)
	v_sub_f32_e32 v22, v22, v192
	v_mul_f32_e32 v22, v22, v193
	v_fma_f32 v22, v184, v22, v188
	v_sub_f32_e32 v23, v23, v192
	v_mul_f32_e32 v23, v23, v193
	v_fma_f32 v23, v185, v23, v189
	v_sub_f32_e32 v24, v24, v192
	v_mul_f32_e32 v24, v24, v193
	v_fma_f32 v24, v186, v24, v190
	v_sub_f32_e32 v25, v25, v192
	v_mul_f32_e32 v25, v25, v193
	v_fma_f32 v25, v187, v25, v191
	global_store_dwordx4 v137, v[22:25], s[94:95] offset:192
	ds_read_b128 v[184:187], v136 offset:320
	ds_read_b128 v[188:191], v136 offset:4416
	s_waitcnt lgkmcnt(2)
	v_sub_f32_e32 v18, v18, v192
	v_mul_f32_e32 v18, v18, v193
	v_fma_f32 v18, v176, v18, v180
	v_sub_f32_e32 v19, v19, v192
	v_mul_f32_e32 v19, v19, v193
	v_fma_f32 v19, v177, v19, v181
	v_sub_f32_e32 v20, v20, v192
	v_mul_f32_e32 v20, v20, v193
	v_fma_f32 v20, v178, v20, v182
	v_sub_f32_e32 v21, v21, v192
	v_mul_f32_e32 v21, v21, v193
	v_fma_f32 v21, v179, v21, v183
	global_store_dwordx4 v137, v[18:21], s[94:95] offset:256
	ds_read_b128 v[176:179], v136 offset:384
	ds_read_b128 v[180:183], v136 offset:4480
	s_waitcnt lgkmcnt(2)
	v_sub_f32_e32 v14, v14, v192
	v_mul_f32_e32 v14, v14, v193
	v_fma_f32 v14, v184, v14, v188
	v_sub_f32_e32 v15, v15, v192
	v_mul_f32_e32 v15, v15, v193
	v_fma_f32 v15, v185, v15, v189
	v_sub_f32_e32 v16, v16, v192
	v_mul_f32_e32 v16, v16, v193
	v_fma_f32 v16, v186, v16, v190
	v_sub_f32_e32 v17, v17, v192
	v_mul_f32_e32 v17, v17, v193
	v_fma_f32 v17, v187, v17, v191
	global_store_dwordx4 v137, v[14:17], s[94:95] offset:320
	ds_read_b128 v[184:187], v136 offset:448
	ds_read_b128 v[188:191], v136 offset:4544
	s_waitcnt lgkmcnt(2)
	v_sub_f32_e32 v10, v10, v192
	v_mul_f32_e32 v10, v10, v193
	v_fma_f32 v10, v176, v10, v180
	v_sub_f32_e32 v11, v11, v192
	v_mul_f32_e32 v11, v11, v193
	v_fma_f32 v11, v177, v11, v181
	v_sub_f32_e32 v12, v12, v192
	v_mul_f32_e32 v12, v12, v193
	v_fma_f32 v12, v178, v12, v182
	v_sub_f32_e32 v13, v13, v192
	v_mul_f32_e32 v13, v13, v193
	v_fma_f32 v13, v179, v13, v183
	global_store_dwordx4 v137, v[10:13], s[94:95] offset:384
	s_waitcnt lgkmcnt(0)
	v_sub_f32_e32 v6, v6, v192
	v_mul_f32_e32 v6, v6, v193
	v_fma_f32 v6, v184, v6, v188
	v_sub_f32_e32 v7, v7, v192
	v_mul_f32_e32 v7, v7, v193
	v_fma_f32 v7, v185, v7, v189
	v_sub_f32_e32 v8, v8, v192
	v_mul_f32_e32 v8, v8, v193
	v_fma_f32 v8, v186, v8, v190
	v_sub_f32_e32 v9, v9, v192
	v_mul_f32_e32 v9, v9, v193
	v_fma_f32 v9, v187, v9, v191
	global_store_dwordx4 v137, v[6:9], s[94:95] offset:448
	s_waitcnt vmcnt(16) lgkmcnt(0)
	s_barrier
; DI float bf2f(unsigned b) { return __uint_as_float(b << 16); }
; DI void unit_O(const Params& p, char* lds, int l, int tile, int glu_tiles, int tile_b) {
;     ...
;         float s2[2], ss2[2];
; #pragma unroll
;         for (int mh = 0; mh < 2; ++mh) {
;             const int mt = half * 2 + mh, rl = mh * 16 + l15;
;             float s = 0.f, ss = 0.f;
; #pragma unroll
;             for (int nt = 0; nt < 8; ++nt) {
;                 f32x4 xr;
;                 if (l == 0) {
;                     const int chunk = wid * 32 + nt * 4 + quad;
;                     xr = *(const f32x4*)(XR + rl * 4096 + ((chunk ^ l15) << 4));
;                 } else {
;                     const u32x2 hb = *(const u32x2*)(XR + ((wid * 4 + (nt >> 1)) * 32 + rl) * 64 + (nt & 1) * 32 + quad * 8);
;                     xr = (f32x4){bf2f(hb[0] & 0xffffu), bf2f(hb[0] >> 16), bf2f(hb[1] & 0xffffu), bf2f(hb[1] >> 16)};
;                 }
; #pragma unroll
;                 for (int i = 0; i < 4; ++i) { const float v = acc[mt][nt][i] + DN_ALPHA * xr[i]; acc[mt][nt][i] = v; s += v; ss += v * v; }
;             }
;             s2[mh] = s; ss2[mh] = ss;
;         }
; #pragma unroll
;         for (int mh = 0; mh < 2; ++mh) { s2[mh] += __shfl_xor(s2[mh], 16); ss2[mh] += __shfl_xor(ss2[mh], 16); }
; #pragma unroll
;         for (int mh = 0; mh < 2; ++mh) { s2[mh] += __shfl_xor(s2[mh], 32); ss2[mh] += __shfl_xor(ss2[mh], 32); }
;         if (quad == 0) {
; #pragma unroll
;             for (int mh = 0; mh < 2; ++mh) *(f32x2*)&red[((mh * 16 + l15) * 8 + wid) * 2] = (f32x2){s2[mh], ss2[mh]};
;         }
;         __syncthreads();
	ds_read_b64 v[180:181], v133 offset:32768
	ds_read_b64 v[182:183], v133 offset:32800
	ds_read_b64 v[184:185], v133 offset:33792
	ds_read_b64 v[186:187], v133 offset:33824
	ds_read_b64 v[188:189], v133 offset:34816
	ds_read_b64 v[190:191], v133 offset:34848
	ds_read_b64 v[192:193], v133 offset:35840
	ds_read_b64 v[194:195], v133 offset:35872
	s_waitcnt lgkmcnt(7)
	v_lshlrev_b32_e32 v144, 16, v180
	v_and_b32_e32 v145, 0xffff0000, v180
	v_lshlrev_b32_e32 v146, 16, v181
	v_and_b32_e32 v147, 0xffff0000, v181
	v_fmac_f32_e32 v62, s58, v144
	v_fmac_f32_e32 v63, s58, v145
	v_fmac_f32_e32 v64, s58, v146
	v_fmac_f32_e32 v65, s58, v147
	v_mov_b32_e32 v196, v62
	v_mul_f32_e32 v197, v62, v62
	v_mov_b32_e32 v130, v63
	v_mul_f32_e32 v142, v63, v63
	v_add_f32_e32 v196, v196, v64
	v_fmac_f32_e32 v197, v64, v64
	v_add_f32_e32 v130, v130, v65
	v_fmac_f32_e32 v142, v65, v65
	s_waitcnt lgkmcnt(6)
	v_lshlrev_b32_e32 v148, 16, v182
	v_and_b32_e32 v149, 0xffff0000, v182
	v_lshlrev_b32_e32 v150, 16, v183
	v_and_b32_e32 v151, 0xffff0000, v183
	v_fmac_f32_e32 v58, s58, v148
	v_fmac_f32_e32 v59, s58, v149
	v_fmac_f32_e32 v60, s58, v150
	v_fmac_f32_e32 v61, s58, v151
	v_add_f32_e32 v196, v196, v58
	v_fmac_f32_e32 v197, v58, v58
	v_add_f32_e32 v130, v130, v59
	v_fmac_f32_e32 v142, v59, v59
	v_add_f32_e32 v196, v196, v60
	v_fmac_f32_e32 v197, v60, v60
	v_add_f32_e32 v130, v130, v61
	v_fmac_f32_e32 v142, v61, v61
	s_waitcnt lgkmcnt(5)
	v_lshlrev_b32_e32 v152, 16, v184
	v_and_b32_e32 v153, 0xffff0000, v184
	v_lshlrev_b32_e32 v154, 16, v185
	v_and_b32_e32 v155, 0xffff0000, v185
	v_fmac_f32_e32 v54, s58, v152
	v_fmac_f32_e32 v55, s58, v153
	v_fmac_f32_e32 v56, s58, v154
	v_fmac_f32_e32 v57, s58, v155
	v_add_f32_e32 v196, v196, v54
	v_fmac_f32_e32 v197, v54, v54
	v_add_f32_e32 v130, v130, v55
	v_fmac_f32_e32 v142, v55, v55
	v_add_f32_e32 v196, v196, v56
	v_fmac_f32_e32 v197, v56, v56
	v_add_f32_e32 v130, v130, v57
	v_fmac_f32_e32 v142, v57, v57
	s_waitcnt lgkmcnt(4)
	v_lshlrev_b32_e32 v156, 16, v186
	v_and_b32_e32 v157, 0xffff0000, v186
	v_lshlrev_b32_e32 v158, 16, v187
	v_and_b32_e32 v159, 0xffff0000, v187
	v_fmac_f32_e32 v50, s58, v156
	v_fmac_f32_e32 v51, s58, v157
	v_fmac_f32_e32 v52, s58, v158
	v_fmac_f32_e32 v53, s58, v159
	v_add_f32_e32 v196, v196, v50
	v_fmac_f32_e32 v197, v50, v50
	v_add_f32_e32 v130, v130, v51
	v_fmac_f32_e32 v142, v51, v51
	v_add_f32_e32 v196, v196, v52
	v_fmac_f32_e32 v197, v52, v52
	v_add_f32_e32 v130, v130, v53
	v_fmac_f32_e32 v142, v53, v53
	s_waitcnt lgkmcnt(3)
	v_lshlrev_b32_e32 v160, 16, v188
	v_and_b32_e32 v161, 0xffff0000, v188
	v_lshlrev_b32_e32 v162, 16, v189
	v_and_b32_e32 v163, 0xffff0000, v189
	v_fmac_f32_e32 v46, s58, v160
	v_fmac_f32_e32 v47, s58, v161
	v_fmac_f32_e32 v48, s58, v162
	v_fmac_f32_e32 v49, s58, v163
	v_add_f32_e32 v196, v196, v46
	v_fmac_f32_e32 v197, v46, v46
	v_add_f32_e32 v130, v130, v47
	v_fmac_f32_e32 v142, v47, v47
	v_add_f32_e32 v196, v196, v48
	v_fmac_f32_e32 v197, v48, v48
	v_add_f32_e32 v130, v130, v49
	v_fmac_f32_e32 v142, v49, v49
	s_waitcnt lgkmcnt(2)
	v_lshlrev_b32_e32 v164, 16, v190
	v_and_b32_e32 v165, 0xffff0000, v190
	v_lshlrev_b32_e32 v166, 16, v191
	v_and_b32_e32 v167, 0xffff0000, v191
	v_fmac_f32_e32 v42, s58, v164
	v_fmac_f32_e32 v43, s58, v165
	v_fmac_f32_e32 v44, s58, v166
	v_fmac_f32_e32 v45, s58, v167
	v_add_f32_e32 v196, v196, v42
	v_fmac_f32_e32 v197, v42, v42
	v_add_f32_e32 v130, v130, v43
	v_fmac_f32_e32 v142, v43, v43
	v_add_f32_e32 v196, v196, v44
	v_fmac_f32_e32 v197, v44, v44
	v_add_f32_e32 v130, v130, v45
	v_fmac_f32_e32 v142, v45, v45
	s_waitcnt lgkmcnt(1)
	v_lshlrev_b32_e32 v168, 16, v192
	v_and_b32_e32 v169, 0xffff0000, v192
	v_lshlrev_b32_e32 v170, 16, v193
	v_and_b32_e32 v171, 0xffff0000, v193
	v_fmac_f32_e32 v38, s58, v168
	v_fmac_f32_e32 v39, s58, v169
	v_fmac_f32_e32 v40, s58, v170
	v_fmac_f32_e32 v41, s58, v171
	v_add_f32_e32 v196, v196, v38
	v_fmac_f32_e32 v197, v38, v38
	v_add_f32_e32 v130, v130, v39
	v_fmac_f32_e32 v142, v39, v39
	v_add_f32_e32 v196, v196, v40
	v_fmac_f32_e32 v197, v40, v40
	v_add_f32_e32 v130, v130, v41
	v_fmac_f32_e32 v142, v41, v41
	s_waitcnt lgkmcnt(0)
	v_lshlrev_b32_e32 v172, 16, v194
	v_and_b32_e32 v173, 0xffff0000, v194
	v_lshlrev_b32_e32 v174, 16, v195
	v_and_b32_e32 v175, 0xffff0000, v195
	v_fmac_f32_e32 v2, s58, v172
	v_fmac_f32_e32 v3, s58, v173
	v_fmac_f32_e32 v4, s58, v174
	v_fmac_f32_e32 v5, s58, v175
	v_add_f32_e32 v196, v196, v2
	v_fmac_f32_e32 v197, v2, v2
	v_add_f32_e32 v130, v130, v3
	v_fmac_f32_e32 v142, v3, v3
	v_add_f32_e32 v196, v196, v4
	v_fmac_f32_e32 v197, v4, v4
	v_add_f32_e32 v130, v130, v5
	v_fmac_f32_e32 v142, v5, v5
	v_add_f32_e32 v196, v196, v130
	v_add_f32_e32 v197, v197, v142
	v_mov_b32_e32 v198, v196
	v_mov_b32_e32 v199, v197
	s_nop 1
	v_permlane16_swap_b32 v198, v196
	v_permlane16_swap_b32 v199, v197
	v_add_f32_e32 v196, v196, v198
	v_add_f32_e32 v197, v197, v199
	v_mov_b32_e32 v198, v196
	v_mov_b32_e32 v199, v197
	s_nop 1
	v_permlane32_swap_b32 v198, v196
	v_permlane32_swap_b32 v199, v197
	v_add_f32_e32 v196, v196, v198
	v_add_f32_e32 v197, v197, v199
	s_mov_b64 exec, 0xffff
	ds_write_b64 v134, v[196:197]
	s_mov_b64 exec, -1
	s_waitcnt lgkmcnt(0)
	s_barrier
; DI unsigned pk2(float lo, float hi) { const f32x2 v = {lo, hi}; const bf16x2_t b = __builtin_convertvector(v, bf16x2_t); return __builtin_bit_cast(unsigned, b); }
; DI size_t xb_off(int tok, int col) { return ((size_t)(((tok >> 7) * 32 + (col >> 5)) * 128 + (tok & 127))) * 32 + (col & 31); }
; DI void unit_O(const Params& p, char* lds, int l, int tile, int glu_tiles, int tile_b) {
;     ...
;         for (int mh = 0; mh < 2; ++mh) {
;             const int mt = half * 2 + mh, rl = mh * 16 + l15, row = mt * 16 + l15;
;             float s = 0.f, ss = 0.f;
; #pragma unroll
;             for (int w = 0; w < 4; ++w) { const f32x4 v = *(const f32x4*)&red[rl * 16 + 4 * w]; s += v[0] + v[2]; ss += v[1] + v[3]; }
;             const float mu = s * (1.f / 1024.f);
;             const float var = ss * (1.f / 1024.f) - mu * mu;
;             const float rs = rsqrtf(var + LN_EPS);
;             float* orow = xo + (r0 + row) * 1024 + wid * 128 + quad * 4;
;             bf16_t* brow = xbo + xb_off((int)r0 + row, wid * 128) + quad * 4;
;             const float* gp = GB + wid * 128 + quad * 4;
; #pragma unroll
;             for (int nt = 0; nt < 8; ++nt) {
;                 const f32x4 g = *(const f32x4*)(gp + nt * 16), bb = *(const f32x4*)(gp + 1024 + nt * 16);
;                 f32x4 o;
; #pragma unroll
;                 for (int i = 0; i < 4; ++i) o[i] = (acc[mt][nt][i] - mu) * rs * g[i] + bb[i];
;                 if (l == 0) *(u32x2*)(brow + (nt >> 1) * 4096 + (nt & 1) * 16) = (u32x2){pk2(o[0], o[1]), pk2(o[2], o[3])};
;                 else *(f32x4*)(orow + nt * 16) = o;
	ds_read_b128 v[160:163], v135 offset:0
	ds_read_b128 v[164:167], v135 offset:16
	ds_read_b128 v[168:171], v135 offset:32
	ds_read_b128 v[172:175], v135 offset:48
	s_waitcnt lgkmcnt(0)
	v_add_f32_e32 v160, v160, v162
	v_add_f32_e32 v161, v161, v163
	v_add_f32_e32 v164, v164, v166
	v_add_f32_e32 v165, v165, v167
	v_add_f32_e32 v168, v168, v170
	v_add_f32_e32 v169, v169, v171
	v_add_f32_e32 v172, v172, v174
	v_add_f32_e32 v173, v173, v175
	v_add_f32_e32 v160, v160, v164
	v_add_f32_e32 v161, v161, v165
	v_add_f32_e32 v168, v168, v172
	v_add_f32_e32 v169, v169, v173
	v_add_f32_e32 v160, v160, v168
	v_add_f32_e32 v161, v161, v169
	v_mul_f32_e32 v192, 0x3a800000, v160
	v_mul_f32_e32 v193, 0x3a800000, v161
	v_fma_f32 v193, -v192, v192, v193
	v_add_f32_e32 v193, 0x3727c5ac, v193
	v_rsq_f32_e32 v193, v193
	s_nop 0
	s_add_u32 s94, s78, 0x30000
	s_addc_u32 s95, s79, 0
	ds_read_b128 v[176:179], v136
	ds_read_b128 v[180:183], v136 offset:4096
	ds_read_b128 v[184:187], v136 offset:64
	ds_read_b128 v[188:191], v136 offset:4160
	s_waitcnt lgkmcnt(2)
	v_sub_f32_e32 v62, v62, v192
	v_mul_f32_e32 v62, v62, v193
	v_fma_f32 v62, v176, v62, v180
	v_sub_f32_e32 v63, v63, v192
	v_mul_f32_e32 v63, v63, v193
	v_fma_f32 v63, v177, v63, v181
	v_sub_f32_e32 v64, v64, v192
	v_mul_f32_e32 v64, v64, v193
	v_fma_f32 v64, v178, v64, v182
	v_sub_f32_e32 v65, v65, v192
	v_mul_f32_e32 v65, v65, v193
	v_fma_f32 v65, v179, v65, v183
	global_store_dwordx4 v137, v[62:65], s[94:95]
	ds_read_b128 v[176:179], v136 offset:128
	ds_read_b128 v[180:183], v136 offset:4224
	s_waitcnt lgkmcnt(2)
	v_sub_f32_e32 v58, v58, v192
	v_mul_f32_e32 v58, v58, v193
	v_fma_f32 v58, v184, v58, v188
	v_sub_f32_e32 v59, v59, v192
	v_mul_f32_e32 v59, v59, v193
	v_fma_f32 v59, v185, v59, v189
	v_sub_f32_e32 v60, v60, v192
	v_mul_f32_e32 v60, v60, v193
	v_fma_f32 v60, v186, v60, v190
	v_sub_f32_e32 v61, v61, v192
	v_mul_f32_e32 v61, v61, v193
	v_fma_f32 v61, v187, v61, v191
	global_store_dwordx4 v137, v[58:61], s[94:95] offset:64
	ds_read_b128 v[184:187], v136 offset:192
	ds_read_b128 v[188:191], v136 offset:4288
	s_waitcnt lgkmcnt(2)
	v_sub_f32_e32 v54, v54, v192
	v_mul_f32_e32 v54, v54, v193
	v_fma_f32 v54, v176, v54, v180
	v_sub_f32_e32 v55, v55, v192
	v_mul_f32_e32 v55, v55, v193
	v_fma_f32 v55, v177, v55, v181
	v_sub_f32_e32 v56, v56, v192
	v_mul_f32_e32 v56, v56, v193
	v_fma_f32 v56, v178, v56, v182
	v_sub_f32_e32 v57, v57, v192
	v_mul_f32_e32 v57, v57, v193
	v_fma_f32 v57, v179, v57, v183
	global_store_dwordx4 v137, v[54:57], s[94:95] offset:128
	ds_read_b128 v[176:179], v136 offset:256
	ds_read_b128 v[180:183], v136 offset:4352
	s_waitcnt lgkmcnt(2)
	v_sub_f32_e32 v50, v50, v192
	v_mul_f32_e32 v50, v50, v193
	v_fma_f32 v50, v184, v50, v188
	v_sub_f32_e32 v51, v51, v192
	v_mul_f32_e32 v51, v51, v193
	v_fma_f32 v51, v185, v51, v189
	v_sub_f32_e32 v52, v52, v192
	v_mul_f32_e32 v52, v52, v193
	v_fma_f32 v52, v186, v52, v190
	v_sub_f32_e32 v53, v53, v192
	v_mul_f32_e32 v53, v53, v193
	v_fma_f32 v53, v187, v53, v191
	global_store_dwordx4 v137, v[50:53], s[94:95] offset:192
	ds_read_b128 v[184:187], v136 offset:320
	ds_read_b128 v[188:191], v136 offset:4416
	s_waitcnt lgkmcnt(2)
	v_sub_f32_e32 v46, v46, v192
	v_mul_f32_e32 v46, v46, v193
	v_fma_f32 v46, v176, v46, v180
	v_sub_f32_e32 v47, v47, v192
	v_mul_f32_e32 v47, v47, v193
	v_fma_f32 v47, v177, v47, v181
	v_sub_f32_e32 v48, v48, v192
	v_mul_f32_e32 v48, v48, v193
	v_fma_f32 v48, v178, v48, v182
	v_sub_f32_e32 v49, v49, v192
	v_mul_f32_e32 v49, v49, v193
	v_fma_f32 v49, v179, v49, v183
	global_store_dwordx4 v137, v[46:49], s[94:95] offset:256
	ds_read_b128 v[176:179], v136 offset:384
	ds_read_b128 v[180:183], v136 offset:4480
	s_waitcnt lgkmcnt(2)
	v_sub_f32_e32 v42, v42, v192
	v_mul_f32_e32 v42, v42, v193
	v_fma_f32 v42, v184, v42, v188
	v_sub_f32_e32 v43, v43, v192
	v_mul_f32_e32 v43, v43, v193
	v_fma_f32 v43, v185, v43, v189
	v_sub_f32_e32 v44, v44, v192
	v_mul_f32_e32 v44, v44, v193
	v_fma_f32 v44, v186, v44, v190
	v_sub_f32_e32 v45, v45, v192
	v_mul_f32_e32 v45, v45, v193
	v_fma_f32 v45, v187, v45, v191
	global_store_dwordx4 v137, v[42:45], s[94:95] offset:320
	ds_read_b128 v[184:187], v136 offset:448
	ds_read_b128 v[188:191], v136 offset:4544
	s_waitcnt lgkmcnt(2)
	v_sub_f32_e32 v38, v38, v192
	v_mul_f32_e32 v38, v38, v193
	v_fma_f32 v38, v176, v38, v180
	v_sub_f32_e32 v39, v39, v192
	v_mul_f32_e32 v39, v39, v193
	v_fma_f32 v39, v177, v39, v181
	v_sub_f32_e32 v40, v40, v192
	v_mul_f32_e32 v40, v40, v193
	v_fma_f32 v40, v178, v40, v182
	v_sub_f32_e32 v41, v41, v192
	v_mul_f32_e32 v41, v41, v193
	v_fma_f32 v41, v179, v41, v183
	global_store_dwordx4 v137, v[38:41], s[94:95] offset:384
	s_waitcnt lgkmcnt(0)
	v_sub_f32_e32 v2, v2, v192
	v_mul_f32_e32 v2, v2, v193
	v_fma_f32 v2, v184, v2, v188
	v_sub_f32_e32 v3, v3, v192
	v_mul_f32_e32 v3, v3, v193
	v_fma_f32 v3, v185, v3, v189
	v_sub_f32_e32 v4, v4, v192
	v_mul_f32_e32 v4, v4, v193
	v_fma_f32 v4, v186, v4, v190
	v_sub_f32_e32 v5, v5, v192
	v_mul_f32_e32 v5, v5, v193
	v_fma_f32 v5, v187, v5, v191
	global_store_dwordx4 v137, v[2:5], s[94:95] offset:448
;     ...
;     auto issue_one = [&](int kt, int b, int i) {
;         const int row = lrow + 128 * i;
;         if ((NCH % 512 == 0) || (i < NCH / 512) || row < ROWS) {
;             const int kq = (kt + koff) & (KT - 1);
;             const char* ua = (const char*)A + (size_t)((DBG & 1) ? 0 : kq) * (BM * 64);
;             const char* ub = (const char*)Bt + (size_t)((DBG & 2) ? 0 : kq) * ((size_t)ldbk * 2);
;             const char* src;
;             if (BM % 128 == 0) src = (i < BM / 128) ? (ua + i * 8192 + loff) : (ub + (i * 128 - BM) * 64 + loff);
;             else if (i == 0) src = (lrow < BM) ? (ua + loff) : (ub + loff - BM * 64);
;             else src = ub + (i * 128 - BM) * 64 + loff;
;             __builtin_amdgcn_global_load_lds((const unsigned*)src, (unsigned*)(lds + b * BUF + i * 8192 + tid * 16), 16, 0, 0);
;         }
;     };
;     auto issue = [&](int kt, int b) {
; #pragma unroll
;         for (int i = 0; i < NIT; ++i) issue_one(kt, b, i);
;     };
;     ...
;     __syncthreads();
; #pragma unroll
;     for (int d = 0; d < D; ++d) issue(d, d);
.Le1_done:
	s_andn2_b64 vcc, exec, s[28:29]
	s_cbranch_vccnz .LBB0_85
.LBB0_376:
	v_mov_b32_e32 v136, v212
	v_mov_b32_e32 v2, v212
	s_ashr_i32 s49, s48, 31
	s_lshl_b64 s[8:9], s[48:49], 17
	v_lshrrev_b32_e32 v0, 4, v2
	v_sub_u32_e32 v0, 0, v0
	s_add_u32 s8, s54, s8
	v_ashrrev_i32_e32 v3, 2, v2
	v_xor_b32_e32 v0, v2, v0
	s_addc_u32 s9, s55, s9
	v_lshlrev_b32_e32 v4, 6, v3
	v_lshlrev_b32_e32 v0, 4, v0
	v_readlane_b32 s28, v244, 52
	v_and_or_b32 v0, v0, 48, v4
	s_add_u32 s28, s8, s28
	v_lshlrev_b32_e32 v137, 4, v2
	s_addc_u32 s29, s9, 0
	v_lshl_add_u64 v[6:7], s[20:21], 0, v[0:1]
	v_add_u32_e32 v138, 0, v137
	v_lshl_add_u64 v[4:5], s[28:29], 0, v[0:1]
	v_lshl_add_u64 v[6:7], v[6:7], 0, s[4:5]
	v_cmp_gt_i32_e32 vcc, 64, v3
	v_add_u32_e32 v3, 0x2000, v138
	v_readfirstlane_b32 s28, v138
	v_cndmask_b32_e32 v5, v7, v5, vcc
	v_cndmask_b32_e32 v4, v6, v4, vcc
	s_mov_b32 m0, s28
	v_readfirstlane_b32 s28, v3
	s_barrier
	global_load_lds_dwordx4 v[4:5], off
	s_mov_b32 m0, s28
	v_readlane_b32 s28, v243, 40
	v_add_u32_e32 v6, 0x4000, v138
	v_readlane_b32 s29, v243, 41
	v_add_u32_e32 v7, 0x6000, v138
	v_add_u32_e32 v8, 0x8000, v138
	v_add_u32_e32 v9, 0xa000, v138
	v_add_u32_e32 v10, 0xc000, v138
	v_add_u32_e32 v11, 0xe000, v138
	global_load_lds_dwordx4 v0, s[28:29]
	v_readfirstlane_b32 s28, v6
	s_mov_b32 m0, s28
	v_readlane_b32 s28, v243, 42
	v_readlane_b32 s29, v243, 43
	s_nop 4
	global_load_lds_dwordx4 v0, s[28:29]
	v_readfirstlane_b32 s28, v7
	s_mov_b32 m0, s28
	v_readlane_b32 s28, v243, 44
	v_readlane_b32 s29, v243, 45
	s_nop 4
	global_load_lds_dwordx4 v0, s[28:29]
	v_readfirstlane_b32 s28, v8
	s_mov_b32 m0, s28
	v_readlane_b32 s28, v243, 46
	v_readlane_b32 s29, v243, 47
	s_nop 4
	global_load_lds_dwordx4 v0, s[28:29]
	v_readfirstlane_b32 s28, v9
	s_mov_b32 m0, s28
	v_readlane_b32 s28, v243, 48
	v_readlane_b32 s29, v243, 49
	s_nop 4
	global_load_lds_dwordx4 v0, s[28:29]
	v_readfirstlane_b32 s28, v10
	s_mov_b32 m0, s28
	v_readlane_b32 s28, v243, 50
	v_readlane_b32 s29, v243, 51
	s_nop 4
	global_load_lds_dwordx4 v0, s[28:29]
	v_readfirstlane_b32 s28, v11
	s_mov_b32 m0, s28
	v_readlane_b32 s28, v243, 52
	v_readlane_b32 s29, v243, 53
	s_nop 4
	global_load_lds_dwordx4 v0, s[28:29]
	s_and_saveexec_b64 s[28:29], vcc
	s_cbranch_execz .LBB0_378
	s_add_i32 s40, 0, 0x10000
	v_readlane_b32 s46, v243, 54
	v_add_u32_e32 v3, s40, v137
	v_readlane_b32 s47, v243, 55
	v_readfirstlane_b32 s40, v3
	s_mov_b32 m0, s40
	v_lshl_add_u64 v[4:5], s[46:47], 0, v[0:1]
	global_load_lds_dwordx4 v[4:5], off

;     ...
;         for (int mt = 0; mt < MT; ++mt) af[mt] = *(const bf16x8*)(base + (wr * WM + mt * 16 + l15) * 64 + rsw);
;         constexpr int TOT = MT * NT, PER = (TOT + NIT - 1) / NIT;
; #pragma unroll
;         for (int part = 0; part < NIT; ++part) {
; #pragma unroll
;             for (int q = 0; q < PER; ++q) {
;                 const int idx = part * PER + q;
;                 if (idx < TOT) {
;                     const int mt = idx / NT, nt = idx % NT;
;                     acc[mt][nt] = SWAP ? mfma16(bfr[nt], af[mt], acc[mt][nt]) : mfma16(af[mt], bfr[nt], acc[mt][nt]);
;                 }
;             }
;             __builtin_amdgcn_sched_barrier(0);
;             if (do_issue) issue_one(ikt, ib, part);
;             __builtin_amdgcn_sched_barrier(0);
;         }
; DI void unit_O(const Params& p, char* lds, int l, int tile, int glu_tiles, int tile_b) {
;     ...
;     const int xrot = (int)(((blockIdx.x >> 3) + (blockIdx.x & 7) * 4) & 31) * 4;
;     const bf16_t* xbres = WS_PTR(const bf16_t, OFF_XB1) + ((size_t)((tile >> 1) * 32) * 128 + (tile & 1) * 64) * 32;
;     auto issue_x = [&](int half) {
;         if (l == 0) {
; #pragma unroll 1
;             for (int i = 0; i < 16; ++i) {
;                 const int pc = (wid * 16 + i + xrot) & 127, row = pc >> 2, phys = (pc & 3) * 64 + lane, logical = phys ^ (row & 15);
;                 __builtin_amdgcn_global_load_lds((const unsigned*)(xres + (r0 + half * 32 + row) * 1024 + logical * 4), (unsigned*)(XR + pc * 1024 + lane * 16), 16, 0, 0);
;             }
;         } else {
; #pragma unroll 1
;             for (int i = 0; i < 8; ++i) {
;                 const int pc = (wid * 8 + i + (xrot >> 1)) & 63, kt = pc >> 1, sub = pc & 1;
;                 __builtin_amdgcn_global_load_lds((const unsigned*)(xbres + ((size_t)kt * 128 + half * 32) * 32 + sub * 512 + lane * 8), (unsigned*)(XR + pc * 1024 + lane * 16), 16, 0, 0);
;             }
;         }
;     };
;     issue_x(0);
;     {
;         const float* gsrc = (tid < 256) ? (p.ln_g + l * 1024 + tid * 4) : (p.ln_b + l * 1024 + (tid - 256) * 4);
;         *(f32x4*)(GB + tid * 4) = *(const f32x4*)gsrc;
;     }
;     float* xo = (l == 0) ? WS_PTR(float, OFF_X1) : p.out;
;     bf16_t* xbo = WS_PTR(bf16_t, OFF_XB1);
; #pragma unroll
;     for (int half = 0; half < 2; ++half) {
;         if (half == 0) wait_vm<0>();
;         else wait_vm<8>();
;         __syncthreads();
.Lpo2_join:
.LBB0_382:
	s_waitcnt vmcnt(0)
	v_add_u32_e32 v0, 0x11000, v140
	s_barrier
	v_add_u32_e32 v134, v0, v141
	v_add_u32_e32 v0, v0, v139
	ds_read_b128 v[130:133], v134 offset:4096
	ds_read_b128 v[138:141], v0
	ds_read_b128 v[142:145], v134 offset:5120
	ds_read_b128 v[146:149], v0 offset:1024
	ds_read_b128 v[150:153], v134 offset:6144
	ds_read_b128 v[154:157], v134 offset:7168
	ds_read_b128 v[158:161], v134 offset:8192
	ds_read_b128 v[162:165], v134 offset:9216
	ds_read_b128 v[166:169], v134 offset:10240
	ds_read_b128 v[170:173], v134 offset:11264
	ds_read_b128 v[174:177], v0 offset:2048
	ds_read_b128 v[178:181], v0 offset:3072
	s_waitcnt lgkmcnt(0)
	v_mfma_f32_16x16x32_bf16 v[98:101], v[130:133], v[138:141], v[98:101]
	v_and_b32_e32 v197, 63, v136
	v_ashrrev_i32_e32 v236, 6, v136
	v_mfma_f32_16x16x32_bf16 v[94:97], v[142:145], v[138:141], v[94:97]
	v_mfma_f32_16x16x32_bf16 v[90:93], v[150:153], v[138:141], v[90:93]
	v_mfma_f32_16x16x32_bf16 v[86:89], v[154:157], v[138:141], v[86:89]
	v_mfma_f32_16x16x32_bf16 v[82:85], v[158:161], v[138:141], v[82:85]
	v_mfma_f32_16x16x32_bf16 v[78:81], v[162:165], v[138:141], v[78:81]
	v_mfma_f32_16x16x32_bf16 v[74:77], v[166:169], v[138:141], v[74:77]
	v_mfma_f32_16x16x32_bf16 v[70:73], v[170:173], v[138:141], v[70:73]
	v_mfma_f32_16x16x32_bf16 v[126:129], v[130:133], v[146:149], v[126:129]
	v_mfma_f32_16x16x32_bf16 v[122:125], v[142:145], v[146:149], v[122:125]
	v_mfma_f32_16x16x32_bf16 v[118:121], v[150:153], v[146:149], v[118:121]
	v_mfma_f32_16x16x32_bf16 v[114:117], v[154:157], v[146:149], v[114:117]
	v_mfma_f32_16x16x32_bf16 v[110:113], v[158:161], v[146:149], v[110:113]
	v_mfma_f32_16x16x32_bf16 v[106:109], v[162:165], v[146:149], v[106:109]
	v_mfma_f32_16x16x32_bf16 v[102:105], v[166:169], v[146:149], v[102:105]
	v_mfma_f32_16x16x32_bf16 v[66:69], v[170:173], v[146:149], v[66:69]
	v_mfma_f32_16x16x32_bf16 v[34:37], v[130:133], v[174:177], v[34:37]
	v_mfma_f32_16x16x32_bf16 v[30:33], v[142:145], v[174:177], v[30:33]
	v_mfma_f32_16x16x32_bf16 v[26:29], v[150:153], v[174:177], v[26:29]
	v_mfma_f32_16x16x32_bf16 v[22:25], v[154:157], v[174:177], v[22:25]
	v_mfma_f32_16x16x32_bf16 v[18:21], v[158:161], v[174:177], v[18:21]
	v_mfma_f32_16x16x32_bf16 v[14:17], v[162:165], v[174:177], v[14:17]
	v_mfma_f32_16x16x32_bf16 v[10:13], v[166:169], v[174:177], v[10:13]
	v_mfma_f32_16x16x32_bf16 v[6:9], v[170:173], v[174:177], v[6:9]
	v_mfma_f32_16x16x32_bf16 v[62:65], v[130:133], v[178:181], v[62:65]
	v_mfma_f32_16x16x32_bf16 v[58:61], v[142:145], v[178:181], v[58:61]
	v_mfma_f32_16x16x32_bf16 v[54:57], v[150:153], v[178:181], v[54:57]
	v_mfma_f32_16x16x32_bf16 v[50:53], v[154:157], v[178:181], v[50:53]
	v_mfma_f32_16x16x32_bf16 v[46:49], v[158:161], v[178:181], v[46:49]
	v_mfma_f32_16x16x32_bf16 v[42:45], v[162:165], v[178:181], v[42:45]
	v_mfma_f32_16x16x32_bf16 v[38:41], v[166:169], v[178:181], v[38:41]
	v_mfma_f32_16x16x32_bf16 v[2:5], v[170:173], v[178:181], v[2:5]
	s_barrier
	s_not_b64 s[6:7], s[10:11]
	v_and_b32_e32 v138, 15, v212
	v_bfe_u32 v139, v212, 4, 2
	v_lshrrev_b32_e32 v140, 6, v212
	v_and_b32_e32 v141, 63, v212
	v_readfirstlane_b32 s90, v140
	v_and_b32_e32 v142, 0xff, v212
	v_lshlrev_b32_e32 v142, 4, v142
	s_cmp_lt_u32 s90, 4
	s_cselect_b32 s92, s14, s12
	s_cselect_b32 s93, s15, s13
	s_nop 3
	global_load_dwordx4 v[176:179], v142, s[92:93]
	v_lshlrev_b32_e32 v143, 4, v212
	v_add_u32_e32 v143, 0x20000, v143
	v_lshlrev_b32_e32 v134, 6, v138
	v_add_u32_e32 v135, 0x22000, v134
	v_lshl_add_u32 v134, v140, 3, v135
	v_lshlrev_b32_e32 v136, 9, v140
	v_lshl_add_u32 v136, v139, 4, v136
	v_add_u32_e32 v136, 0x20000, v136
	s_cmp_lg_u64 s[10:11], 0
	s_cbranch_scc1 .Le2_l1
	s_lshl_b32 s40, s48, 18
	s_lshl_b32 s91, s90, 13
	s_add_u32 s96, s52, s40
	s_addc_u32 s97, s53, 0
	s_add_u32 s96, s96, s91
	s_addc_u32 s97, s97, 0
	s_lshl_b32 s40, s90, 1
	v_xor_b32_e32 v131, s40, v141
	v_lshlrev_b32_e32 v131, 4, v131
	s_add_u32 s40, s40, 1
	v_xor_b32_e32 v132, s40, v141
	v_lshlrev_b32_e32 v132, 4, v132
	v_lshlrev_b32_e32 v133, 12, v138
	v_lshl_add_u32 v133, v140, 9, v133
	v_add_u32_e32 v200, 0, v139
	v_xor_b32_e32 v200, v200, v138
	v_lshl_add_u32 v200, v200, 4, v133
	v_add_u32_e32 v204, 0x10000, v200
	v_add_u32_e32 v201, 4, v139
	v_xor_b32_e32 v201, v201, v138
	v_lshl_add_u32 v201, v201, 4, v133
	v_add_u32_e32 v205, 0x10000, v201
	v_add_u32_e32 v202, 8, v139
	v_xor_b32_e32 v202, v202, v138
	v_lshl_add_u32 v202, v202, 4, v133
	v_add_u32_e32 v206, 0x10000, v202
	v_add_u32_e32 v203, 12, v139
	v_xor_b32_e32 v203, v203, v138
	v_lshl_add_u32 v203, v203, 4, v133
	v_add_u32_e32 v207, 0x10000, v203
	v_and_b32_e32 v137, 1, v139
	v_lshlrev_b32_e32 v137, 5, v137
	v_lshrrev_b32_e32 v130, 1, v139
	v_lshl_or_b32 v137, v130, 4, v137
	v_lshl_or_b32 v137, v138, 6, v137
	v_lshl_or_b32 v137, v140, 15, v137
	s_lshr_b32 s40, s48, 1
	s_lshl_b32 s40, s40, 18
	s_and_b32 s46, s48, 1
	s_lshl_b32 s46, s46, 12
	s_add_u32 s40, s40, s46
	s_add_u32 s78, s56, s40
	s_addc_u32 s79, s57, 0
	s_add_u32 s92, s96, 0x0
	s_addc_u32 s93, s97, 0
	s_add_u32 s40, s91, 0x0
	s_mov_b32 m0, s40
	s_nop 0
	global_load_lds_dwordx4 v131, s[92:93]
	global_load_lds_dwordx4 v131, s[92:93] offset:1024
	global_load_lds_dwordx4 v131, s[92:93] offset:2048
	global_load_lds_dwordx4 v131, s[92:93] offset:3072
	s_add_u32 s92, s96, 0x1000
	s_addc_u32 s93, s97, 0
	s_add_u32 s40, s91, 0x1000
	s_mov_b32 m0, s40
	s_nop 0
	global_load_lds_dwordx4 v132, s[92:93]
	global_load_lds_dwordx4 v132, s[92:93] offset:1024
	global_load_lds_dwordx4 v132, s[92:93] offset:2048
	global_load_lds_dwordx4 v132, s[92:93] offset:3072
	s_add_u32 s92, s96, 0x10000
	s_addc_u32 s93, s97, 0
	s_add_u32 s40, s91, 0x10000
	s_mov_b32 m0, s40
	s_nop 0
	global_load_lds_dwordx4 v131, s[92:93]
	global_load_lds_dwordx4 v131, s[92:93] offset:1024
	global_load_lds_dwordx4 v131, s[92:93] offset:2048
	global_load_lds_dwordx4 v131, s[92:93] offset:3072
	s_add_u32 s92, s96, 0x11000
	s_addc_u32 s93, s97, 0
	s_add_u32 s40, s91, 0x11000
	s_mov_b32 m0, s40
	s_nop 0
	global_load_lds_dwordx4 v132, s[92:93]
	global_load_lds_dwordx4 v132, s[92:93] offset:1024
	global_load_lds_dwordx4 v132, s[92:93] offset:2048
	global_load_lds_dwordx4 v132, s[92:93] offset:3072
	s_waitcnt vmcnt(16)
	ds_write_b128 v143, v[176:179]
	s_waitcnt vmcnt(8) lgkmcnt(0)
	s_barrier
; DI float bf2f(unsigned b) { return __uint_as_float(b << 16); }
; DI void unit_O(const Params& p, char* lds, int l, int tile, int glu_tiles, int tile_b) {
;     ...
;         float s2[2], ss2[2];
; #pragma unroll
;         for (int mh = 0; mh < 2; ++mh) {
;             const int mt = half * 2 + mh, rl = mh * 16 + l15;
;             float s = 0.f, ss = 0.f;
; #pragma unroll
;             for (int nt = 0; nt < 8; ++nt) {
;                 f32x4 xr;
;                 if (l == 0) {
;                     const int chunk = wid * 32 + nt * 4 + quad;
;                     xr = *(const f32x4*)(XR + rl * 4096 + ((chunk ^ l15) << 4));
;                 } else {
;                     const u32x2 hb = *(const u32x2*)(XR + ((wid * 4 + (nt >> 1)) * 32 + rl) * 64 + (nt & 1) * 32 + quad * 8);
;                     xr = (f32x4){bf2f(hb[0] & 0xffffu), bf2f(hb[0] >> 16), bf2f(hb[1] & 0xffffu), bf2f(hb[1] >> 16)};
;                 }
; #pragma unroll
;                 for (int i = 0; i < 4; ++i) { const float v = acc[mt][nt][i] + DN_ALPHA * xr[i]; acc[mt][nt][i] = v; s += v; ss += v * v; }
;             }
;             s2[mh] = s; ss2[mh] = ss;
;         }
; #pragma unroll
;         for (int mh = 0; mh < 2; ++mh) { s2[mh] += __shfl_xor(s2[mh], 16); ss2[mh] += __shfl_xor(ss2[mh], 16); }
; #pragma unroll
;         for (int mh = 0; mh < 2; ++mh) { s2[mh] += __shfl_xor(s2[mh], 32); ss2[mh] += __shfl_xor(ss2[mh], 32); }
;         if (quad == 0) {
; #pragma unroll
;             for (int mh = 0; mh < 2; ++mh) *(f32x2*)&red[((mh * 16 + l15) * 8 + wid) * 2] = (f32x2){s2[mh], ss2[mh]};
;         }
;         __syncthreads();
;         if (half == 0) issue_x(1);
; #pragma unroll
;         for (int mh = 0; mh < 2; ++mh) {
;             const int mt = half * 2 + mh, rl = mh * 16 + l15, row = mt * 16 + l15;
;             float s = 0.f, ss = 0.f;
; #pragma unroll
;             for (int w = 0; w < 4; ++w) { const f32x4 v = *(const f32x4*)&red[rl * 16 + 4 * w]; s += v[0] + v[2]; ss += v[1] + v[3]; }
;             const float mu = s * (1.f / 1024.f);
;             const float var = ss * (1.f / 1024.f) - mu * mu;
;             const float rs = rsqrtf(var + LN_EPS);
;             float* orow = xo + (r0 + row) * 1024 + wid * 128 + quad * 4;
	ds_read_b128 v[144:147], v200
	ds_read_b128 v[148:151], v201
	ds_read_b128 v[152:155], v202
	ds_read_b128 v[156:159], v203
	ds_read_b128 v[160:163], v200 offset:256
	ds_read_b128 v[164:167], v201 offset:256
	ds_read_b128 v[168:171], v202 offset:256
	ds_read_b128 v[172:175], v203 offset:256
	s_waitcnt lgkmcnt(7)
	v_fmac_f32_e32 v98, s58, v144
	v_fmac_f32_e32 v99, s58, v145
	v_fmac_f32_e32 v100, s58, v146
	v_fmac_f32_e32 v101, s58, v147
	v_mov_b32_e32 v196, v98
	v_mul_f32_e32 v197, v98, v98
	v_mov_b32_e32 v130, v99
	v_mul_f32_e32 v142, v99, v99
	v_add_f32_e32 v196, v196, v100
	v_fmac_f32_e32 v197, v100, v100
	v_add_f32_e32 v130, v130, v101
	v_fmac_f32_e32 v142, v101, v101
	s_waitcnt lgkmcnt(6)
	v_fmac_f32_e32 v94, s58, v148
	v_fmac_f32_e32 v95, s58, v149
	v_fmac_f32_e32 v96, s58, v150
	v_fmac_f32_e32 v97, s58, v151
	v_add_f32_e32 v196, v196, v94
	v_fmac_f32_e32 v197, v94, v94
	v_add_f32_e32 v130, v130, v95
	v_fmac_f32_e32 v142, v95, v95
	v_add_f32_e32 v196, v196, v96
	v_fmac_f32_e32 v197, v96, v96
	v_add_f32_e32 v130, v130, v97
	v_fmac_f32_e32 v142, v97, v97
	s_waitcnt lgkmcnt(5)
	v_fmac_f32_e32 v90, s58, v152
	v_fmac_f32_e32 v91, s58, v153
	v_fmac_f32_e32 v92, s58, v154
	v_fmac_f32_e32 v93, s58, v155
	v_add_f32_e32 v196, v196, v90
	v_fmac_f32_e32 v197, v90, v90
	v_add_f32_e32 v130, v130, v91
	v_fmac_f32_e32 v142, v91, v91
	v_add_f32_e32 v196, v196, v92
	v_fmac_f32_e32 v197, v92, v92
	v_add_f32_e32 v130, v130, v93
	v_fmac_f32_e32 v142, v93, v93
	s_waitcnt lgkmcnt(4)
	v_fmac_f32_e32 v86, s58, v156
	v_fmac_f32_e32 v87, s58, v157
	v_fmac_f32_e32 v88, s58, v158
	v_fmac_f32_e32 v89, s58, v159
	v_add_f32_e32 v196, v196, v86
	v_fmac_f32_e32 v197, v86, v86
	v_add_f32_e32 v130, v130, v87
	v_fmac_f32_e32 v142, v87, v87
	v_add_f32_e32 v196, v196, v88
	v_fmac_f32_e32 v197, v88, v88
	v_add_f32_e32 v130, v130, v89
	v_fmac_f32_e32 v142, v89, v89
	s_waitcnt lgkmcnt(3)
	v_fmac_f32_e32 v82, s58, v160
	v_fmac_f32_e32 v83, s58, v161
	v_fmac_f32_e32 v84, s58, v162
	v_fmac_f32_e32 v85, s58, v163
	v_add_f32_e32 v196, v196, v82
	v_fmac_f32_e32 v197, v82, v82
	v_add_f32_e32 v130, v130, v83
	v_fmac_f32_e32 v142, v83, v83
	v_add_f32_e32 v196, v196, v84
	v_fmac_f32_e32 v197, v84, v84
	v_add_f32_e32 v130, v130, v85
	v_fmac_f32_e32 v142, v85, v85
	s_waitcnt lgkmcnt(2)
	v_fmac_f32_e32 v78, s58, v164
	v_fmac_f32_e32 v79, s58, v165
	v_fmac_f32_e32 v80, s58, v166
	v_fmac_f32_e32 v81, s58, v167
	v_add_f32_e32 v196, v196, v78
	v_fmac_f32_e32 v197, v78, v78
	v_add_f32_e32 v130, v130, v79
	v_fmac_f32_e32 v142, v79, v79
	v_add_f32_e32 v196, v196, v80
	v_fmac_f32_e32 v197, v80, v80
	v_add_f32_e32 v130, v130, v81
	v_fmac_f32_e32 v142, v81, v81
	s_waitcnt lgkmcnt(1)
	v_fmac_f32_e32 v74, s58, v168
	v_fmac_f32_e32 v75, s58, v169
	v_fmac_f32_e32 v76, s58, v170
	v_fmac_f32_e32 v77, s58, v171
	v_add_f32_e32 v196, v196, v74
	v_fmac_f32_e32 v197, v74, v74
	v_add_f32_e32 v130, v130, v75
	v_fmac_f32_e32 v142, v75, v75
	v_add_f32_e32 v196, v196, v76
	v_fmac_f32_e32 v197, v76, v76
	v_add_f32_e32 v130, v130, v77
	v_fmac_f32_e32 v142, v77, v77
	s_waitcnt lgkmcnt(0)
	v_fmac_f32_e32 v70, s58, v172
	v_fmac_f32_e32 v71, s58, v173
	v_fmac_f32_e32 v72, s58, v174
	v_fmac_f32_e32 v73, s58, v175
	v_add_f32_e32 v196, v196, v70
	v_fmac_f32_e32 v197, v70, v70
	v_add_f32_e32 v130, v130, v71
	v_fmac_f32_e32 v142, v71, v71
	v_add_f32_e32 v196, v196, v72
	v_fmac_f32_e32 v197, v72, v72
	v_add_f32_e32 v130, v130, v73
	v_fmac_f32_e32 v142, v73, v73
	v_add_f32_e32 v196, v196, v130
	v_add_f32_e32 v197, v197, v142
	v_mov_b32_e32 v198, v196
	v_mov_b32_e32 v199, v197
	s_nop 1
	v_permlane16_swap_b32 v198, v196
	v_permlane16_swap_b32 v199, v197
	v_add_f32_e32 v196, v196, v198
	v_add_f32_e32 v197, v197, v199
	v_mov_b32_e32 v198, v196
	v_mov_b32_e32 v199, v197
	s_nop 1
	v_permlane32_swap_b32 v198, v196
	v_permlane32_swap_b32 v199, v197
	v_add_f32_e32 v196, v196, v198
	v_add_f32_e32 v197, v197, v199
	s_mov_b64 exec, 0xffff
	ds_write_b64 v134, v[196:197]
	s_mov_b64 exec, -1
	s_waitcnt lgkmcnt(0)
	s_barrier
	s_add_u32 s92, s96, 0x20000
	s_addc_u32 s93, s97, 0
	s_add_u32 s40, s91, 0x0
	s_mov_b32 m0, s40
	s_nop 0
	global_load_lds_dwordx4 v131, s[92:93]
	global_load_lds_dwordx4 v131, s[92:93] offset:1024
	global_load_lds_dwordx4 v131, s[92:93] offset:2048
	global_load_lds_dwordx4 v131, s[92:93] offset:3072
	s_add_u32 s92, s96, 0x21000
	s_addc_u32 s93, s97, 0
	s_add_u32 s40, s91, 0x1000
	s_mov_b32 m0, s40
	s_nop 0
	global_load_lds_dwordx4 v132, s[92:93]
	global_load_lds_dwordx4 v132, s[92:93] offset:1024
	global_load_lds_dwordx4 v132, s[92:93] offset:2048
	global_load_lds_dwordx4 v132, s[92:93] offset:3072
	ds_read_b128 v[160:163], v135 offset:0
	ds_read_b128 v[164:167], v135 offset:16
	ds_read_b128 v[168:171], v135 offset:32
	ds_read_b128 v[172:175], v135 offset:48
	s_waitcnt lgkmcnt(0)
	v_add_f32_e32 v160, v160, v162
	v_add_f32_e32 v161, v161, v163
	v_add_f32_e32 v164, v164, v166
	v_add_f32_e32 v165, v165, v167
	v_add_f32_e32 v168, v168, v170
	v_add_f32_e32 v169, v169, v171
	v_add_f32_e32 v172, v172, v174
	v_add_f32_e32 v173, v173, v175
	v_add_f32_e32 v160, v160, v164
	v_add_f32_e32 v161, v161, v165
	v_add_f32_e32 v168, v168, v172
	v_add_f32_e32 v169, v169, v173
	v_add_f32_e32 v160, v160, v168
	v_add_f32_e32 v161, v161, v169
	v_mul_f32_e32 v192, 0x3a800000, v160
	v_mul_f32_e32 v193, 0x3a800000, v161
	v_fma_f32 v193, -v192, v192, v193
	v_add_f32_e32 v193, 0x3727c5ac, v193
	v_rsq_f32_e32 v193, v193
	s_nop 0
	s_add_u32 s94, s78, 0x0
	s_addc_u32 s95, s79, 0
	ds_read_b128 v[176:179], v136
	ds_read_b128 v[180:183], v136 offset:4096
	ds_read_b128 v[184:187], v136 offset:64
	ds_read_b128 v[188:191], v136 offset:4160
	s_waitcnt lgkmcnt(2)
; DI unsigned pk2(float lo, float hi) { const f32x2 v = {lo, hi}; const bf16x2_t b = __builtin_convertvector(v, bf16x2_t); return __builtin_bit_cast(unsigned, b); }
; DI size_t xb_off(int tok, int col) { return ((size_t)(((tok >> 7) * 32 + (col >> 5)) * 128 + (tok & 127))) * 32 + (col & 31); }
; DI void unit_O(const Params& p, char* lds, int l, int tile, int glu_tiles, int tile_b) {
;     ...
;             float* orow = xo + (r0 + row) * 1024 + wid * 128 + quad * 4;
;             bf16_t* brow = xbo + xb_off((int)r0 + row, wid * 128) + quad * 4;
;             const float* gp = GB + wid * 128 + quad * 4;
; #pragma unroll
;             for (int nt = 0; nt < 8; ++nt) {
;                 const f32x4 g = *(const f32x4*)(gp + nt * 16), bb = *(const f32x4*)(gp + 1024 + nt * 16);
;                 f32x4 o;
; #pragma unroll
;                 for (int i = 0; i < 4; ++i) o[i] = (acc[mt][nt][i] - mu) * rs * g[i] + bb[i];
;                 if (l == 0) *(u32x2*)(brow + (nt >> 1) * 4096 + (nt & 1) * 16) = (u32x2){pk2(o[0], o[1]), pk2(o[2], o[3])};
;                 else *(f32x4*)(orow + nt * 16) = o;
	v_sub_f32_e32 v98, v98, v192
	v_mul_f32_e32 v98, v98, v193
	v_fma_f32 v98, v176, v98, v180
	v_sub_f32_e32 v99, v99, v192
	v_mul_f32_e32 v99, v99, v193
	v_fma_f32 v99, v177, v99, v181
	v_sub_f32_e32 v100, v100, v192
	v_mul_f32_e32 v100, v100, v193
	v_fma_f32 v100, v178, v100, v182
	v_sub_f32_e32 v101, v101, v192
	v_mul_f32_e32 v101, v101, v193
	v_fma_f32 v101, v179, v101, v183
	v_cvt_pk_bf16_f32 v144, v98, v99
	v_cvt_pk_bf16_f32 v145, v100, v101
	ds_read_b128 v[176:179], v136 offset:128
	ds_read_b128 v[180:183], v136 offset:4224
	s_waitcnt lgkmcnt(2)
	v_sub_f32_e32 v94, v94, v192
	v_mul_f32_e32 v94, v94, v193
	v_fma_f32 v94, v184, v94, v188
	v_sub_f32_e32 v95, v95, v192
	v_mul_f32_e32 v95, v95, v193
	v_fma_f32 v95, v185, v95, v189
	v_sub_f32_e32 v96, v96, v192
	v_mul_f32_e32 v96, v96, v193
	v_fma_f32 v96, v186, v96, v190
	v_sub_f32_e32 v97, v97, v192
	v_mul_f32_e32 v97, v97, v193
	v_fma_f32 v97, v187, v97, v191
	v_cvt_pk_bf16_f32 v146, v94, v95
	v_cvt_pk_bf16_f32 v147, v96, v97
	s_nop 1
	v_permlane16_swap_b32 v144, v146
	v_permlane16_swap_b32 v145, v147
	global_store_dwordx4 v137, v[144:147], s[94:95]
	s_add_u32 s94, s94, 0x2000
	s_addc_u32 s95, s95, 0
	ds_read_b128 v[184:187], v136 offset:192
	ds_read_b128 v[188:191], v136 offset:4288
	s_waitcnt lgkmcnt(2)
	v_sub_f32_e32 v90, v90, v192
	v_mul_f32_e32 v90, v90, v193
	v_fma_f32 v90, v176, v90, v180
	v_sub_f32_e32 v91, v91, v192
	v_mul_f32_e32 v91, v91, v193
	v_fma_f32 v91, v177, v91, v181
	v_sub_f32_e32 v92, v92, v192
	v_mul_f32_e32 v92, v92, v193
	v_fma_f32 v92, v178, v92, v182
	v_sub_f32_e32 v93, v93, v192
	v_mul_f32_e32 v93, v93, v193
	v_fma_f32 v93, v179, v93, v183
	v_cvt_pk_bf16_f32 v152, v90, v91
	v_cvt_pk_bf16_f32 v153, v92, v93
	ds_read_b128 v[176:179], v136 offset:256
	ds_read_b128 v[180:183], v136 offset:4352
	s_waitcnt lgkmcnt(2)
	v_sub_f32_e32 v86, v86, v192
	v_mul_f32_e32 v86, v86, v193
	v_fma_f32 v86, v184, v86, v188
	v_sub_f32_e32 v87, v87, v192
	v_mul_f32_e32 v87, v87, v193
	v_fma_f32 v87, v185, v87, v189
	v_sub_f32_e32 v88, v88, v192
	v_mul_f32_e32 v88, v88, v193
	v_fma_f32 v88, v186, v88, v190
	v_sub_f32_e32 v89, v89, v192
	v_mul_f32_e32 v89, v89, v193
	v_fma_f32 v89, v187, v89, v191
	v_cvt_pk_bf16_f32 v154, v86, v87
	v_cvt_pk_bf16_f32 v155, v88, v89
	s_nop 1
	v_permlane16_swap_b32 v152, v154
	v_permlane16_swap_b32 v153, v155
	global_store_dwordx4 v137, v[152:155], s[94:95]
	s_add_u32 s94, s94, 0x2000
	s_addc_u32 s95, s95, 0
	ds_read_b128 v[184:187], v136 offset:320
	ds_read_b128 v[188:191], v136 offset:4416
	s_waitcnt lgkmcnt(2)
	v_sub_f32_e32 v82, v82, v192
	v_mul_f32_e32 v82, v82, v193
	v_fma_f32 v82, v176, v82, v180
	v_sub_f32_e32 v83, v83, v192
	v_mul_f32_e32 v83, v83, v193
	v_fma_f32 v83, v177, v83, v181
	v_sub_f32_e32 v84, v84, v192
	v_mul_f32_e32 v84, v84, v193
	v_fma_f32 v84, v178, v84, v182
	v_sub_f32_e32 v85, v85, v192
	v_mul_f32_e32 v85, v85, v193
	v_fma_f32 v85, v179, v85, v183
	v_cvt_pk_bf16_f32 v144, v82, v83
	v_cvt_pk_bf16_f32 v145, v84, v85
	ds_read_b128 v[176:179], v136 offset:384
	ds_read_b128 v[180:183], v136 offset:4480
	s_waitcnt lgkmcnt(2)
	v_sub_f32_e32 v78, v78, v192
	v_mul_f32_e32 v78, v78, v193
	v_fma_f32 v78, v184, v78, v188
	v_sub_f32_e32 v79, v79, v192
	v_mul_f32_e32 v79, v79, v193
	v_fma_f32 v79, v185, v79, v189
	v_sub_f32_e32 v80, v80, v192
	v_mul_f32_e32 v80, v80, v193
	v_fma_f32 v80, v186, v80, v190
	v_sub_f32_e32 v81, v81, v192
	v_mul_f32_e32 v81, v81, v193
	v_fma_f32 v81, v187, v81, v191
	v_cvt_pk_bf16_f32 v146, v78, v79
	v_cvt_pk_bf16_f32 v147, v80, v81
	s_nop 1
	v_permlane16_swap_b32 v144, v146
	v_permlane16_swap_b32 v145, v147
	global_store_dwordx4 v137, v[144:147], s[94:95]
	s_add_u32 s94, s94, 0x2000
	s_addc_u32 s95, s95, 0
	ds_read_b128 v[184:187], v136 offset:448
	ds_read_b128 v[188:191], v136 offset:4544
	s_waitcnt lgkmcnt(2)
	v_sub_f32_e32 v74, v74, v192
	v_mul_f32_e32 v74, v74, v193
	v_fma_f32 v74, v176, v74, v180
	v_sub_f32_e32 v75, v75, v192
	v_mul_f32_e32 v75, v75, v193
	v_fma_f32 v75, v177, v75, v181
	v_sub_f32_e32 v76, v76, v192
	v_mul_f32_e32 v76, v76, v193
	v_fma_f32 v76, v178, v76, v182
	v_sub_f32_e32 v77, v77, v192
	v_mul_f32_e32 v77, v77, v193
	v_fma_f32 v77, v179, v77, v183
	v_cvt_pk_bf16_f32 v152, v74, v75
	v_cvt_pk_bf16_f32 v153, v76, v77
	s_waitcnt lgkmcnt(0)
	v_sub_f32_e32 v70, v70, v192
	v_mul_f32_e32 v70, v70, v193
	v_fma_f32 v70, v184, v70, v188
	v_sub_f32_e32 v71, v71, v192
	v_mul_f32_e32 v71, v71, v193
	v_fma_f32 v71, v185, v71, v189
	v_sub_f32_e32 v72, v72, v192
	v_mul_f32_e32 v72, v72, v193
	v_fma_f32 v72, v186, v72, v190
	v_sub_f32_e32 v73, v73, v192
	v_mul_f32_e32 v73, v73, v193
	v_fma_f32 v73, v187, v73, v191
	v_cvt_pk_bf16_f32 v154, v70, v71
	v_cvt_pk_bf16_f32 v155, v72, v73
	s_nop 1
	v_permlane16_swap_b32 v152, v154
	v_permlane16_swap_b32 v153, v155
	global_store_dwordx4 v137, v[152:155], s[94:95]
	s_waitcnt vmcnt(12) lgkmcnt(0)
	s_barrier
; DI float bf2f(unsigned b) { return __uint_as_float(b << 16); }
; DI void unit_O(const Params& p, char* lds, int l, int tile, int glu_tiles, int tile_b) {
;     ...
;         float s2[2], ss2[2];
; #pragma unroll
;         for (int mh = 0; mh < 2; ++mh) {
;             const int mt = half * 2 + mh, rl = mh * 16 + l15;
;             float s = 0.f, ss = 0.f;
; #pragma unroll
;             for (int nt = 0; nt < 8; ++nt) {
;                 f32x4 xr;
;                 if (l == 0) {
;                     const int chunk = wid * 32 + nt * 4 + quad;
;                     xr = *(const f32x4*)(XR + rl * 4096 + ((chunk ^ l15) << 4));
;                 } else {
;                     const u32x2 hb = *(const u32x2*)(XR + ((wid * 4 + (nt >> 1)) * 32 + rl) * 64 + (nt & 1) * 32 + quad * 8);
;                     xr = (f32x4){bf2f(hb[0] & 0xffffu), bf2f(hb[0] >> 16), bf2f(hb[1] & 0xffffu), bf2f(hb[1] >> 16)};
;                 }
; #pragma unroll
;                 for (int i = 0; i < 4; ++i) { const float v = acc[mt][nt][i] + DN_ALPHA * xr[i]; acc[mt][nt][i] = v; s += v; ss += v * v; }
;             }
;             s2[mh] = s; ss2[mh] = ss;
;         }
; #pragma unroll
;         for (int mh = 0; mh < 2; ++mh) { s2[mh] += __shfl_xor(s2[mh], 16); ss2[mh] += __shfl_xor(ss2[mh], 16); }
; #pragma unroll
;         for (int mh = 0; mh < 2; ++mh) { s2[mh] += __shfl_xor(s2[mh], 32); ss2[mh] += __shfl_xor(ss2[mh], 32); }
;         if (quad == 0) {
; #pragma unroll
;             for (int mh = 0; mh < 2; ++mh) *(f32x2*)&red[((mh * 16 + l15) * 8 + wid) * 2] = (f32x2){s2[mh], ss2[mh]};
;         }
;         __syncthreads();
;         if (half == 0) issue_x(1);
; #pragma unroll
;         for (int mh = 0; mh < 2; ++mh) {
;             const int mt = half * 2 + mh, rl = mh * 16 + l15, row = mt * 16 + l15;
;             float s = 0.f, ss = 0.f;
; #pragma unroll
;             for (int w = 0; w < 4; ++w) { const f32x4 v = *(const f32x4*)&red[rl * 16 + 4 * w]; s += v[0] + v[2]; ss += v[1] + v[3]; }
;             const float mu = s * (1.f / 1024.f);
;             const float var = ss * (1.f / 1024.f) - mu * mu;
;             const float rs = rsqrtf(var + LN_EPS);
;             float* orow = xo + (r0 + row) * 1024 + wid * 128 + quad * 4;
	ds_read_b128 v[144:147], v204
	ds_read_b128 v[148:151], v205
	ds_read_b128 v[152:155], v206
	ds_read_b128 v[156:159], v207
	ds_read_b128 v[160:163], v204 offset:256
	ds_read_b128 v[164:167], v205 offset:256
	ds_read_b128 v[168:171], v206 offset:256
	ds_read_b128 v[172:175], v207 offset:256
	s_waitcnt lgkmcnt(7)
	v_fmac_f32_e32 v126, s58, v144
	v_fmac_f32_e32 v127, s58, v145
	v_fmac_f32_e32 v128, s58, v146
	v_fmac_f32_e32 v129, s58, v147
	v_mov_b32_e32 v196, v126
	v_mul_f32_e32 v197, v126, v126
	v_mov_b32_e32 v130, v127
	v_mul_f32_e32 v142, v127, v127
	v_add_f32_e32 v196, v196, v128
	v_fmac_f32_e32 v197, v128, v128
	v_add_f32_e32 v130, v130, v129
	v_fmac_f32_e32 v142, v129, v129
	s_waitcnt lgkmcnt(6)
	v_fmac_f32_e32 v122, s58, v148
	v_fmac_f32_e32 v123, s58, v149
	v_fmac_f32_e32 v124, s58, v150
	v_fmac_f32_e32 v125, s58, v151
	v_add_f32_e32 v196, v196, v122
	v_fmac_f32_e32 v197, v122, v122
	v_add_f32_e32 v130, v130, v123
	v_fmac_f32_e32 v142, v123, v123
	v_add_f32_e32 v196, v196, v124
	v_fmac_f32_e32 v197, v124, v124
	v_add_f32_e32 v130, v130, v125
	v_fmac_f32_e32 v142, v125, v125
	s_waitcnt lgkmcnt(5)
	v_fmac_f32_e32 v118, s58, v152
	v_fmac_f32_e32 v119, s58, v153
	v_fmac_f32_e32 v120, s58, v154
	v_fmac_f32_e32 v121, s58, v155
	v_add_f32_e32 v196, v196, v118
	v_fmac_f32_e32 v197, v118, v118
	v_add_f32_e32 v130, v130, v119
	v_fmac_f32_e32 v142, v119, v119
	v_add_f32_e32 v196, v196, v120
	v_fmac_f32_e32 v197, v120, v120
	v_add_f32_e32 v130, v130, v121
	v_fmac_f32_e32 v142, v121, v121
	s_waitcnt lgkmcnt(4)
	v_fmac_f32_e32 v114, s58, v156
	v_fmac_f32_e32 v115, s58, v157
	v_fmac_f32_e32 v116, s58, v158
	v_fmac_f32_e32 v117, s58, v159
	v_add_f32_e32 v196, v196, v114
	v_fmac_f32_e32 v197, v114, v114
	v_add_f32_e32 v130, v130, v115
	v_fmac_f32_e32 v142, v115, v115
	v_add_f32_e32 v196, v196, v116
	v_fmac_f32_e32 v197, v116, v116
	v_add_f32_e32 v130, v130, v117
	v_fmac_f32_e32 v142, v117, v117
	s_waitcnt lgkmcnt(3)
	v_fmac_f32_e32 v110, s58, v160
	v_fmac_f32_e32 v111, s58, v161
	v_fmac_f32_e32 v112, s58, v162
	v_fmac_f32_e32 v113, s58, v163
	v_add_f32_e32 v196, v196, v110
	v_fmac_f32_e32 v197, v110, v110
	v_add_f32_e32 v130, v130, v111
	v_fmac_f32_e32 v142, v111, v111
	v_add_f32_e32 v196, v196, v112
	v_fmac_f32_e32 v197, v112, v112
	v_add_f32_e32 v130, v130, v113
	v_fmac_f32_e32 v142, v113, v113
	s_waitcnt lgkmcnt(2)
	v_fmac_f32_e32 v106, s58, v164
	v_fmac_f32_e32 v107, s58, v165
	v_fmac_f32_e32 v108, s58, v166
	v_fmac_f32_e32 v109, s58, v167
	v_add_f32_e32 v196, v196, v106
	v_fmac_f32_e32 v197, v106, v106
	v_add_f32_e32 v130, v130, v107
	v_fmac_f32_e32 v142, v107, v107
	v_add_f32_e32 v196, v196, v108
	v_fmac_f32_e32 v197, v108, v108
	v_add_f32_e32 v130, v130, v109
	v_fmac_f32_e32 v142, v109, v109
	s_waitcnt lgkmcnt(1)
	v_fmac_f32_e32 v102, s58, v168
	v_fmac_f32_e32 v103, s58, v169
	v_fmac_f32_e32 v104, s58, v170
	v_fmac_f32_e32 v105, s58, v171
	v_add_f32_e32 v196, v196, v102
	v_fmac_f32_e32 v197, v102, v102
	v_add_f32_e32 v130, v130, v103
	v_fmac_f32_e32 v142, v103, v103
	v_add_f32_e32 v196, v196, v104
	v_fmac_f32_e32 v197, v104, v104
	v_add_f32_e32 v130, v130, v105
	v_fmac_f32_e32 v142, v105, v105
	s_waitcnt lgkmcnt(0)
	v_fmac_f32_e32 v66, s58, v172
	v_fmac_f32_e32 v67, s58, v173
	v_fmac_f32_e32 v68, s58, v174
	v_fmac_f32_e32 v69, s58, v175
	v_add_f32_e32 v196, v196, v66
	v_fmac_f32_e32 v197, v66, v66
	v_add_f32_e32 v130, v130, v67
	v_fmac_f32_e32 v142, v67, v67
	v_add_f32_e32 v196, v196, v68
	v_fmac_f32_e32 v197, v68, v68
	v_add_f32_e32 v130, v130, v69
	v_fmac_f32_e32 v142, v69, v69
	v_add_f32_e32 v196, v196, v130
	v_add_f32_e32 v197, v197, v142
	v_mov_b32_e32 v198, v196
	v_mov_b32_e32 v199, v197
	s_nop 1
	v_permlane16_swap_b32 v198, v196
	v_permlane16_swap_b32 v199, v197
	v_add_f32_e32 v196, v196, v198
	v_add_f32_e32 v197, v197, v199
	v_mov_b32_e32 v198, v196
	v_mov_b32_e32 v199, v197
	s_nop 1
	v_permlane32_swap_b32 v198, v196
	v_permlane32_swap_b32 v199, v197
	v_add_f32_e32 v196, v196, v198
	v_add_f32_e32 v197, v197, v199
	s_mov_b64 exec, 0xffff
	ds_write_b64 v134, v[196:197]
	s_mov_b64 exec, -1
	s_waitcnt lgkmcnt(0)
	s_barrier
	s_add_u32 s92, s96, 0x30000
	s_addc_u32 s93, s97, 0
	s_add_u32 s40, s91, 0x10000
	s_mov_b32 m0, s40
	s_nop 0
	global_load_lds_dwordx4 v131, s[92:93]
	global_load_lds_dwordx4 v131, s[92:93] offset:1024
	global_load_lds_dwordx4 v131, s[92:93] offset:2048
	global_load_lds_dwordx4 v131, s[92:93] offset:3072
	s_add_u32 s92, s96, 0x31000
	s_addc_u32 s93, s97, 0
	s_add_u32 s40, s91, 0x11000
	s_mov_b32 m0, s40
	s_nop 0
	global_load_lds_dwordx4 v132, s[92:93]
	global_load_lds_dwordx4 v132, s[92:93] offset:1024
	global_load_lds_dwordx4 v132, s[92:93] offset:2048
	global_load_lds_dwordx4 v132, s[92:93] offset:3072
	ds_read_b128 v[160:163], v135 offset:0
	ds_read_b128 v[164:167], v135 offset:16
	ds_read_b128 v[168:171], v135 offset:32
	ds_read_b128 v[172:175], v135 offset:48
	s_waitcnt lgkmcnt(0)
	v_add_f32_e32 v160, v160, v162
	v_add_f32_e32 v161, v161, v163
	v_add_f32_e32 v164, v164, v166
	v_add_f32_e32 v165, v165, v167
	v_add_f32_e32 v168, v168, v170
	v_add_f32_e32 v169, v169, v171
	v_add_f32_e32 v172, v172, v174
	v_add_f32_e32 v173, v173, v175
	v_add_f32_e32 v160, v160, v164
	v_add_f32_e32 v161, v161, v165
	v_add_f32_e32 v168, v168, v172
	v_add_f32_e32 v169, v169, v173
	v_add_f32_e32 v160, v160, v168
	v_add_f32_e32 v161, v161, v169
	v_mul_f32_e32 v192, 0x3a800000, v160
	v_mul_f32_e32 v193, 0x3a800000, v161
	v_fma_f32 v193, -v192, v192, v193
	v_add_f32_e32 v193, 0x3727c5ac, v193
	v_rsq_f32_e32 v193, v193
	s_nop 0
	s_add_u32 s94, s78, 0x400
	s_addc_u32 s95, s79, 0
	ds_read_b128 v[176:179], v136
	ds_read_b128 v[180:183], v136 offset:4096
	ds_read_b128 v[184:187], v136 offset:64
	ds_read_b128 v[188:191], v136 offset:4160
	s_waitcnt lgkmcnt(2)
; DI unsigned pk2(float lo, float hi) { const f32x2 v = {lo, hi}; const bf16x2_t b = __builtin_convertvector(v, bf16x2_t); return __builtin_bit_cast(unsigned, b); }
; DI size_t xb_off(int tok, int col) { return ((size_t)(((tok >> 7) * 32 + (col >> 5)) * 128 + (tok & 127))) * 32 + (col & 31); }
; DI void unit_O(const Params& p, char* lds, int l, int tile, int glu_tiles, int tile_b) {
;     ...
;             float* orow = xo + (r0 + row) * 1024 + wid * 128 + quad * 4;
;             bf16_t* brow = xbo + xb_off((int)r0 + row, wid * 128) + quad * 4;
;             const float* gp = GB + wid * 128 + quad * 4;
; #pragma unroll
;             for (int nt = 0; nt < 8; ++nt) {
;                 const f32x4 g = *(const f32x4*)(gp + nt * 16), bb = *(const f32x4*)(gp + 1024 + nt * 16);
;                 f32x4 o;
; #pragma unroll
;                 for (int i = 0; i < 4; ++i) o[i] = (acc[mt][nt][i] - mu) * rs * g[i] + bb[i];
;                 if (l == 0) *(u32x2*)(brow + (nt >> 1) * 4096 + (nt & 1) * 16) = (u32x2){pk2(o[0], o[1]), pk2(o[2], o[3])};
;                 else *(f32x4*)(orow + nt * 16) = o;
	v_sub_f32_e32 v126, v126, v192
	v_mul_f32_e32 v126, v126, v193
	v_fma_f32 v126, v176, v126, v180
	v_sub_f32_e32 v127, v127, v192
	v_mul_f32_e32 v127, v127, v193
	v_fma_f32 v127, v177, v127, v181
	v_sub_f32_e32 v128, v128, v192
	v_mul_f32_e32 v128, v128, v193
	v_fma_f32 v128, v178, v128, v182
	v_sub_f32_e32 v129, v129, v192
	v_mul_f32_e32 v129, v129, v193
	v_fma_f32 v129, v179, v129, v183
	v_cvt_pk_bf16_f32 v144, v126, v127
	v_cvt_pk_bf16_f32 v145, v128, v129
	ds_read_b128 v[176:179], v136 offset:128
	ds_read_b128 v[180:183], v136 offset:4224
	s_waitcnt lgkmcnt(2)
	v_sub_f32_e32 v122, v122, v192
	v_mul_f32_e32 v122, v122, v193
	v_fma_f32 v122, v184, v122, v188
	v_sub_f32_e32 v123, v123, v192
	v_mul_f32_e32 v123, v123, v193
	v_fma_f32 v123, v185, v123, v189
	v_sub_f32_e32 v124, v124, v192
	v_mul_f32_e32 v124, v124, v193
	v_fma_f32 v124, v186, v124, v190
	v_sub_f32_e32 v125, v125, v192
	v_mul_f32_e32 v125, v125, v193
	v_fma_f32 v125, v187, v125, v191
	v_cvt_pk_bf16_f32 v146, v122, v123
	v_cvt_pk_bf16_f32 v147, v124, v125
	s_nop 1
	v_permlane16_swap_b32 v144, v146
	v_permlane16_swap_b32 v145, v147
	global_store_dwordx4 v137, v[144:147], s[94:95]
	s_add_u32 s94, s94, 0x2000
	s_addc_u32 s95, s95, 0
	ds_read_b128 v[184:187], v136 offset:192
	ds_read_b128 v[188:191], v136 offset:4288
	s_waitcnt lgkmcnt(2)
	v_sub_f32_e32 v118, v118, v192
	v_mul_f32_e32 v118, v118, v193
	v_fma_f32 v118, v176, v118, v180
	v_sub_f32_e32 v119, v119, v192
	v_mul_f32_e32 v119, v119, v193
	v_fma_f32 v119, v177, v119, v181
	v_sub_f32_e32 v120, v120, v192
	v_mul_f32_e32 v120, v120, v193
	v_fma_f32 v120, v178, v120, v182
	v_sub_f32_e32 v121, v121, v192
	v_mul_f32_e32 v121, v121, v193
	v_fma_f32 v121, v179, v121, v183
	v_cvt_pk_bf16_f32 v152, v118, v119
	v_cvt_pk_bf16_f32 v153, v120, v121
	ds_read_b128 v[176:179], v136 offset:256
	ds_read_b128 v[180:183], v136 offset:4352
	s_waitcnt lgkmcnt(2)
	v_sub_f32_e32 v114, v114, v192
	v_mul_f32_e32 v114, v114, v193
	v_fma_f32 v114, v184, v114, v188
	v_sub_f32_e32 v115, v115, v192
	v_mul_f32_e32 v115, v115, v193
	v_fma_f32 v115, v185, v115, v189
	v_sub_f32_e32 v116, v116, v192
	v_mul_f32_e32 v116, v116, v193
	v_fma_f32 v116, v186, v116, v190
	v_sub_f32_e32 v117, v117, v192
	v_mul_f32_e32 v117, v117, v193
	v_fma_f32 v117, v187, v117, v191
	v_cvt_pk_bf16_f32 v154, v114, v115
	v_cvt_pk_bf16_f32 v155, v116, v117
	s_nop 1
	v_permlane16_swap_b32 v152, v154
	v_permlane16_swap_b32 v153, v155
	global_store_dwordx4 v137, v[152:155], s[94:95]
	s_add_u32 s94, s94, 0x2000
	s_addc_u32 s95, s95, 0
	ds_read_b128 v[184:187], v136 offset:320
	ds_read_b128 v[188:191], v136 offset:4416
	s_waitcnt lgkmcnt(2)
	v_sub_f32_e32 v110, v110, v192
	v_mul_f32_e32 v110, v110, v193
	v_fma_f32 v110, v176, v110, v180
	v_sub_f32_e32 v111, v111, v192
	v_mul_f32_e32 v111, v111, v193
	v_fma_f32 v111, v177, v111, v181
	v_sub_f32_e32 v112, v112, v192
	v_mul_f32_e32 v112, v112, v193
	v_fma_f32 v112, v178, v112, v182
	v_sub_f32_e32 v113, v113, v192
	v_mul_f32_e32 v113, v113, v193
	v_fma_f32 v113, v179, v113, v183
	v_cvt_pk_bf16_f32 v144, v110, v111
	v_cvt_pk_bf16_f32 v145, v112, v113
	ds_read_b128 v[176:179], v136 offset:384
	ds_read_b128 v[180:183], v136 offset:4480
	s_waitcnt lgkmcnt(2)
	v_sub_f32_e32 v106, v106, v192
	v_mul_f32_e32 v106, v106, v193
	v_fma_f32 v106, v184, v106, v188
	v_sub_f32_e32 v107, v107, v192
	v_mul_f32_e32 v107, v107, v193
	v_fma_f32 v107, v185, v107, v189
	v_sub_f32_e32 v108, v108, v192
	v_mul_f32_e32 v108, v108, v193
	v_fma_f32 v108, v186, v108, v190
	v_sub_f32_e32 v109, v109, v192
	v_mul_f32_e32 v109, v109, v193
	v_fma_f32 v109, v187, v109, v191
	v_cvt_pk_bf16_f32 v146, v106, v107
	v_cvt_pk_bf16_f32 v147, v108, v109
	s_nop 1
	v_permlane16_swap_b32 v144, v146
	v_permlane16_swap_b32 v145, v147
	global_store_dwordx4 v137, v[144:147], s[94:95]
	s_add_u32 s94, s94, 0x2000
	s_addc_u32 s95, s95, 0
	ds_read_b128 v[184:187], v136 offset:448
	ds_read_b128 v[188:191], v136 offset:4544
	s_waitcnt lgkmcnt(2)
	v_sub_f32_e32 v102, v102, v192
	v_mul_f32_e32 v102, v102, v193
	v_fma_f32 v102, v176, v102, v180
	v_sub_f32_e32 v103, v103, v192
	v_mul_f32_e32 v103, v103, v193
	v_fma_f32 v103, v177, v103, v181
	v_sub_f32_e32 v104, v104, v192
	v_mul_f32_e32 v104, v104, v193
	v_fma_f32 v104, v178, v104, v182
	v_sub_f32_e32 v105, v105, v192
	v_mul_f32_e32 v105, v105, v193
	v_fma_f32 v105, v179, v105, v183
	v_cvt_pk_bf16_f32 v152, v102, v103
	v_cvt_pk_bf16_f32 v153, v104, v105
	s_waitcnt lgkmcnt(0)
	v_sub_f32_e32 v66, v66, v192
	v_mul_f32_e32 v66, v66, v193
	v_fma_f32 v66, v184, v66, v188
	v_sub_f32_e32 v67, v67, v192
	v_mul_f32_e32 v67, v67, v193
	v_fma_f32 v67, v185, v67, v189
	v_sub_f32_e32 v68, v68, v192
	v_mul_f32_e32 v68, v68, v193
	v_fma_f32 v68, v186, v68, v190
	v_sub_f32_e32 v69, v69, v192
	v_mul_f32_e32 v69, v69, v193
	v_fma_f32 v69, v187, v69, v191
	v_cvt_pk_bf16_f32 v154, v66, v67
	v_cvt_pk_bf16_f32 v155, v68, v69
	s_nop 1
	v_permlane16_swap_b32 v152, v154
	v_permlane16_swap_b32 v153, v155
	global_store_dwordx4 v137, v[152:155], s[94:95]
	s_waitcnt vmcnt(16) lgkmcnt(0)
	s_barrier
; DI float bf2f(unsigned b) { return __uint_as_float(b << 16); }
; DI void unit_O(const Params& p, char* lds, int l, int tile, int glu_tiles, int tile_b) {
;     ...
;         float s2[2], ss2[2];
; #pragma unroll
;         for (int mh = 0; mh < 2; ++mh) {
;             const int mt = half * 2 + mh, rl = mh * 16 + l15;
;             float s = 0.f, ss = 0.f;
; #pragma unroll
;             for (int nt = 0; nt < 8; ++nt) {
;                 f32x4 xr;
;                 if (l == 0) {
;                     const int chunk = wid * 32 + nt * 4 + quad;
;                     xr = *(const f32x4*)(XR + rl * 4096 + ((chunk ^ l15) << 4));
;                 } else {
;                     const u32x2 hb = *(const u32x2*)(XR + ((wid * 4 + (nt >> 1)) * 32 + rl) * 64 + (nt & 1) * 32 + quad * 8);
;                     xr = (f32x4){bf2f(hb[0] & 0xffffu), bf2f(hb[0] >> 16), bf2f(hb[1] & 0xffffu), bf2f(hb[1] >> 16)};
;                 }
; #pragma unroll
;                 for (int i = 0; i < 4; ++i) { const float v = acc[mt][nt][i] + DN_ALPHA * xr[i]; acc[mt][nt][i] = v; s += v; ss += v * v; }
;             }
;             s2[mh] = s; ss2[mh] = ss;
;         }
; #pragma unroll
;         for (int mh = 0; mh < 2; ++mh) { s2[mh] += __shfl_xor(s2[mh], 16); ss2[mh] += __shfl_xor(ss2[mh], 16); }
; #pragma unroll
;         for (int mh = 0; mh < 2; ++mh) { s2[mh] += __shfl_xor(s2[mh], 32); ss2[mh] += __shfl_xor(ss2[mh], 32); }
;         if (quad == 0) {
; #pragma unroll
;             for (int mh = 0; mh < 2; ++mh) *(f32x2*)&red[((mh * 16 + l15) * 8 + wid) * 2] = (f32x2){s2[mh], ss2[mh]};
;         }
;         __syncthreads();
;         if (half == 0) issue_x(1);
; #pragma unroll
;         for (int mh = 0; mh < 2; ++mh) {
;             const int mt = half * 2 + mh, rl = mh * 16 + l15, row = mt * 16 + l15;
;             float s = 0.f, ss = 0.f;
; #pragma unroll
;             for (int w = 0; w < 4; ++w) { const f32x4 v = *(const f32x4*)&red[rl * 16 + 4 * w]; s += v[0] + v[2]; ss += v[1] + v[3]; }
;             const float mu = s * (1.f / 1024.f);
;             const float var = ss * (1.f / 1024.f) - mu * mu;
;             const float rs = rsqrtf(var + LN_EPS);
;             float* orow = xo + (r0 + row) * 1024 + wid * 128 + quad * 4;
	ds_read_b128 v[144:147], v200
	ds_read_b128 v[148:151], v201
	ds_read_b128 v[152:155], v202
	ds_read_b128 v[156:159], v203
	ds_read_b128 v[160:163], v200 offset:256
	ds_read_b128 v[164:167], v201 offset:256
	ds_read_b128 v[168:171], v202 offset:256
	ds_read_b128 v[172:175], v203 offset:256
	s_waitcnt lgkmcnt(7)
	v_fmac_f32_e32 v34, s58, v144
	v_fmac_f32_e32 v35, s58, v145
	v_fmac_f32_e32 v36, s58, v146
	v_fmac_f32_e32 v37, s58, v147
	v_mov_b32_e32 v196, v34
	v_mul_f32_e32 v197, v34, v34
	v_mov_b32_e32 v130, v35
	v_mul_f32_e32 v142, v35, v35
	v_add_f32_e32 v196, v196, v36
	v_fmac_f32_e32 v197, v36, v36
	v_add_f32_e32 v130, v130, v37
	v_fmac_f32_e32 v142, v37, v37
	s_waitcnt lgkmcnt(6)
	v_fmac_f32_e32 v30, s58, v148
	v_fmac_f32_e32 v31, s58, v149
	v_fmac_f32_e32 v32, s58, v150
	v_fmac_f32_e32 v33, s58, v151
	v_add_f32_e32 v196, v196, v30
	v_fmac_f32_e32 v197, v30, v30
	v_add_f32_e32 v130, v130, v31
	v_fmac_f32_e32 v142, v31, v31
	v_add_f32_e32 v196, v196, v32
	v_fmac_f32_e32 v197, v32, v32
	v_add_f32_e32 v130, v130, v33
	v_fmac_f32_e32 v142, v33, v33
	s_waitcnt lgkmcnt(5)
	v_fmac_f32_e32 v26, s58, v152
	v_fmac_f32_e32 v27, s58, v153
	v_fmac_f32_e32 v28, s58, v154
	v_fmac_f32_e32 v29, s58, v155
	v_add_f32_e32 v196, v196, v26
	v_fmac_f32_e32 v197, v26, v26
	v_add_f32_e32 v130, v130, v27
	v_fmac_f32_e32 v142, v27, v27
	v_add_f32_e32 v196, v196, v28
	v_fmac_f32_e32 v197, v28, v28
	v_add_f32_e32 v130, v130, v29
	v_fmac_f32_e32 v142, v29, v29
	s_waitcnt lgkmcnt(4)
	v_fmac_f32_e32 v22, s58, v156
	v_fmac_f32_e32 v23, s58, v157
	v_fmac_f32_e32 v24, s58, v158
	v_fmac_f32_e32 v25, s58, v159
	v_add_f32_e32 v196, v196, v22
	v_fmac_f32_e32 v197, v22, v22
	v_add_f32_e32 v130, v130, v23
	v_fmac_f32_e32 v142, v23, v23
	v_add_f32_e32 v196, v196, v24
	v_fmac_f32_e32 v197, v24, v24
	v_add_f32_e32 v130, v130, v25
	v_fmac_f32_e32 v142, v25, v25
	s_waitcnt lgkmcnt(3)
	v_fmac_f32_e32 v18, s58, v160
	v_fmac_f32_e32 v19, s58, v161
	v_fmac_f32_e32 v20, s58, v162
	v_fmac_f32_e32 v21, s58, v163
	v_add_f32_e32 v196, v196, v18
	v_fmac_f32_e32 v197, v18, v18
	v_add_f32_e32 v130, v130, v19
	v_fmac_f32_e32 v142, v19, v19
	v_add_f32_e32 v196, v196, v20
	v_fmac_f32_e32 v197, v20, v20
	v_add_f32_e32 v130, v130, v21
	v_fmac_f32_e32 v142, v21, v21
	s_waitcnt lgkmcnt(2)
	v_fmac_f32_e32 v14, s58, v164
	v_fmac_f32_e32 v15, s58, v165
	v_fmac_f32_e32 v16, s58, v166
	v_fmac_f32_e32 v17, s58, v167
	v_add_f32_e32 v196, v196, v14
	v_fmac_f32_e32 v197, v14, v14
	v_add_f32_e32 v130, v130, v15
	v_fmac_f32_e32 v142, v15, v15
	v_add_f32_e32 v196, v196, v16
	v_fmac_f32_e32 v197, v16, v16
	v_add_f32_e32 v130, v130, v17
	v_fmac_f32_e32 v142, v17, v17
	s_waitcnt lgkmcnt(1)
	v_fmac_f32_e32 v10, s58, v168
	v_fmac_f32_e32 v11, s58, v169
	v_fmac_f32_e32 v12, s58, v170
	v_fmac_f32_e32 v13, s58, v171
	v_add_f32_e32 v196, v196, v10
	v_fmac_f32_e32 v197, v10, v10
	v_add_f32_e32 v130, v130, v11
	v_fmac_f32_e32 v142, v11, v11
	v_add_f32_e32 v196, v196, v12
	v_fmac_f32_e32 v197, v12, v12
	v_add_f32_e32 v130, v130, v13
	v_fmac_f32_e32 v142, v13, v13
	s_waitcnt lgkmcnt(0)
	v_fmac_f32_e32 v6, s58, v172
	v_fmac_f32_e32 v7, s58, v173
	v_fmac_f32_e32 v8, s58, v174
	v_fmac_f32_e32 v9, s58, v175
	v_add_f32_e32 v196, v196, v6
	v_fmac_f32_e32 v197, v6, v6
	v_add_f32_e32 v130, v130, v7
	v_fmac_f32_e32 v142, v7, v7
	v_add_f32_e32 v196, v196, v8
	v_fmac_f32_e32 v197, v8, v8
	v_add_f32_e32 v130, v130, v9
	v_fmac_f32_e32 v142, v9, v9
	v_add_f32_e32 v196, v196, v130
	v_add_f32_e32 v197, v197, v142
	v_mov_b32_e32 v198, v196
	v_mov_b32_e32 v199, v197
	s_nop 1
	v_permlane16_swap_b32 v198, v196
	v_permlane16_swap_b32 v199, v197
	v_add_f32_e32 v196, v196, v198
	v_add_f32_e32 v197, v197, v199
	v_mov_b32_e32 v198, v196
	v_mov_b32_e32 v199, v197
	s_nop 1
	v_permlane32_swap_b32 v198, v196
	v_permlane32_swap_b32 v199, v197
	v_add_f32_e32 v196, v196, v198
	v_add_f32_e32 v197, v197, v199
	s_mov_b64 exec, 0xffff
	ds_write_b64 v134, v[196:197]
	s_mov_b64 exec, -1
	s_waitcnt lgkmcnt(0)
	s_barrier
	ds_read_b128 v[160:163], v135 offset:0
	ds_read_b128 v[164:167], v135 offset:16
	ds_read_b128 v[168:171], v135 offset:32
	ds_read_b128 v[172:175], v135 offset:48
	s_waitcnt lgkmcnt(0)
	v_add_f32_e32 v160, v160, v162
	v_add_f32_e32 v161, v161, v163
	v_add_f32_e32 v164, v164, v166
	v_add_f32_e32 v165, v165, v167
	v_add_f32_e32 v168, v168, v170
	v_add_f32_e32 v169, v169, v171
	v_add_f32_e32 v172, v172, v174
	v_add_f32_e32 v173, v173, v175
	v_add_f32_e32 v160, v160, v164
	v_add_f32_e32 v161, v161, v165
	v_add_f32_e32 v168, v168, v172
	v_add_f32_e32 v169, v169, v173
	v_add_f32_e32 v160, v160, v168
	v_add_f32_e32 v161, v161, v169
	v_mul_f32_e32 v192, 0x3a800000, v160
	v_mul_f32_e32 v193, 0x3a800000, v161
	v_fma_f32 v193, -v192, v192, v193
	v_add_f32_e32 v193, 0x3727c5ac, v193
	v_rsq_f32_e32 v193, v193
	s_nop 0
	s_add_u32 s94, s78, 0x800
	s_addc_u32 s95, s79, 0
	ds_read_b128 v[176:179], v136
	ds_read_b128 v[180:183], v136 offset:4096
	ds_read_b128 v[184:187], v136 offset:64
	ds_read_b128 v[188:191], v136 offset:4160
	s_waitcnt lgkmcnt(2)
	v_sub_f32_e32 v34, v34, v192
	v_mul_f32_e32 v34, v34, v193
	v_fma_f32 v34, v176, v34, v180
	v_sub_f32_e32 v35, v35, v192
	v_mul_f32_e32 v35, v35, v193
	v_fma_f32 v35, v177, v35, v181
	v_sub_f32_e32 v36, v36, v192
	v_mul_f32_e32 v36, v36, v193
	v_fma_f32 v36, v178, v36, v182
	v_sub_f32_e32 v37, v37, v192
	v_mul_f32_e32 v37, v37, v193
	v_fma_f32 v37, v179, v37, v183
	v_cvt_pk_bf16_f32 v144, v34, v35
	v_cvt_pk_bf16_f32 v145, v36, v37
	ds_read_b128 v[176:179], v136 offset:128
	ds_read_b128 v[180:183], v136 offset:4224
	s_waitcnt lgkmcnt(2)
; DI unsigned pk2(float lo, float hi) { const f32x2 v = {lo, hi}; const bf16x2_t b = __builtin_convertvector(v, bf16x2_t); return __builtin_bit_cast(unsigned, b); }
; DI size_t xb_off(int tok, int col) { return ((size_t)(((tok >> 7) * 32 + (col >> 5)) * 128 + (tok & 127))) * 32 + (col & 31); }
; DI void unit_O(const Params& p, char* lds, int l, int tile, int glu_tiles, int tile_b) {
;     ...
;             float* orow = xo + (r0 + row) * 1024 + wid * 128 + quad * 4;
;             bf16_t* brow = xbo + xb_off((int)r0 + row, wid * 128) + quad * 4;
;             const float* gp = GB + wid * 128 + quad * 4;
; #pragma unroll
;             for (int nt = 0; nt < 8; ++nt) {
;                 const f32x4 g = *(const f32x4*)(gp + nt * 16), bb = *(const f32x4*)(gp + 1024 + nt * 16);
;                 f32x4 o;
; #pragma unroll
;                 for (int i = 0; i < 4; ++i) o[i] = (acc[mt][nt][i] - mu) * rs * g[i] + bb[i];
;                 if (l == 0) *(u32x2*)(brow + (nt >> 1) * 4096 + (nt & 1) * 16) = (u32x2){pk2(o[0], o[1]), pk2(o[2], o[3])};
;                 else *(f32x4*)(orow + nt * 16) = o;
	v_sub_f32_e32 v30, v30, v192
	v_mul_f32_e32 v30, v30, v193
	v_fma_f32 v30, v184, v30, v188
	v_sub_f32_e32 v31, v31, v192
	v_mul_f32_e32 v31, v31, v193
	v_fma_f32 v31, v185, v31, v189
	v_sub_f32_e32 v32, v32, v192
	v_mul_f32_e32 v32, v32, v193
	v_fma_f32 v32, v186, v32, v190
	v_sub_f32_e32 v33, v33, v192
	v_mul_f32_e32 v33, v33, v193
	v_fma_f32 v33, v187, v33, v191
	v_cvt_pk_bf16_f32 v146, v30, v31
	v_cvt_pk_bf16_f32 v147, v32, v33
	s_nop 1
	v_permlane16_swap_b32 v144, v146
	v_permlane16_swap_b32 v145, v147
	global_store_dwordx4 v137, v[144:147], s[94:95]
	s_add_u32 s94, s94, 0x2000
	s_addc_u32 s95, s95, 0
	ds_read_b128 v[184:187], v136 offset:192
	ds_read_b128 v[188:191], v136 offset:4288
	s_waitcnt lgkmcnt(2)
	v_sub_f32_e32 v26, v26, v192
	v_mul_f32_e32 v26, v26, v193
	v_fma_f32 v26, v176, v26, v180
	v_sub_f32_e32 v27, v27, v192
	v_mul_f32_e32 v27, v27, v193
	v_fma_f32 v27, v177, v27, v181
	v_sub_f32_e32 v28, v28, v192
	v_mul_f32_e32 v28, v28, v193
	v_fma_f32 v28, v178, v28, v182
	v_sub_f32_e32 v29, v29, v192
	v_mul_f32_e32 v29, v29, v193
	v_fma_f32 v29, v179, v29, v183
	v_cvt_pk_bf16_f32 v152, v26, v27
	v_cvt_pk_bf16_f32 v153, v28, v29
	ds_read_b128 v[176:179], v136 offset:256
	ds_read_b128 v[180:183], v136 offset:4352
	s_waitcnt lgkmcnt(2)
	v_sub_f32_e32 v22, v22, v192
	v_mul_f32_e32 v22, v22, v193
	v_fma_f32 v22, v184, v22, v188
	v_sub_f32_e32 v23, v23, v192
	v_mul_f32_e32 v23, v23, v193
	v_fma_f32 v23, v185, v23, v189
	v_sub_f32_e32 v24, v24, v192
	v_mul_f32_e32 v24, v24, v193
	v_fma_f32 v24, v186, v24, v190
	v_sub_f32_e32 v25, v25, v192
	v_mul_f32_e32 v25, v25, v193
	v_fma_f32 v25, v187, v25, v191
	v_cvt_pk_bf16_f32 v154, v22, v23
	v_cvt_pk_bf16_f32 v155, v24, v25
	s_nop 1
	v_permlane16_swap_b32 v152, v154
	v_permlane16_swap_b32 v153, v155
	global_store_dwordx4 v137, v[152:155], s[94:95]
	s_add_u32 s94, s94, 0x2000
	s_addc_u32 s95, s95, 0
	ds_read_b128 v[184:187], v136 offset:320
	ds_read_b128 v[188:191], v136 offset:4416
	s_waitcnt lgkmcnt(2)
	v_sub_f32_e32 v18, v18, v192
	v_mul_f32_e32 v18, v18, v193
	v_fma_f32 v18, v176, v18, v180
	v_sub_f32_e32 v19, v19, v192
	v_mul_f32_e32 v19, v19, v193
	v_fma_f32 v19, v177, v19, v181
	v_sub_f32_e32 v20, v20, v192
	v_mul_f32_e32 v20, v20, v193
	v_fma_f32 v20, v178, v20, v182
	v_sub_f32_e32 v21, v21, v192
	v_mul_f32_e32 v21, v21, v193
	v_fma_f32 v21, v179, v21, v183
	v_cvt_pk_bf16_f32 v144, v18, v19
	v_cvt_pk_bf16_f32 v145, v20, v21
	ds_read_b128 v[176:179], v136 offset:384
	ds_read_b128 v[180:183], v136 offset:4480
	s_waitcnt lgkmcnt(2)
	v_sub_f32_e32 v14, v14, v192
	v_mul_f32_e32 v14, v14, v193
	v_fma_f32 v14, v184, v14, v188
	v_sub_f32_e32 v15, v15, v192
	v_mul_f32_e32 v15, v15, v193
	v_fma_f32 v15, v185, v15, v189
	v_sub_f32_e32 v16, v16, v192
	v_mul_f32_e32 v16, v16, v193
	v_fma_f32 v16, v186, v16, v190
	v_sub_f32_e32 v17, v17, v192
	v_mul_f32_e32 v17, v17, v193
	v_fma_f32 v17, v187, v17, v191
	v_cvt_pk_bf16_f32 v146, v14, v15
	v_cvt_pk_bf16_f32 v147, v16, v17
	s_nop 1
	v_permlane16_swap_b32 v144, v146
	v_permlane16_swap_b32 v145, v147
	global_store_dwordx4 v137, v[144:147], s[94:95]
	s_add_u32 s94, s94, 0x2000
	s_addc_u32 s95, s95, 0
	ds_read_b128 v[184:187], v136 offset:448
	ds_read_b128 v[188:191], v136 offset:4544
	s_waitcnt lgkmcnt(2)
	v_sub_f32_e32 v10, v10, v192
	v_mul_f32_e32 v10, v10, v193
	v_fma_f32 v10, v176, v10, v180
	v_sub_f32_e32 v11, v11, v192
	v_mul_f32_e32 v11, v11, v193
	v_fma_f32 v11, v177, v11, v181
	v_sub_f32_e32 v12, v12, v192
	v_mul_f32_e32 v12, v12, v193
	v_fma_f32 v12, v178, v12, v182
	v_sub_f32_e32 v13, v13, v192
	v_mul_f32_e32 v13, v13, v193
	v_fma_f32 v13, v179, v13, v183
	v_cvt_pk_bf16_f32 v152, v10, v11
	v_cvt_pk_bf16_f32 v153, v12, v13
	s_waitcnt lgkmcnt(0)
	v_sub_f32_e32 v6, v6, v192
	v_mul_f32_e32 v6, v6, v193
	v_fma_f32 v6, v184, v6, v188
	v_sub_f32_e32 v7, v7, v192
	v_mul_f32_e32 v7, v7, v193
	v_fma_f32 v7, v185, v7, v189
	v_sub_f32_e32 v8, v8, v192
	v_mul_f32_e32 v8, v8, v193
	v_fma_f32 v8, v186, v8, v190
	v_sub_f32_e32 v9, v9, v192
	v_mul_f32_e32 v9, v9, v193
	v_fma_f32 v9, v187, v9, v191
	v_cvt_pk_bf16_f32 v154, v6, v7
	v_cvt_pk_bf16_f32 v155, v8, v9
	s_nop 1
	v_permlane16_swap_b32 v152, v154
	v_permlane16_swap_b32 v153, v155
	global_store_dwordx4 v137, v[152:155], s[94:95]
	s_waitcnt vmcnt(8) lgkmcnt(0)
	s_barrier
; DI float bf2f(unsigned b) { return __uint_as_float(b << 16); }
; DI void unit_O(const Params& p, char* lds, int l, int tile, int glu_tiles, int tile_b) {
;     ...
;         float s2[2], ss2[2];
; #pragma unroll
;         for (int mh = 0; mh < 2; ++mh) {
;             const int mt = half * 2 + mh, rl = mh * 16 + l15;
;             float s = 0.f, ss = 0.f;
; #pragma unroll
;             for (int nt = 0; nt < 8; ++nt) {
;                 f32x4 xr;
;                 if (l == 0) {
;                     const int chunk = wid * 32 + nt * 4 + quad;
;                     xr = *(const f32x4*)(XR + rl * 4096 + ((chunk ^ l15) << 4));
;                 } else {
;                     const u32x2 hb = *(const u32x2*)(XR + ((wid * 4 + (nt >> 1)) * 32 + rl) * 64 + (nt & 1) * 32 + quad * 8);
;                     xr = (f32x4){bf2f(hb[0] & 0xffffu), bf2f(hb[0] >> 16), bf2f(hb[1] & 0xffffu), bf2f(hb[1] >> 16)};
;                 }
; #pragma unroll
;                 for (int i = 0; i < 4; ++i) { const float v = acc[mt][nt][i] + DN_ALPHA * xr[i]; acc[mt][nt][i] = v; s += v; ss += v * v; }
;             }
;             s2[mh] = s; ss2[mh] = ss;
;         }
; #pragma unroll
;         for (int mh = 0; mh < 2; ++mh) { s2[mh] += __shfl_xor(s2[mh], 16); ss2[mh] += __shfl_xor(ss2[mh], 16); }
; #pragma unroll
;         for (int mh = 0; mh < 2; ++mh) { s2[mh] += __shfl_xor(s2[mh], 32); ss2[mh] += __shfl_xor(ss2[mh], 32); }
;         if (quad == 0) {
; #pragma unroll
;             for (int mh = 0; mh < 2; ++mh) *(f32x2*)&red[((mh * 16 + l15) * 8 + wid) * 2] = (f32x2){s2[mh], ss2[mh]};
;         }
;         __syncthreads();
;         if (half == 0) issue_x(1);
; #pragma unroll
;         for (int mh = 0; mh < 2; ++mh) {
;             const int mt = half * 2 + mh, rl = mh * 16 + l15, row = mt * 16 + l15;
;             float s = 0.f, ss = 0.f;
; #pragma unroll
;             for (int w = 0; w < 4; ++w) { const f32x4 v = *(const f32x4*)&red[rl * 16 + 4 * w]; s += v[0] + v[2]; ss += v[1] + v[3]; }
;             const float mu = s * (1.f / 1024.f);
;             const float var = ss * (1.f / 1024.f) - mu * mu;
;             const float rs = rsqrtf(var + LN_EPS);
;             float* orow = xo + (r0 + row) * 1024 + wid * 128 + quad * 4;
	ds_read_b128 v[144:147], v204
	ds_read_b128 v[148:151], v205
	ds_read_b128 v[152:155], v206
	ds_read_b128 v[156:159], v207
	ds_read_b128 v[160:163], v204 offset:256
	ds_read_b128 v[164:167], v205 offset:256
	ds_read_b128 v[168:171], v206 offset:256
	ds_read_b128 v[172:175], v207 offset:256
	s_waitcnt lgkmcnt(7)
	v_fmac_f32_e32 v62, s58, v144
	v_fmac_f32_e32 v63, s58, v145
	v_fmac_f32_e32 v64, s58, v146
	v_fmac_f32_e32 v65, s58, v147
	v_mov_b32_e32 v196, v62
	v_mul_f32_e32 v197, v62, v62
	v_mov_b32_e32 v130, v63
	v_mul_f32_e32 v142, v63, v63
	v_add_f32_e32 v196, v196, v64
	v_fmac_f32_e32 v197, v64, v64
	v_add_f32_e32 v130, v130, v65
	v_fmac_f32_e32 v142, v65, v65
	s_waitcnt lgkmcnt(6)
	v_fmac_f32_e32 v58, s58, v148
	v_fmac_f32_e32 v59, s58, v149
	v_fmac_f32_e32 v60, s58, v150
	v_fmac_f32_e32 v61, s58, v151
	v_add_f32_e32 v196, v196, v58
	v_fmac_f32_e32 v197, v58, v58
	v_add_f32_e32 v130, v130, v59
	v_fmac_f32_e32 v142, v59, v59
	v_add_f32_e32 v196, v196, v60
	v_fmac_f32_e32 v197, v60, v60
	v_add_f32_e32 v130, v130, v61
	v_fmac_f32_e32 v142, v61, v61
	s_waitcnt lgkmcnt(5)
	v_fmac_f32_e32 v54, s58, v152
	v_fmac_f32_e32 v55, s58, v153
	v_fmac_f32_e32 v56, s58, v154
	v_fmac_f32_e32 v57, s58, v155
	v_add_f32_e32 v196, v196, v54
	v_fmac_f32_e32 v197, v54, v54
	v_add_f32_e32 v130, v130, v55
	v_fmac_f32_e32 v142, v55, v55
	v_add_f32_e32 v196, v196, v56
	v_fmac_f32_e32 v197, v56, v56
	v_add_f32_e32 v130, v130, v57
	v_fmac_f32_e32 v142, v57, v57
	s_waitcnt lgkmcnt(4)
	v_fmac_f32_e32 v50, s58, v156
	v_fmac_f32_e32 v51, s58, v157
	v_fmac_f32_e32 v52, s58, v158
	v_fmac_f32_e32 v53, s58, v159
	v_add_f32_e32 v196, v196, v50
	v_fmac_f32_e32 v197, v50, v50
	v_add_f32_e32 v130, v130, v51
	v_fmac_f32_e32 v142, v51, v51
	v_add_f32_e32 v196, v196, v52
	v_fmac_f32_e32 v197, v52, v52
	v_add_f32_e32 v130, v130, v53
	v_fmac_f32_e32 v142, v53, v53
	s_waitcnt lgkmcnt(3)
	v_fmac_f32_e32 v46, s58, v160
	v_fmac_f32_e32 v47, s58, v161
	v_fmac_f32_e32 v48, s58, v162
	v_fmac_f32_e32 v49, s58, v163
	v_add_f32_e32 v196, v196, v46
	v_fmac_f32_e32 v197, v46, v46
	v_add_f32_e32 v130, v130, v47
	v_fmac_f32_e32 v142, v47, v47
	v_add_f32_e32 v196, v196, v48
	v_fmac_f32_e32 v197, v48, v48
	v_add_f32_e32 v130, v130, v49
	v_fmac_f32_e32 v142, v49, v49
	s_waitcnt lgkmcnt(2)
	v_fmac_f32_e32 v42, s58, v164
	v_fmac_f32_e32 v43, s58, v165
	v_fmac_f32_e32 v44, s58, v166
	v_fmac_f32_e32 v45, s58, v167
	v_add_f32_e32 v196, v196, v42
	v_fmac_f32_e32 v197, v42, v42
	v_add_f32_e32 v130, v130, v43
	v_fmac_f32_e32 v142, v43, v43
	v_add_f32_e32 v196, v196, v44
	v_fmac_f32_e32 v197, v44, v44
	v_add_f32_e32 v130, v130, v45
	v_fmac_f32_e32 v142, v45, v45
	s_waitcnt lgkmcnt(1)
	v_fmac_f32_e32 v38, s58, v168
	v_fmac_f32_e32 v39, s58, v169
	v_fmac_f32_e32 v40, s58, v170
	v_fmac_f32_e32 v41, s58, v171
	v_add_f32_e32 v196, v196, v38
	v_fmac_f32_e32 v197, v38, v38
	v_add_f32_e32 v130, v130, v39
	v_fmac_f32_e32 v142, v39, v39
	v_add_f32_e32 v196, v196, v40
	v_fmac_f32_e32 v197, v40, v40
	v_add_f32_e32 v130, v130, v41
	v_fmac_f32_e32 v142, v41, v41
	s_waitcnt lgkmcnt(0)
	v_fmac_f32_e32 v2, s58, v172
	v_fmac_f32_e32 v3, s58, v173
	v_fmac_f32_e32 v4, s58, v174
	v_fmac_f32_e32 v5, s58, v175
	v_add_f32_e32 v196, v196, v2
	v_fmac_f32_e32 v197, v2, v2
	v_add_f32_e32 v130, v130, v3
	v_fmac_f32_e32 v142, v3, v3
	v_add_f32_e32 v196, v196, v4
	v_fmac_f32_e32 v197, v4, v4
	v_add_f32_e32 v130, v130, v5
	v_fmac_f32_e32 v142, v5, v5
	v_add_f32_e32 v196, v196, v130
	v_add_f32_e32 v197, v197, v142
	v_mov_b32_e32 v198, v196
	v_mov_b32_e32 v199, v197
	s_nop 1
	v_permlane16_swap_b32 v198, v196
	v_permlane16_swap_b32 v199, v197
	v_add_f32_e32 v196, v196, v198
	v_add_f32_e32 v197, v197, v199
	v_mov_b32_e32 v198, v196
	v_mov_b32_e32 v199, v197
	s_nop 1
	v_permlane32_swap_b32 v198, v196
	v_permlane32_swap_b32 v199, v197
	v_add_f32_e32 v196, v196, v198
	v_add_f32_e32 v197, v197, v199
	s_mov_b64 exec, 0xffff
	ds_write_b64 v134, v[196:197]
	s_mov_b64 exec, -1
	s_waitcnt lgkmcnt(0)
	s_barrier
	ds_read_b128 v[160:163], v135 offset:0
	ds_read_b128 v[164:167], v135 offset:16
	ds_read_b128 v[168:171], v135 offset:32
	ds_read_b128 v[172:175], v135 offset:48
	s_waitcnt lgkmcnt(0)
	v_add_f32_e32 v160, v160, v162
	v_add_f32_e32 v161, v161, v163
	v_add_f32_e32 v164, v164, v166
	v_add_f32_e32 v165, v165, v167
	v_add_f32_e32 v168, v168, v170
	v_add_f32_e32 v169, v169, v171
	v_add_f32_e32 v172, v172, v174
	v_add_f32_e32 v173, v173, v175
	v_add_f32_e32 v160, v160, v164
	v_add_f32_e32 v161, v161, v165
	v_add_f32_e32 v168, v168, v172
	v_add_f32_e32 v169, v169, v173
	v_add_f32_e32 v160, v160, v168
	v_add_f32_e32 v161, v161, v169
	v_mul_f32_e32 v192, 0x3a800000, v160
	v_mul_f32_e32 v193, 0x3a800000, v161
	v_fma_f32 v193, -v192, v192, v193
	v_add_f32_e32 v193, 0x3727c5ac, v193
	v_rsq_f32_e32 v193, v193
	s_nop 0
	s_add_u32 s94, s78, 0xc00
	s_addc_u32 s95, s79, 0
	ds_read_b128 v[176:179], v136
	ds_read_b128 v[180:183], v136 offset:4096
	ds_read_b128 v[184:187], v136 offset:64
	ds_read_b128 v[188:191], v136 offset:4160
	s_waitcnt lgkmcnt(2)
	v_sub_f32_e32 v62, v62, v192
	v_mul_f32_e32 v62, v62, v193
	v_fma_f32 v62, v176, v62, v180
	v_sub_f32_e32 v63, v63, v192
	v_mul_f32_e32 v63, v63, v193
	v_fma_f32 v63, v177, v63, v181
	v_sub_f32_e32 v64, v64, v192
	v_mul_f32_e32 v64, v64, v193
	v_fma_f32 v64, v178, v64, v182
	v_sub_f32_e32 v65, v65, v192
	v_mul_f32_e32 v65, v65, v193
	v_fma_f32 v65, v179, v65, v183
	v_cvt_pk_bf16_f32 v144, v62, v63
	v_cvt_pk_bf16_f32 v145, v64, v65
	ds_read_b128 v[176:179], v136 offset:128
	ds_read_b128 v[180:183], v136 offset:4224
	s_waitcnt lgkmcnt(2)
; DI unsigned pk2(float lo, float hi) { const f32x2 v = {lo, hi}; const bf16x2_t b = __builtin_convertvector(v, bf16x2_t); return __builtin_bit_cast(unsigned, b); }
; DI size_t xb_off(int tok, int col) { return ((size_t)(((tok >> 7) * 32 + (col >> 5)) * 128 + (tok & 127))) * 32 + (col & 31); }
; DI void unit_O(const Params& p, char* lds, int l, int tile, int glu_tiles, int tile_b) {
;     ...
;             float* orow = xo + (r0 + row) * 1024 + wid * 128 + quad * 4;
;             bf16_t* brow = xbo + xb_off((int)r0 + row, wid * 128) + quad * 4;
;             const float* gp = GB + wid * 128 + quad * 4;
; #pragma unroll
;             for (int nt = 0; nt < 8; ++nt) {
;                 const f32x4 g = *(const f32x4*)(gp + nt * 16), bb = *(const f32x4*)(gp + 1024 + nt * 16);
;                 f32x4 o;
; #pragma unroll
;                 for (int i = 0; i < 4; ++i) o[i] = (acc[mt][nt][i] - mu) * rs * g[i] + bb[i];
;                 if (l == 0) *(u32x2*)(brow + (nt >> 1) * 4096 + (nt & 1) * 16) = (u32x2){pk2(o[0], o[1]), pk2(o[2], o[3])};
;                 else *(f32x4*)(orow + nt * 16) = o;
	v_sub_f32_e32 v58, v58, v192
	v_mul_f32_e32 v58, v58, v193
	v_fma_f32 v58, v184, v58, v188
	v_sub_f32_e32 v59, v59, v192
	v_mul_f32_e32 v59, v59, v193
	v_fma_f32 v59, v185, v59, v189
	v_sub_f32_e32 v60, v60, v192
	v_mul_f32_e32 v60, v60, v193
	v_fma_f32 v60, v186, v60, v190
	v_sub_f32_e32 v61, v61, v192
	v_mul_f32_e32 v61, v61, v193
	v_fma_f32 v61, v187, v61, v191
	v_cvt_pk_bf16_f32 v146, v58, v59
	v_cvt_pk_bf16_f32 v147, v60, v61
	s_nop 1
	v_permlane16_swap_b32 v144, v146
	v_permlane16_swap_b32 v145, v147
	global_store_dwordx4 v137, v[144:147], s[94:95]
	s_add_u32 s94, s94, 0x2000
	s_addc_u32 s95, s95, 0
	ds_read_b128 v[184:187], v136 offset:192
	ds_read_b128 v[188:191], v136 offset:4288
	s_waitcnt lgkmcnt(2)
	v_sub_f32_e32 v54, v54, v192
	v_mul_f32_e32 v54, v54, v193
	v_fma_f32 v54, v176, v54, v180
	v_sub_f32_e32 v55, v55, v192
	v_mul_f32_e32 v55, v55, v193
	v_fma_f32 v55, v177, v55, v181
	v_sub_f32_e32 v56, v56, v192
	v_mul_f32_e32 v56, v56, v193
	v_fma_f32 v56, v178, v56, v182
	v_sub_f32_e32 v57, v57, v192
	v_mul_f32_e32 v57, v57, v193
	v_fma_f32 v57, v179, v57, v183
	v_cvt_pk_bf16_f32 v152, v54, v55
	v_cvt_pk_bf16_f32 v153, v56, v57
	ds_read_b128 v[176:179], v136 offset:256
	ds_read_b128 v[180:183], v136 offset:4352
	s_waitcnt lgkmcnt(2)
	v_sub_f32_e32 v50, v50, v192
	v_mul_f32_e32 v50, v50, v193
	v_fma_f32 v50, v184, v50, v188
	v_sub_f32_e32 v51, v51, v192
	v_mul_f32_e32 v51, v51, v193
	v_fma_f32 v51, v185, v51, v189
	v_sub_f32_e32 v52, v52, v192
	v_mul_f32_e32 v52, v52, v193
	v_fma_f32 v52, v186, v52, v190
	v_sub_f32_e32 v53, v53, v192
	v_mul_f32_e32 v53, v53, v193
	v_fma_f32 v53, v187, v53, v191
	v_cvt_pk_bf16_f32 v154, v50, v51
	v_cvt_pk_bf16_f32 v155, v52, v53
	s_nop 1
	v_permlane16_swap_b32 v152, v154
	v_permlane16_swap_b32 v153, v155
	global_store_dwordx4 v137, v[152:155], s[94:95]
	s_add_u32 s94, s94, 0x2000
	s_addc_u32 s95, s95, 0
	ds_read_b128 v[184:187], v136 offset:320
	ds_read_b128 v[188:191], v136 offset:4416
	s_waitcnt lgkmcnt(2)
	v_sub_f32_e32 v46, v46, v192
	v_mul_f32_e32 v46, v46, v193
	v_fma_f32 v46, v176, v46, v180
	v_sub_f32_e32 v47, v47, v192
	v_mul_f32_e32 v47, v47, v193
	v_fma_f32 v47, v177, v47, v181
	v_sub_f32_e32 v48, v48, v192
	v_mul_f32_e32 v48, v48, v193
	v_fma_f32 v48, v178, v48, v182
	v_sub_f32_e32 v49, v49, v192
	v_mul_f32_e32 v49, v49, v193
	v_fma_f32 v49, v179, v49, v183
	v_cvt_pk_bf16_f32 v144, v46, v47
	v_cvt_pk_bf16_f32 v145, v48, v49
	ds_read_b128 v[176:179], v136 offset:384
	ds_read_b128 v[180:183], v136 offset:4480
	s_waitcnt lgkmcnt(2)
	v_sub_f32_e32 v42, v42, v192
	v_mul_f32_e32 v42, v42, v193
	v_fma_f32 v42, v184, v42, v188
	v_sub_f32_e32 v43, v43, v192
	v_mul_f32_e32 v43, v43, v193
	v_fma_f32 v43, v185, v43, v189
	v_sub_f32_e32 v44, v44, v192
	v_mul_f32_e32 v44, v44, v193
	v_fma_f32 v44, v186, v44, v190
	v_sub_f32_e32 v45, v45, v192
	v_mul_f32_e32 v45, v45, v193
	v_fma_f32 v45, v187, v45, v191
	v_cvt_pk_bf16_f32 v146, v42, v43
	v_cvt_pk_bf16_f32 v147, v44, v45
	s_nop 1
	v_permlane16_swap_b32 v144, v146
	v_permlane16_swap_b32 v145, v147
	global_store_dwordx4 v137, v[144:147], s[94:95]
	s_add_u32 s94, s94, 0x2000
	s_addc_u32 s95, s95, 0
	ds_read_b128 v[184:187], v136 offset:448
	ds_read_b128 v[188:191], v136 offset:4544
	s_waitcnt lgkmcnt(2)
	v_sub_f32_e32 v38, v38, v192
	v_mul_f32_e32 v38, v38, v193
	v_fma_f32 v38, v176, v38, v180
	v_sub_f32_e32 v39, v39, v192
	v_mul_f32_e32 v39, v39, v193
	v_fma_f32 v39, v177, v39, v181
	v_sub_f32_e32 v40, v40, v192
	v_mul_f32_e32 v40, v40, v193
	v_fma_f32 v40, v178, v40, v182
	v_sub_f32_e32 v41, v41, v192
	v_mul_f32_e32 v41, v41, v193
	v_fma_f32 v41, v179, v41, v183
	v_cvt_pk_bf16_f32 v152, v38, v39
	v_cvt_pk_bf16_f32 v153, v40, v41
	s_waitcnt lgkmcnt(0)
	v_sub_f32_e32 v2, v2, v192
	v_mul_f32_e32 v2, v2, v193
	v_fma_f32 v2, v184, v2, v188
	v_sub_f32_e32 v3, v3, v192
	v_mul_f32_e32 v3, v3, v193
	v_fma_f32 v3, v185, v3, v189
	v_sub_f32_e32 v4, v4, v192
	v_mul_f32_e32 v4, v4, v193
	v_fma_f32 v4, v186, v4, v190
	v_sub_f32_e32 v5, v5, v192
	v_mul_f32_e32 v5, v5, v193
	v_fma_f32 v5, v187, v5, v191
	v_cvt_pk_bf16_f32 v154, v2, v3
	v_cvt_pk_bf16_f32 v155, v4, v5
	s_nop 1
	v_permlane16_swap_b32 v152, v154
	v_permlane16_swap_b32 v153, v155
	global_store_dwordx4 v137, v[152:155], s[94:95]
	s_branch .Le2_done
; DI void unit_O(const Params& p, char* lds, int l, int tile, int glu_tiles, int tile_b) {
;     ...
; #pragma unroll 1
;             for (int i = 0; i < 8; ++i) {
;                 const int pc = (wid * 8 + i + (xrot >> 1)) & 63, kt = pc >> 1, sub = pc & 1;
;                 __builtin_amdgcn_global_load_lds((const unsigned*)(xbres + ((size_t)kt * 128 + half * 32) * 32 + sub * 512 + lane * 8), (unsigned*)(XR + pc * 1024 + lane * 16), 16, 0, 0);
;             }
;         }
;     };
;     issue_x(0);
;     {
;         const float* gsrc = (tid < 256) ? (p.ln_g + l * 1024 + tid * 4) : (p.ln_b + l * 1024 + (tid - 256) * 4);
;         *(f32x4*)(GB + tid * 4) = *(const f32x4*)gsrc;
;     }
;     float* xo = (l == 0) ? WS_PTR(float, OFF_X1) : p.out;
;     bf16_t* xbo = WS_PTR(bf16_t, OFF_XB1);
; #pragma unroll
;     for (int half = 0; half < 2; ++half) {
;         if (half == 0) wait_vm<0>();
;         else wait_vm<8>();
;         __syncthreads();
;         float s2[2], ss2[2];
; #pragma unroll
;         for (int mh = 0; mh < 2; ++mh) {
;             const int mt = half * 2 + mh, rl = mh * 16 + l15;
;             float s = 0.f, ss = 0.f;
; #pragma unroll
;             for (int nt = 0; nt < 8; ++nt) {
;                 f32x4 xr;
;                 if (l == 0) {
;                     const int chunk = wid * 32 + nt * 4 + quad;
;                     xr = *(const f32x4*)(XR + rl * 4096 + ((chunk ^ l15) << 4));
;                 } else {
;                     const u32x2 hb = *(const u32x2*)(XR + ((wid * 4 + (nt >> 1)) * 32 + rl) * 64 + (nt & 1) * 32 + quad * 8);
;                     xr = (f32x4){bf2f(hb[0] & 0xffffu), bf2f(hb[0] >> 16), bf2f(hb[1] & 0xffffu), bf2f(hb[1] >> 16)};
;                 }
; #pragma unroll
;                 for (int i = 0; i < 4; ++i) { const float v = acc[mt][nt][i] + DN_ALPHA * xr[i]; acc[mt][nt][i] = v; s += v; ss += v * v; }
;             }
;             s2[mh] = s; ss2[mh] = ss;
;         }
; #pragma unroll
;         for (int mh = 0; mh < 2; ++mh) { s2[mh] += __shfl_xor(s2[mh], 16); ss2[mh] += __shfl_xor(ss2[mh], 16); }
; #pragma unroll
;         for (int mh = 0; mh < 2; ++mh) { s2[mh] += __shfl_xor(s2[mh], 32); ss2[mh] += __shfl_xor(ss2[mh], 32); }
;         if (quad == 0) {
; #pragma unroll
;             for (int mh = 0; mh < 2; ++mh) *(f32x2*)&red[((mh * 16 + l15) * 8 + wid) * 2] = (f32x2){s2[mh], ss2[mh]};
;         }
;         __syncthreads();
.Le2_l1:
	s_lshr_b32 s40, s48, 1
	s_lshl_b32 s40, s40, 18
	s_and_b32 s46, s48, 1
	s_lshl_b32 s46, s46, 12
	s_add_u32 s40, s40, s46
	s_lshl_b32 s91, s90, 12
	s_lshl_b32 s46, s90, 15
	s_add_u32 s96, s56, s40
	s_addc_u32 s97, s57, 0
	s_add_u32 s96, s96, s46
	s_addc_u32 s97, s97, 0
	v_lshlrev_b32_e32 v131, 4, v141
	v_lshlrev_b32_e32 v133, 12, v140
	v_lshl_add_u32 v133, v138, 6, v133
	v_lshl_add_u32 v133, v139, 3, v133
	v_lshlrev_b32_e32 v137, 12, v138
	v_lshl_add_u32 v137, v140, 9, v137
	v_lshl_add_u32 v137, v139, 4, v137
	s_lshl_b32 s40, s48, 18
	s_add_u32 s78, s16, s40
	s_addc_u32 s79, s17, 0
	s_add_u32 s92, s96, 0x0
	s_addc_u32 s93, s97, 0
	s_add_u32 s40, s91, 0x0
	s_mov_b32 m0, s40
	s_nop 0
	global_load_lds_dwordx4 v131, s[92:93]
	s_add_u32 s92, s92, 0x2000
	s_addc_u32 s93, s93, 0
	s_add_u32 m0, m0, 0x400
	s_nop 0
	global_load_lds_dwordx4 v131, s[92:93]
	s_add_u32 s92, s92, 0x2000
	s_addc_u32 s93, s93, 0
	s_add_u32 m0, m0, 0x400
	s_nop 0
	global_load_lds_dwordx4 v131, s[92:93]
	s_add_u32 s92, s92, 0x2000
	s_addc_u32 s93, s93, 0
	s_add_u32 m0, m0, 0x400
	s_nop 0
	global_load_lds_dwordx4 v131, s[92:93]
	s_add_u32 s92, s96, 0x400
	s_addc_u32 s93, s97, 0
	s_add_u32 s40, s91, 0x8000
	s_mov_b32 m0, s40
	s_nop 0
	global_load_lds_dwordx4 v131, s[92:93]
	s_add_u32 s92, s92, 0x2000
	s_addc_u32 s93, s93, 0
	s_add_u32 m0, m0, 0x400
	s_nop 0
	global_load_lds_dwordx4 v131, s[92:93]
	s_add_u32 s92, s92, 0x2000
	s_addc_u32 s93, s93, 0
	s_add_u32 m0, m0, 0x400
	s_nop 0
	global_load_lds_dwordx4 v131, s[92:93]
	s_add_u32 s92, s92, 0x2000
	s_addc_u32 s93, s93, 0
	s_add_u32 m0, m0, 0x400
	s_nop 0
	global_load_lds_dwordx4 v131, s[92:93]
	s_waitcnt vmcnt(8)
	ds_write_b128 v143, v[176:179]
	s_waitcnt vmcnt(4) lgkmcnt(0)
	s_barrier
	ds_read_b64 v[180:181], v133 offset:0
	ds_read_b64 v[182:183], v133 offset:32
	ds_read_b64 v[184:185], v133 offset:1024
	ds_read_b64 v[186:187], v133 offset:1056
	ds_read_b64 v[188:189], v133 offset:2048
	ds_read_b64 v[190:191], v133 offset:2080
	ds_read_b64 v[192:193], v133 offset:3072
	ds_read_b64 v[194:195], v133 offset:3104
	s_waitcnt lgkmcnt(7)
	v_lshlrev_b32_e32 v144, 16, v180
	v_and_b32_e32 v145, 0xffff0000, v180
	v_lshlrev_b32_e32 v146, 16, v181
	v_and_b32_e32 v147, 0xffff0000, v181
	v_fmac_f32_e32 v98, s58, v144
	v_fmac_f32_e32 v99, s58, v145
	v_fmac_f32_e32 v100, s58, v146
	v_fmac_f32_e32 v101, s58, v147
	v_mov_b32_e32 v196, v98
	v_mul_f32_e32 v197, v98, v98
	v_mov_b32_e32 v130, v99
	v_mul_f32_e32 v142, v99, v99
	v_add_f32_e32 v196, v196, v100
	v_fmac_f32_e32 v197, v100, v100
	v_add_f32_e32 v130, v130, v101
	v_fmac_f32_e32 v142, v101, v101
	s_waitcnt lgkmcnt(6)
	v_lshlrev_b32_e32 v148, 16, v182
	v_and_b32_e32 v149, 0xffff0000, v182
	v_lshlrev_b32_e32 v150, 16, v183
	v_and_b32_e32 v151, 0xffff0000, v183
	v_fmac_f32_e32 v94, s58, v148
	v_fmac_f32_e32 v95, s58, v149
	v_fmac_f32_e32 v96, s58, v150
	v_fmac_f32_e32 v97, s58, v151
	v_add_f32_e32 v196, v196, v94
	v_fmac_f32_e32 v197, v94, v94
	v_add_f32_e32 v130, v130, v95
	v_fmac_f32_e32 v142, v95, v95
	v_add_f32_e32 v196, v196, v96
	v_fmac_f32_e32 v197, v96, v96
	v_add_f32_e32 v130, v130, v97
	v_fmac_f32_e32 v142, v97, v97
	s_waitcnt lgkmcnt(5)
	v_lshlrev_b32_e32 v152, 16, v184
	v_and_b32_e32 v153, 0xffff0000, v184
	v_lshlrev_b32_e32 v154, 16, v185
	v_and_b32_e32 v155, 0xffff0000, v185
	v_fmac_f32_e32 v90, s58, v152
	v_fmac_f32_e32 v91, s58, v153
	v_fmac_f32_e32 v92, s58, v154
	v_fmac_f32_e32 v93, s58, v155
	v_add_f32_e32 v196, v196, v90
	v_fmac_f32_e32 v197, v90, v90
	v_add_f32_e32 v130, v130, v91
	v_fmac_f32_e32 v142, v91, v91
	v_add_f32_e32 v196, v196, v92
	v_fmac_f32_e32 v197, v92, v92
	v_add_f32_e32 v130, v130, v93
	v_fmac_f32_e32 v142, v93, v93
	s_waitcnt lgkmcnt(4)
	v_lshlrev_b32_e32 v156, 16, v186
	v_and_b32_e32 v157, 0xffff0000, v186
	v_lshlrev_b32_e32 v158, 16, v187
	v_and_b32_e32 v159, 0xffff0000, v187
	v_fmac_f32_e32 v86, s58, v156
	v_fmac_f32_e32 v87, s58, v157
	v_fmac_f32_e32 v88, s58, v158
	v_fmac_f32_e32 v89, s58, v159
	v_add_f32_e32 v196, v196, v86
	v_fmac_f32_e32 v197, v86, v86
	v_add_f32_e32 v130, v130, v87
	v_fmac_f32_e32 v142, v87, v87
	v_add_f32_e32 v196, v196, v88
	v_fmac_f32_e32 v197, v88, v88
	v_add_f32_e32 v130, v130, v89
	v_fmac_f32_e32 v142, v89, v89
	s_waitcnt lgkmcnt(3)
	v_lshlrev_b32_e32 v160, 16, v188
	v_and_b32_e32 v161, 0xffff0000, v188
	v_lshlrev_b32_e32 v162, 16, v189
	v_and_b32_e32 v163, 0xffff0000, v189
	v_fmac_f32_e32 v82, s58, v160
	v_fmac_f32_e32 v83, s58, v161
	v_fmac_f32_e32 v84, s58, v162
	v_fmac_f32_e32 v85, s58, v163
	v_add_f32_e32 v196, v196, v82
	v_fmac_f32_e32 v197, v82, v82
	v_add_f32_e32 v130, v130, v83
	v_fmac_f32_e32 v142, v83, v83
	v_add_f32_e32 v196, v196, v84
	v_fmac_f32_e32 v197, v84, v84
	v_add_f32_e32 v130, v130, v85
	v_fmac_f32_e32 v142, v85, v85
	s_waitcnt lgkmcnt(2)
	v_lshlrev_b32_e32 v164, 16, v190
	v_and_b32_e32 v165, 0xffff0000, v190
	v_lshlrev_b32_e32 v166, 16, v191
	v_and_b32_e32 v167, 0xffff0000, v191
	v_fmac_f32_e32 v78, s58, v164
	v_fmac_f32_e32 v79, s58, v165
	v_fmac_f32_e32 v80, s58, v166
	v_fmac_f32_e32 v81, s58, v167
	v_add_f32_e32 v196, v196, v78
	v_fmac_f32_e32 v197, v78, v78
	v_add_f32_e32 v130, v130, v79
	v_fmac_f32_e32 v142, v79, v79
	v_add_f32_e32 v196, v196, v80
	v_fmac_f32_e32 v197, v80, v80
	v_add_f32_e32 v130, v130, v81
	v_fmac_f32_e32 v142, v81, v81
	s_waitcnt lgkmcnt(1)
	v_lshlrev_b32_e32 v168, 16, v192
	v_and_b32_e32 v169, 0xffff0000, v192
	v_lshlrev_b32_e32 v170, 16, v193
	v_and_b32_e32 v171, 0xffff0000, v193
	v_fmac_f32_e32 v74, s58, v168
	v_fmac_f32_e32 v75, s58, v169
	v_fmac_f32_e32 v76, s58, v170
	v_fmac_f32_e32 v77, s58, v171
	v_add_f32_e32 v196, v196, v74
	v_fmac_f32_e32 v197, v74, v74
	v_add_f32_e32 v130, v130, v75
	v_fmac_f32_e32 v142, v75, v75
	v_add_f32_e32 v196, v196, v76
	v_fmac_f32_e32 v197, v76, v76
	v_add_f32_e32 v130, v130, v77
	v_fmac_f32_e32 v142, v77, v77
	s_waitcnt lgkmcnt(0)
	v_lshlrev_b32_e32 v172, 16, v194
	v_and_b32_e32 v173, 0xffff0000, v194
	v_lshlrev_b32_e32 v174, 16, v195
	v_and_b32_e32 v175, 0xffff0000, v195
	v_fmac_f32_e32 v70, s58, v172
	v_fmac_f32_e32 v71, s58, v173
	v_fmac_f32_e32 v72, s58, v174
	v_fmac_f32_e32 v73, s58, v175
	v_add_f32_e32 v196, v196, v70
	v_fmac_f32_e32 v197, v70, v70
	v_add_f32_e32 v130, v130, v71
	v_fmac_f32_e32 v142, v71, v71
	v_add_f32_e32 v196, v196, v72
	v_fmac_f32_e32 v197, v72, v72
	v_add_f32_e32 v130, v130, v73
	v_fmac_f32_e32 v142, v73, v73
	v_add_f32_e32 v196, v196, v130
	v_add_f32_e32 v197, v197, v142
	v_mov_b32_e32 v198, v196
	v_mov_b32_e32 v199, v197
	s_nop 1
	v_permlane16_swap_b32 v198, v196
	v_permlane16_swap_b32 v199, v197
	v_add_f32_e32 v196, v196, v198
	v_add_f32_e32 v197, v197, v199
	v_mov_b32_e32 v198, v196
	v_mov_b32_e32 v199, v197
	s_nop 1
	v_permlane32_swap_b32 v198, v196
	v_permlane32_swap_b32 v199, v197
	v_add_f32_e32 v196, v196, v198
	v_add_f32_e32 v197, v197, v199
	s_mov_b64 exec, 0xffff
	ds_write_b64 v134, v[196:197]
	s_mov_b64 exec, -1
	s_waitcnt lgkmcnt(0)
	s_barrier
; DI unsigned pk2(float lo, float hi) { const f32x2 v = {lo, hi}; const bf16x2_t b = __builtin_convertvector(v, bf16x2_t); return __builtin_bit_cast(unsigned, b); }
; DI size_t xb_off(int tok, int col) { return ((size_t)(((tok >> 7) * 32 + (col >> 5)) * 128 + (tok & 127))) * 32 + (col & 31); }
; DI void unit_O(const Params& p, char* lds, int l, int tile, int glu_tiles, int tile_b) {
;     ...
;         if (half == 0) issue_x(1);
; #pragma unroll
;         for (int mh = 0; mh < 2; ++mh) {
;             const int mt = half * 2 + mh, rl = mh * 16 + l15, row = mt * 16 + l15;
;             float s = 0.f, ss = 0.f;
; #pragma unroll
;             for (int w = 0; w < 4; ++w) { const f32x4 v = *(const f32x4*)&red[rl * 16 + 4 * w]; s += v[0] + v[2]; ss += v[1] + v[3]; }
;             const float mu = s * (1.f / 1024.f);
;             const float var = ss * (1.f / 1024.f) - mu * mu;
;             const float rs = rsqrtf(var + LN_EPS);
;             float* orow = xo + (r0 + row) * 1024 + wid * 128 + quad * 4;
;             bf16_t* brow = xbo + xb_off((int)r0 + row, wid * 128) + quad * 4;
;             const float* gp = GB + wid * 128 + quad * 4;
; #pragma unroll
;             for (int nt = 0; nt < 8; ++nt) {
;                 const f32x4 g = *(const f32x4*)(gp + nt * 16), bb = *(const f32x4*)(gp + 1024 + nt * 16);
;                 f32x4 o;
; #pragma unroll
;                 for (int i = 0; i < 4; ++i) o[i] = (acc[mt][nt][i] - mu) * rs * g[i] + bb[i];
;                 if (l == 0) *(u32x2*)(brow + (nt >> 1) * 4096 + (nt & 1) * 16) = (u32x2){pk2(o[0], o[1]), pk2(o[2], o[3])};
;                 else *(f32x4*)(orow + nt * 16) = o;
	s_add_u32 s92, s96, 0x800
	s_addc_u32 s93, s97, 0
	s_add_u32 s40, s91, 0x0
	s_mov_b32 m0, s40
	s_nop 0
	global_load_lds_dwordx4 v131, s[92:93]
	s_add_u32 s92, s92, 0x2000
	s_addc_u32 s93, s93, 0
	s_add_u32 m0, m0, 0x400
	s_nop 0
	global_load_lds_dwordx4 v131, s[92:93]
	s_add_u32 s92, s92, 0x2000
	s_addc_u32 s93, s93, 0
	s_add_u32 m0, m0, 0x400
	s_nop 0
	global_load_lds_dwordx4 v131, s[92:93]
	s_add_u32 s92, s92, 0x2000
	s_addc_u32 s93, s93, 0
	s_add_u32 m0, m0, 0x400
	s_nop 0
	global_load_lds_dwordx4 v131, s[92:93]
	ds_read_b128 v[160:163], v135 offset:0
	ds_read_b128 v[164:167], v135 offset:16
	ds_read_b128 v[168:171], v135 offset:32
	ds_read_b128 v[172:175], v135 offset:48
	s_waitcnt lgkmcnt(0)
	v_add_f32_e32 v160, v160, v162
	v_add_f32_e32 v161, v161, v163
	v_add_f32_e32 v164, v164, v166
	v_add_f32_e32 v165, v165, v167
	v_add_f32_e32 v168, v168, v170
	v_add_f32_e32 v169, v169, v171
	v_add_f32_e32 v172, v172, v174
	v_add_f32_e32 v173, v173, v175
	v_add_f32_e32 v160, v160, v164
	v_add_f32_e32 v161, v161, v165
	v_add_f32_e32 v168, v168, v172
	v_add_f32_e32 v169, v169, v173
	v_add_f32_e32 v160, v160, v168
	v_add_f32_e32 v161, v161, v169
	v_mul_f32_e32 v192, 0x3a800000, v160
	v_mul_f32_e32 v193, 0x3a800000, v161
	v_fma_f32 v193, -v192, v192, v193
	v_add_f32_e32 v193, 0x3727c5ac, v193
	v_rsq_f32_e32 v193, v193
	s_nop 0
	s_add_u32 s94, s78, 0x0
	s_addc_u32 s95, s79, 0
	ds_read_b128 v[176:179], v136
	ds_read_b128 v[180:183], v136 offset:4096
	ds_read_b128 v[184:187], v136 offset:64
	ds_read_b128 v[188:191], v136 offset:4160
	s_waitcnt lgkmcnt(2)
	v_sub_f32_e32 v98, v98, v192
	v_mul_f32_e32 v98, v98, v193
	v_fma_f32 v98, v176, v98, v180
	v_sub_f32_e32 v99, v99, v192
	v_mul_f32_e32 v99, v99, v193
	v_fma_f32 v99, v177, v99, v181
	v_sub_f32_e32 v100, v100, v192
	v_mul_f32_e32 v100, v100, v193
	v_fma_f32 v100, v178, v100, v182
	v_sub_f32_e32 v101, v101, v192
	v_mul_f32_e32 v101, v101, v193
	v_fma_f32 v101, v179, v101, v183
	global_store_dwordx4 v137, v[98:101], s[94:95]
	ds_read_b128 v[176:179], v136 offset:128
	ds_read_b128 v[180:183], v136 offset:4224
	s_waitcnt lgkmcnt(2)
	v_sub_f32_e32 v94, v94, v192
	v_mul_f32_e32 v94, v94, v193
	v_fma_f32 v94, v184, v94, v188
	v_sub_f32_e32 v95, v95, v192
	v_mul_f32_e32 v95, v95, v193
	v_fma_f32 v95, v185, v95, v189
	v_sub_f32_e32 v96, v96, v192
	v_mul_f32_e32 v96, v96, v193
	v_fma_f32 v96, v186, v96, v190
	v_sub_f32_e32 v97, v97, v192
	v_mul_f32_e32 v97, v97, v193
	v_fma_f32 v97, v187, v97, v191
	global_store_dwordx4 v137, v[94:97], s[94:95] offset:64
	ds_read_b128 v[184:187], v136 offset:192
	ds_read_b128 v[188:191], v136 offset:4288
	s_waitcnt lgkmcnt(2)
	v_sub_f32_e32 v90, v90, v192
	v_mul_f32_e32 v90, v90, v193
	v_fma_f32 v90, v176, v90, v180
	v_sub_f32_e32 v91, v91, v192
	v_mul_f32_e32 v91, v91, v193
	v_fma_f32 v91, v177, v91, v181
	v_sub_f32_e32 v92, v92, v192
	v_mul_f32_e32 v92, v92, v193
	v_fma_f32 v92, v178, v92, v182
	v_sub_f32_e32 v93, v93, v192
	v_mul_f32_e32 v93, v93, v193
	v_fma_f32 v93, v179, v93, v183
	global_store_dwordx4 v137, v[90:93], s[94:95] offset:128
	ds_read_b128 v[176:179], v136 offset:256
	ds_read_b128 v[180:183], v136 offset:4352
	s_waitcnt lgkmcnt(2)
	v_sub_f32_e32 v86, v86, v192
	v_mul_f32_e32 v86, v86, v193
	v_fma_f32 v86, v184, v86, v188
	v_sub_f32_e32 v87, v87, v192
	v_mul_f32_e32 v87, v87, v193
	v_fma_f32 v87, v185, v87, v189
	v_sub_f32_e32 v88, v88, v192
	v_mul_f32_e32 v88, v88, v193
	v_fma_f32 v88, v186, v88, v190
	v_sub_f32_e32 v89, v89, v192
	v_mul_f32_e32 v89, v89, v193
	v_fma_f32 v89, v187, v89, v191
	global_store_dwordx4 v137, v[86:89], s[94:95] offset:192
	ds_read_b128 v[184:187], v136 offset:320
	ds_read_b128 v[188:191], v136 offset:4416
	s_waitcnt lgkmcnt(2)
	v_sub_f32_e32 v82, v82, v192
	v_mul_f32_e32 v82, v82, v193
	v_fma_f32 v82, v176, v82, v180
	v_sub_f32_e32 v83, v83, v192
	v_mul_f32_e32 v83, v83, v193
	v_fma_f32 v83, v177, v83, v181
	v_sub_f32_e32 v84, v84, v192
	v_mul_f32_e32 v84, v84, v193
	v_fma_f32 v84, v178, v84, v182
	v_sub_f32_e32 v85, v85, v192
	v_mul_f32_e32 v85, v85, v193
	v_fma_f32 v85, v179, v85, v183
	global_store_dwordx4 v137, v[82:85], s[94:95] offset:256
	ds_read_b128 v[176:179], v136 offset:384
	ds_read_b128 v[180:183], v136 offset:4480
	s_waitcnt lgkmcnt(2)
	v_sub_f32_e32 v78, v78, v192
	v_mul_f32_e32 v78, v78, v193
	v_fma_f32 v78, v184, v78, v188
	v_sub_f32_e32 v79, v79, v192
	v_mul_f32_e32 v79, v79, v193
	v_fma_f32 v79, v185, v79, v189
	v_sub_f32_e32 v80, v80, v192
	v_mul_f32_e32 v80, v80, v193
	v_fma_f32 v80, v186, v80, v190
	v_sub_f32_e32 v81, v81, v192
	v_mul_f32_e32 v81, v81, v193
	v_fma_f32 v81, v187, v81, v191
	global_store_dwordx4 v137, v[78:81], s[94:95] offset:320
	ds_read_b128 v[184:187], v136 offset:448
	ds_read_b128 v[188:191], v136 offset:4544
	s_waitcnt lgkmcnt(2)
	v_sub_f32_e32 v74, v74, v192
	v_mul_f32_e32 v74, v74, v193
	v_fma_f32 v74, v176, v74, v180
	v_sub_f32_e32 v75, v75, v192
	v_mul_f32_e32 v75, v75, v193
	v_fma_f32 v75, v177, v75, v181
	v_sub_f32_e32 v76, v76, v192
	v_mul_f32_e32 v76, v76, v193
	v_fma_f32 v76, v178, v76, v182
	v_sub_f32_e32 v77, v77, v192
	v_mul_f32_e32 v77, v77, v193
	v_fma_f32 v77, v179, v77, v183
	global_store_dwordx4 v137, v[74:77], s[94:95] offset:384
	s_waitcnt lgkmcnt(0)
	v_sub_f32_e32 v70, v70, v192
	v_mul_f32_e32 v70, v70, v193
	v_fma_f32 v70, v184, v70, v188
	v_sub_f32_e32 v71, v71, v192
	v_mul_f32_e32 v71, v71, v193
	v_fma_f32 v71, v185, v71, v189
	v_sub_f32_e32 v72, v72, v192
	v_mul_f32_e32 v72, v72, v193
	v_fma_f32 v72, v186, v72, v190
	v_sub_f32_e32 v73, v73, v192
	v_mul_f32_e32 v73, v73, v193
	v_fma_f32 v73, v187, v73, v191
	global_store_dwordx4 v137, v[70:73], s[94:95] offset:448
	s_waitcnt vmcnt(12) lgkmcnt(0)
	s_barrier
; DI float bf2f(unsigned b) { return __uint_as_float(b << 16); }
; DI void unit_O(const Params& p, char* lds, int l, int tile, int glu_tiles, int tile_b) {
;     ...
;         float s2[2], ss2[2];
; #pragma unroll
;         for (int mh = 0; mh < 2; ++mh) {
;             const int mt = half * 2 + mh, rl = mh * 16 + l15;
;             float s = 0.f, ss = 0.f;
; #pragma unroll
;             for (int nt = 0; nt < 8; ++nt) {
;                 f32x4 xr;
;                 if (l == 0) {
;                     const int chunk = wid * 32 + nt * 4 + quad;
;                     xr = *(const f32x4*)(XR + rl * 4096 + ((chunk ^ l15) << 4));
;                 } else {
;                     const u32x2 hb = *(const u32x2*)(XR + ((wid * 4 + (nt >> 1)) * 32 + rl) * 64 + (nt & 1) * 32 + quad * 8);
;                     xr = (f32x4){bf2f(hb[0] & 0xffffu), bf2f(hb[0] >> 16), bf2f(hb[1] & 0xffffu), bf2f(hb[1] >> 16)};
;                 }
; #pragma unroll
;                 for (int i = 0; i < 4; ++i) { const float v = acc[mt][nt][i] + DN_ALPHA * xr[i]; acc[mt][nt][i] = v; s += v; ss += v * v; }
;             }
;             s2[mh] = s; ss2[mh] = ss;
;         }
; #pragma unroll
;         for (int mh = 0; mh < 2; ++mh) { s2[mh] += __shfl_xor(s2[mh], 16); ss2[mh] += __shfl_xor(ss2[mh], 16); }
; #pragma unroll
;         for (int mh = 0; mh < 2; ++mh) { s2[mh] += __shfl_xor(s2[mh], 32); ss2[mh] += __shfl_xor(ss2[mh], 32); }
;         if (quad == 0) {
; #pragma unroll
;             for (int mh = 0; mh < 2; ++mh) *(f32x2*)&red[((mh * 16 + l15) * 8 + wid) * 2] = (f32x2){s2[mh], ss2[mh]};
;         }
;         __syncthreads();
	ds_read_b64 v[180:181], v133 offset:32768
	ds_read_b64 v[182:183], v133 offset:32800
	ds_read_b64 v[184:185], v133 offset:33792
	ds_read_b64 v[186:187], v133 offset:33824
	ds_read_b64 v[188:189], v133 offset:34816
	ds_read_b64 v[190:191], v133 offset:34848
	ds_read_b64 v[192:193], v133 offset:35840
	ds_read_b64 v[194:195], v133 offset:35872
	s_waitcnt lgkmcnt(7)
	v_lshlrev_b32_e32 v144, 16, v180
	v_and_b32_e32 v145, 0xffff0000, v180
	v_lshlrev_b32_e32 v146, 16, v181
	v_and_b32_e32 v147, 0xffff0000, v181
	v_fmac_f32_e32 v126, s58, v144
	v_fmac_f32_e32 v127, s58, v145
	v_fmac_f32_e32 v128, s58, v146
	v_fmac_f32_e32 v129, s58, v147
	v_mov_b32_e32 v196, v126
	v_mul_f32_e32 v197, v126, v126
	v_mov_b32_e32 v130, v127
	v_mul_f32_e32 v142, v127, v127
	v_add_f32_e32 v196, v196, v128
	v_fmac_f32_e32 v197, v128, v128
	v_add_f32_e32 v130, v130, v129
	v_fmac_f32_e32 v142, v129, v129
	s_waitcnt lgkmcnt(6)
	v_lshlrev_b32_e32 v148, 16, v182
	v_and_b32_e32 v149, 0xffff0000, v182
	v_lshlrev_b32_e32 v150, 16, v183
	v_and_b32_e32 v151, 0xffff0000, v183
	v_fmac_f32_e32 v122, s58, v148
	v_fmac_f32_e32 v123, s58, v149
	v_fmac_f32_e32 v124, s58, v150
	v_fmac_f32_e32 v125, s58, v151
	v_add_f32_e32 v196, v196, v122
	v_fmac_f32_e32 v197, v122, v122
	v_add_f32_e32 v130, v130, v123
	v_fmac_f32_e32 v142, v123, v123
	v_add_f32_e32 v196, v196, v124
	v_fmac_f32_e32 v197, v124, v124
	v_add_f32_e32 v130, v130, v125
	v_fmac_f32_e32 v142, v125, v125
	s_waitcnt lgkmcnt(5)
	v_lshlrev_b32_e32 v152, 16, v184
	v_and_b32_e32 v153, 0xffff0000, v184
	v_lshlrev_b32_e32 v154, 16, v185
	v_and_b32_e32 v155, 0xffff0000, v185
	v_fmac_f32_e32 v118, s58, v152
	v_fmac_f32_e32 v119, s58, v153
	v_fmac_f32_e32 v120, s58, v154
	v_fmac_f32_e32 v121, s58, v155
	v_add_f32_e32 v196, v196, v118
	v_fmac_f32_e32 v197, v118, v118
	v_add_f32_e32 v130, v130, v119
	v_fmac_f32_e32 v142, v119, v119
	v_add_f32_e32 v196, v196, v120
	v_fmac_f32_e32 v197, v120, v120
	v_add_f32_e32 v130, v130, v121
	v_fmac_f32_e32 v142, v121, v121
	s_waitcnt lgkmcnt(4)
	v_lshlrev_b32_e32 v156, 16, v186
	v_and_b32_e32 v157, 0xffff0000, v186
	v_lshlrev_b32_e32 v158, 16, v187
	v_and_b32_e32 v159, 0xffff0000, v187
	v_fmac_f32_e32 v114, s58, v156
	v_fmac_f32_e32 v115, s58, v157
	v_fmac_f32_e32 v116, s58, v158
	v_fmac_f32_e32 v117, s58, v159
	v_add_f32_e32 v196, v196, v114
	v_fmac_f32_e32 v197, v114, v114
	v_add_f32_e32 v130, v130, v115
	v_fmac_f32_e32 v142, v115, v115
	v_add_f32_e32 v196, v196, v116
	v_fmac_f32_e32 v197, v116, v116
	v_add_f32_e32 v130, v130, v117
	v_fmac_f32_e32 v142, v117, v117
	s_waitcnt lgkmcnt(3)
	v_lshlrev_b32_e32 v160, 16, v188
	v_and_b32_e32 v161, 0xffff0000, v188
	v_lshlrev_b32_e32 v162, 16, v189
	v_and_b32_e32 v163, 0xffff0000, v189
	v_fmac_f32_e32 v110, s58, v160
	v_fmac_f32_e32 v111, s58, v161
	v_fmac_f32_e32 v112, s58, v162
	v_fmac_f32_e32 v113, s58, v163
	v_add_f32_e32 v196, v196, v110
	v_fmac_f32_e32 v197, v110, v110
	v_add_f32_e32 v130, v130, v111
	v_fmac_f32_e32 v142, v111, v111
	v_add_f32_e32 v196, v196, v112
	v_fmac_f32_e32 v197, v112, v112
	v_add_f32_e32 v130, v130, v113
	v_fmac_f32_e32 v142, v113, v113
	s_waitcnt lgkmcnt(2)
	v_lshlrev_b32_e32 v164, 16, v190
	v_and_b32_e32 v165, 0xffff0000, v190
	v_lshlrev_b32_e32 v166, 16, v191
	v_and_b32_e32 v167, 0xffff0000, v191
	v_fmac_f32_e32 v106, s58, v164
	v_fmac_f32_e32 v107, s58, v165
	v_fmac_f32_e32 v108, s58, v166
	v_fmac_f32_e32 v109, s58, v167
	v_add_f32_e32 v196, v196, v106
	v_fmac_f32_e32 v197, v106, v106
	v_add_f32_e32 v130, v130, v107
	v_fmac_f32_e32 v142, v107, v107
	v_add_f32_e32 v196, v196, v108
	v_fmac_f32_e32 v197, v108, v108
	v_add_f32_e32 v130, v130, v109
	v_fmac_f32_e32 v142, v109, v109
	s_waitcnt lgkmcnt(1)
	v_lshlrev_b32_e32 v168, 16, v192
	v_and_b32_e32 v169, 0xffff0000, v192
	v_lshlrev_b32_e32 v170, 16, v193
	v_and_b32_e32 v171, 0xffff0000, v193
	v_fmac_f32_e32 v102, s58, v168
	v_fmac_f32_e32 v103, s58, v169
	v_fmac_f32_e32 v104, s58, v170
	v_fmac_f32_e32 v105, s58, v171
	v_add_f32_e32 v196, v196, v102
	v_fmac_f32_e32 v197, v102, v102
	v_add_f32_e32 v130, v130, v103
	v_fmac_f32_e32 v142, v103, v103
	v_add_f32_e32 v196, v196, v104
	v_fmac_f32_e32 v197, v104, v104
	v_add_f32_e32 v130, v130, v105
	v_fmac_f32_e32 v142, v105, v105
	s_waitcnt lgkmcnt(0)
	v_lshlrev_b32_e32 v172, 16, v194
	v_and_b32_e32 v173, 0xffff0000, v194
	v_lshlrev_b32_e32 v174, 16, v195
	v_and_b32_e32 v175, 0xffff0000, v195
	v_fmac_f32_e32 v66, s58, v172
	v_fmac_f32_e32 v67, s58, v173
	v_fmac_f32_e32 v68, s58, v174
	v_fmac_f32_e32 v69, s58, v175
	v_add_f32_e32 v196, v196, v66
	v_fmac_f32_e32 v197, v66, v66
	v_add_f32_e32 v130, v130, v67
	v_fmac_f32_e32 v142, v67, v67
	v_add_f32_e32 v196, v196, v68
	v_fmac_f32_e32 v197, v68, v68
	v_add_f32_e32 v130, v130, v69
	v_fmac_f32_e32 v142, v69, v69
	v_add_f32_e32 v196, v196, v130
	v_add_f32_e32 v197, v197, v142
	v_mov_b32_e32 v198, v196
	v_mov_b32_e32 v199, v197
	s_nop 1
	v_permlane16_swap_b32 v198, v196
	v_permlane16_swap_b32 v199, v197
	v_add_f32_e32 v196, v196, v198
	v_add_f32_e32 v197, v197, v199
	v_mov_b32_e32 v198, v196
	v_mov_b32_e32 v199, v197
	s_nop 1
	v_permlane32_swap_b32 v198, v196
	v_permlane32_swap_b32 v199, v197
	v_add_f32_e32 v196, v196, v198
	v_add_f32_e32 v197, v197, v199
	s_mov_b64 exec, 0xffff
	ds_write_b64 v134, v[196:197]
	s_mov_b64 exec, -1
	s_waitcnt lgkmcnt(0)
	s_barrier
; DI unsigned pk2(float lo, float hi) { const f32x2 v = {lo, hi}; const bf16x2_t b = __builtin_convertvector(v, bf16x2_t); return __builtin_bit_cast(unsigned, b); }
; DI size_t xb_off(int tok, int col) { return ((size_t)(((tok >> 7) * 32 + (col >> 5)) * 128 + (tok & 127))) * 32 + (col & 31); }
; DI void unit_O(const Params& p, char* lds, int l, int tile, int glu_tiles, int tile_b) {
;     ...
;         if (half == 0) issue_x(1);
; #pragma unroll
;         for (int mh = 0; mh < 2; ++mh) {
;             const int mt = half * 2 + mh, rl = mh * 16 + l15, row = mt * 16 + l15;
;             float s = 0.f, ss = 0.f;
; #pragma unroll
;             for (int w = 0; w < 4; ++w) { const f32x4 v = *(const f32x4*)&red[rl * 16 + 4 * w]; s += v[0] + v[2]; ss += v[1] + v[3]; }
;             const float mu = s * (1.f / 1024.f);
;             const float var = ss * (1.f / 1024.f) - mu * mu;
;             const float rs = rsqrtf(var + LN_EPS);
;             float* orow = xo + (r0 + row) * 1024 + wid * 128 + quad * 4;
;             bf16_t* brow = xbo + xb_off((int)r0 + row, wid * 128) + quad * 4;
;             const float* gp = GB + wid * 128 + quad * 4;
; #pragma unroll
;             for (int nt = 0; nt < 8; ++nt) {
;                 const f32x4 g = *(const f32x4*)(gp + nt * 16), bb = *(const f32x4*)(gp + 1024 + nt * 16);
;                 f32x4 o;
; #pragma unroll
;                 for (int i = 0; i < 4; ++i) o[i] = (acc[mt][nt][i] - mu) * rs * g[i] + bb[i];
;                 if (l == 0) *(u32x2*)(brow + (nt >> 1) * 4096 + (nt & 1) * 16) = (u32x2){pk2(o[0], o[1]), pk2(o[2], o[3])};
;                 else *(f32x4*)(orow + nt * 16) = o;
	s_add_u32 s92, s96, 0xc00
	s_addc_u32 s93, s97, 0
	s_add_u32 s40, s91, 0x8000
	s_mov_b32 m0, s40
	s_nop 0
	global_load_lds_dwordx4 v131, s[92:93]
	s_add_u32 s92, s92, 0x2000
	s_addc_u32 s93, s93, 0
	s_add_u32 m0, m0, 0x400
	s_nop 0
	global_load_lds_dwordx4 v131, s[92:93]
	s_add_u32 s92, s92, 0x2000
	s_addc_u32 s93, s93, 0
	s_add_u32 m0, m0, 0x400
	s_nop 0
	global_load_lds_dwordx4 v131, s[92:93]
	s_add_u32 s92, s92, 0x2000
	s_addc_u32 s93, s93, 0
	s_add_u32 m0, m0, 0x400
	s_nop 0
	global_load_lds_dwordx4 v131, s[92:93]
	ds_read_b128 v[160:163], v135 offset:0
	ds_read_b128 v[164:167], v135 offset:16
	ds_read_b128 v[168:171], v135 offset:32
	ds_read_b128 v[172:175], v135 offset:48
	s_waitcnt lgkmcnt(0)
	v_add_f32_e32 v160, v160, v162
	v_add_f32_e32 v161, v161, v163
	v_add_f32_e32 v164, v164, v166
	v_add_f32_e32 v165, v165, v167
	v_add_f32_e32 v168, v168, v170
	v_add_f32_e32 v169, v169, v171
	v_add_f32_e32 v172, v172, v174
	v_add_f32_e32 v173, v173, v175
	v_add_f32_e32 v160, v160, v164
	v_add_f32_e32 v161, v161, v165
	v_add_f32_e32 v168, v168, v172
	v_add_f32_e32 v169, v169, v173
	v_add_f32_e32 v160, v160, v168
	v_add_f32_e32 v161, v161, v169
	v_mul_f32_e32 v192, 0x3a800000, v160
	v_mul_f32_e32 v193, 0x3a800000, v161
	v_fma_f32 v193, -v192, v192, v193
	v_add_f32_e32 v193, 0x3727c5ac, v193
	v_rsq_f32_e32 v193, v193
	s_nop 0
	s_add_u32 s94, s78, 0x10000
	s_addc_u32 s95, s79, 0
	ds_read_b128 v[176:179], v136
	ds_read_b128 v[180:183], v136 offset:4096
	ds_read_b128 v[184:187], v136 offset:64
	ds_read_b128 v[188:191], v136 offset:4160
	s_waitcnt lgkmcnt(2)
	v_sub_f32_e32 v126, v126, v192
	v_mul_f32_e32 v126, v126, v193
	v_fma_f32 v126, v176, v126, v180
	v_sub_f32_e32 v127, v127, v192
	v_mul_f32_e32 v127, v127, v193
	v_fma_f32 v127, v177, v127, v181
	v_sub_f32_e32 v128, v128, v192
	v_mul_f32_e32 v128, v128, v193
	v_fma_f32 v128, v178, v128, v182
	v_sub_f32_e32 v129, v129, v192
	v_mul_f32_e32 v129, v129, v193
	v_fma_f32 v129, v179, v129, v183
	global_store_dwordx4 v137, v[126:129], s[94:95]
	ds_read_b128 v[176:179], v136 offset:128
	ds_read_b128 v[180:183], v136 offset:4224
	s_waitcnt lgkmcnt(2)
	v_sub_f32_e32 v122, v122, v192
	v_mul_f32_e32 v122, v122, v193
	v_fma_f32 v122, v184, v122, v188
	v_sub_f32_e32 v123, v123, v192
	v_mul_f32_e32 v123, v123, v193
	v_fma_f32 v123, v185, v123, v189
	v_sub_f32_e32 v124, v124, v192
	v_mul_f32_e32 v124, v124, v193
	v_fma_f32 v124, v186, v124, v190
	v_sub_f32_e32 v125, v125, v192
	v_mul_f32_e32 v125, v125, v193
	v_fma_f32 v125, v187, v125, v191
	global_store_dwordx4 v137, v[122:125], s[94:95] offset:64
	ds_read_b128 v[184:187], v136 offset:192
	ds_read_b128 v[188:191], v136 offset:4288
	s_waitcnt lgkmcnt(2)
	v_sub_f32_e32 v118, v118, v192
	v_mul_f32_e32 v118, v118, v193
	v_fma_f32 v118, v176, v118, v180
	v_sub_f32_e32 v119, v119, v192
	v_mul_f32_e32 v119, v119, v193
	v_fma_f32 v119, v177, v119, v181
	v_sub_f32_e32 v120, v120, v192
	v_mul_f32_e32 v120, v120, v193
	v_fma_f32 v120, v178, v120, v182
	v_sub_f32_e32 v121, v121, v192
	v_mul_f32_e32 v121, v121, v193
	v_fma_f32 v121, v179, v121, v183
	global_store_dwordx4 v137, v[118:121], s[94:95] offset:128
	ds_read_b128 v[176:179], v136 offset:256
	ds_read_b128 v[180:183], v136 offset:4352
	s_waitcnt lgkmcnt(2)
	v_sub_f32_e32 v114, v114, v192
	v_mul_f32_e32 v114, v114, v193
	v_fma_f32 v114, v184, v114, v188
	v_sub_f32_e32 v115, v115, v192
	v_mul_f32_e32 v115, v115, v193
	v_fma_f32 v115, v185, v115, v189
	v_sub_f32_e32 v116, v116, v192
	v_mul_f32_e32 v116, v116, v193
	v_fma_f32 v116, v186, v116, v190
	v_sub_f32_e32 v117, v117, v192
	v_mul_f32_e32 v117, v117, v193
	v_fma_f32 v117, v187, v117, v191
	global_store_dwordx4 v137, v[114:117], s[94:95] offset:192
	ds_read_b128 v[184:187], v136 offset:320
	ds_read_b128 v[188:191], v136 offset:4416
	s_waitcnt lgkmcnt(2)
	v_sub_f32_e32 v110, v110, v192
	v_mul_f32_e32 v110, v110, v193
	v_fma_f32 v110, v176, v110, v180
	v_sub_f32_e32 v111, v111, v192
	v_mul_f32_e32 v111, v111, v193
	v_fma_f32 v111, v177, v111, v181
	v_sub_f32_e32 v112, v112, v192
	v_mul_f32_e32 v112, v112, v193
	v_fma_f32 v112, v178, v112, v182
	v_sub_f32_e32 v113, v113, v192
	v_mul_f32_e32 v113, v113, v193
	v_fma_f32 v113, v179, v113, v183
	global_store_dwordx4 v137, v[110:113], s[94:95] offset:256
	ds_read_b128 v[176:179], v136 offset:384
	ds_read_b128 v[180:183], v136 offset:4480
	s_waitcnt lgkmcnt(2)
	v_sub_f32_e32 v106, v106, v192
	v_mul_f32_e32 v106, v106, v193
	v_fma_f32 v106, v184, v106, v188
	v_sub_f32_e32 v107, v107, v192
	v_mul_f32_e32 v107, v107, v193
	v_fma_f32 v107, v185, v107, v189
	v_sub_f32_e32 v108, v108, v192
	v_mul_f32_e32 v108, v108, v193
	v_fma_f32 v108, v186, v108, v190
	v_sub_f32_e32 v109, v109, v192
	v_mul_f32_e32 v109, v109, v193
	v_fma_f32 v109, v187, v109, v191
	global_store_dwordx4 v137, v[106:109], s[94:95] offset:320
	ds_read_b128 v[184:187], v136 offset:448
	ds_read_b128 v[188:191], v136 offset:4544
	s_waitcnt lgkmcnt(2)
	v_sub_f32_e32 v102, v102, v192
	v_mul_f32_e32 v102, v102, v193
	v_fma_f32 v102, v176, v102, v180
	v_sub_f32_e32 v103, v103, v192
	v_mul_f32_e32 v103, v103, v193
	v_fma_f32 v103, v177, v103, v181
	v_sub_f32_e32 v104, v104, v192
	v_mul_f32_e32 v104, v104, v193
	v_fma_f32 v104, v178, v104, v182
	v_sub_f32_e32 v105, v105, v192
	v_mul_f32_e32 v105, v105, v193
	v_fma_f32 v105, v179, v105, v183
	global_store_dwordx4 v137, v[102:105], s[94:95] offset:384
	s_waitcnt lgkmcnt(0)
	v_sub_f32_e32 v66, v66, v192
	v_mul_f32_e32 v66, v66, v193
	v_fma_f32 v66, v184, v66, v188
	v_sub_f32_e32 v67, v67, v192
	v_mul_f32_e32 v67, v67, v193
	v_fma_f32 v67, v185, v67, v189
	v_sub_f32_e32 v68, v68, v192
	v_mul_f32_e32 v68, v68, v193
	v_fma_f32 v68, v186, v68, v190
	v_sub_f32_e32 v69, v69, v192
	v_mul_f32_e32 v69, v69, v193
	v_fma_f32 v69, v187, v69, v191
	global_store_dwordx4 v137, v[66:69], s[94:95] offset:448
	s_waitcnt vmcnt(20) lgkmcnt(0)
	s_barrier
; DI float bf2f(unsigned b) { return __uint_as_float(b << 16); }
; DI void unit_O(const Params& p, char* lds, int l, int tile, int glu_tiles, int tile_b) {
;     ...
;         float s2[2], ss2[2];
; #pragma unroll
;         for (int mh = 0; mh < 2; ++mh) {
;             const int mt = half * 2 + mh, rl = mh * 16 + l15;
;             float s = 0.f, ss = 0.f;
; #pragma unroll
;             for (int nt = 0; nt < 8; ++nt) {
;                 f32x4 xr;
;                 if (l == 0) {
;                     const int chunk = wid * 32 + nt * 4 + quad;
;                     xr = *(const f32x4*)(XR + rl * 4096 + ((chunk ^ l15) << 4));
;                 } else {
;                     const u32x2 hb = *(const u32x2*)(XR + ((wid * 4 + (nt >> 1)) * 32 + rl) * 64 + (nt & 1) * 32 + quad * 8);
;                     xr = (f32x4){bf2f(hb[0] & 0xffffu), bf2f(hb[0] >> 16), bf2f(hb[1] & 0xffffu), bf2f(hb[1] >> 16)};
;                 }
; #pragma unroll
;                 for (int i = 0; i < 4; ++i) { const float v = acc[mt][nt][i] + DN_ALPHA * xr[i]; acc[mt][nt][i] = v; s += v; ss += v * v; }
;             }
;             s2[mh] = s; ss2[mh] = ss;
;         }
; #pragma unroll
;         for (int mh = 0; mh < 2; ++mh) { s2[mh] += __shfl_xor(s2[mh], 16); ss2[mh] += __shfl_xor(ss2[mh], 16); }
; #pragma unroll
;         for (int mh = 0; mh < 2; ++mh) { s2[mh] += __shfl_xor(s2[mh], 32); ss2[mh] += __shfl_xor(ss2[mh], 32); }
;         if (quad == 0) {
; #pragma unroll
;             for (int mh = 0; mh < 2; ++mh) *(f32x2*)&red[((mh * 16 + l15) * 8 + wid) * 2] = (f32x2){s2[mh], ss2[mh]};
;         }
;         __syncthreads();
	ds_read_b64 v[180:181], v133 offset:0
	ds_read_b64 v[182:183], v133 offset:32
	ds_read_b64 v[184:185], v133 offset:1024
	ds_read_b64 v[186:187], v133 offset:1056
	ds_read_b64 v[188:189], v133 offset:2048
	ds_read_b64 v[190:191], v133 offset:2080
	ds_read_b64 v[192:193], v133 offset:3072
	ds_read_b64 v[194:195], v133 offset:3104
	s_waitcnt lgkmcnt(7)
	v_lshlrev_b32_e32 v144, 16, v180
	v_and_b32_e32 v145, 0xffff0000, v180
	v_lshlrev_b32_e32 v146, 16, v181
	v_and_b32_e32 v147, 0xffff0000, v181
	v_fmac_f32_e32 v34, s58, v144
	v_fmac_f32_e32 v35, s58, v145
	v_fmac_f32_e32 v36, s58, v146
	v_fmac_f32_e32 v37, s58, v147
	v_mov_b32_e32 v196, v34
	v_mul_f32_e32 v197, v34, v34
	v_mov_b32_e32 v130, v35
	v_mul_f32_e32 v142, v35, v35
	v_add_f32_e32 v196, v196, v36
	v_fmac_f32_e32 v197, v36, v36
	v_add_f32_e32 v130, v130, v37
	v_fmac_f32_e32 v142, v37, v37
	s_waitcnt lgkmcnt(6)
	v_lshlrev_b32_e32 v148, 16, v182
	v_and_b32_e32 v149, 0xffff0000, v182
	v_lshlrev_b32_e32 v150, 16, v183
	v_and_b32_e32 v151, 0xffff0000, v183
	v_fmac_f32_e32 v30, s58, v148
	v_fmac_f32_e32 v31, s58, v149
	v_fmac_f32_e32 v32, s58, v150
	v_fmac_f32_e32 v33, s58, v151
	v_add_f32_e32 v196, v196, v30
	v_fmac_f32_e32 v197, v30, v30
	v_add_f32_e32 v130, v130, v31
	v_fmac_f32_e32 v142, v31, v31
	v_add_f32_e32 v196, v196, v32
	v_fmac_f32_e32 v197, v32, v32
	v_add_f32_e32 v130, v130, v33
	v_fmac_f32_e32 v142, v33, v33
	s_waitcnt lgkmcnt(5)
	v_lshlrev_b32_e32 v152, 16, v184
	v_and_b32_e32 v153, 0xffff0000, v184
	v_lshlrev_b32_e32 v154, 16, v185
	v_and_b32_e32 v155, 0xffff0000, v185
	v_fmac_f32_e32 v26, s58, v152
	v_fmac_f32_e32 v27, s58, v153
	v_fmac_f32_e32 v28, s58, v154
	v_fmac_f32_e32 v29, s58, v155
	v_add_f32_e32 v196, v196, v26
	v_fmac_f32_e32 v197, v26, v26
	v_add_f32_e32 v130, v130, v27
	v_fmac_f32_e32 v142, v27, v27
	v_add_f32_e32 v196, v196, v28
	v_fmac_f32_e32 v197, v28, v28
	v_add_f32_e32 v130, v130, v29
	v_fmac_f32_e32 v142, v29, v29
	s_waitcnt lgkmcnt(4)
	v_lshlrev_b32_e32 v156, 16, v186
	v_and_b32_e32 v157, 0xffff0000, v186
	v_lshlrev_b32_e32 v158, 16, v187
	v_and_b32_e32 v159, 0xffff0000, v187
	v_fmac_f32_e32 v22, s58, v156
	v_fmac_f32_e32 v23, s58, v157
	v_fmac_f32_e32 v24, s58, v158
	v_fmac_f32_e32 v25, s58, v159
	v_add_f32_e32 v196, v196, v22
	v_fmac_f32_e32 v197, v22, v22
	v_add_f32_e32 v130, v130, v23
	v_fmac_f32_e32 v142, v23, v23
	v_add_f32_e32 v196, v196, v24
	v_fmac_f32_e32 v197, v24, v24
	v_add_f32_e32 v130, v130, v25
	v_fmac_f32_e32 v142, v25, v25
	s_waitcnt lgkmcnt(3)
	v_lshlrev_b32_e32 v160, 16, v188
	v_and_b32_e32 v161, 0xffff0000, v188
	v_lshlrev_b32_e32 v162, 16, v189
	v_and_b32_e32 v163, 0xffff0000, v189
	v_fmac_f32_e32 v18, s58, v160
	v_fmac_f32_e32 v19, s58, v161
	v_fmac_f32_e32 v20, s58, v162
	v_fmac_f32_e32 v21, s58, v163
	v_add_f32_e32 v196, v196, v18
	v_fmac_f32_e32 v197, v18, v18
	v_add_f32_e32 v130, v130, v19
	v_fmac_f32_e32 v142, v19, v19
	v_add_f32_e32 v196, v196, v20
	v_fmac_f32_e32 v197, v20, v20
	v_add_f32_e32 v130, v130, v21
	v_fmac_f32_e32 v142, v21, v21
	s_waitcnt lgkmcnt(2)
	v_lshlrev_b32_e32 v164, 16, v190
	v_and_b32_e32 v165, 0xffff0000, v190
	v_lshlrev_b32_e32 v166, 16, v191
	v_and_b32_e32 v167, 0xffff0000, v191
	v_fmac_f32_e32 v14, s58, v164
	v_fmac_f32_e32 v15, s58, v165
	v_fmac_f32_e32 v16, s58, v166
	v_fmac_f32_e32 v17, s58, v167
	v_add_f32_e32 v196, v196, v14
	v_fmac_f32_e32 v197, v14, v14
	v_add_f32_e32 v130, v130, v15
	v_fmac_f32_e32 v142, v15, v15
	v_add_f32_e32 v196, v196, v16
	v_fmac_f32_e32 v197, v16, v16
	v_add_f32_e32 v130, v130, v17
	v_fmac_f32_e32 v142, v17, v17
	s_waitcnt lgkmcnt(1)
	v_lshlrev_b32_e32 v168, 16, v192
	v_and_b32_e32 v169, 0xffff0000, v192
	v_lshlrev_b32_e32 v170, 16, v193
	v_and_b32_e32 v171, 0xffff0000, v193
	v_fmac_f32_e32 v10, s58, v168
	v_fmac_f32_e32 v11, s58, v169
	v_fmac_f32_e32 v12, s58, v170
	v_fmac_f32_e32 v13, s58, v171
	v_add_f32_e32 v196, v196, v10
	v_fmac_f32_e32 v197, v10, v10
	v_add_f32_e32 v130, v130, v11
	v_fmac_f32_e32 v142, v11, v11
	v_add_f32_e32 v196, v196, v12
	v_fmac_f32_e32 v197, v12, v12
	v_add_f32_e32 v130, v130, v13
	v_fmac_f32_e32 v142, v13, v13
	s_waitcnt lgkmcnt(0)
	v_lshlrev_b32_e32 v172, 16, v194
	v_and_b32_e32 v173, 0xffff0000, v194
	v_lshlrev_b32_e32 v174, 16, v195
	v_and_b32_e32 v175, 0xffff0000, v195
	v_fmac_f32_e32 v6, s58, v172
	v_fmac_f32_e32 v7, s58, v173
	v_fmac_f32_e32 v8, s58, v174
	v_fmac_f32_e32 v9, s58, v175
	v_add_f32_e32 v196, v196, v6
	v_fmac_f32_e32 v197, v6, v6
	v_add_f32_e32 v130, v130, v7
	v_fmac_f32_e32 v142, v7, v7
	v_add_f32_e32 v196, v196, v8
	v_fmac_f32_e32 v197, v8, v8
	v_add_f32_e32 v130, v130, v9
	v_fmac_f32_e32 v142, v9, v9
	v_add_f32_e32 v196, v196, v130
	v_add_f32_e32 v197, v197, v142
	v_mov_b32_e32 v198, v196
	v_mov_b32_e32 v199, v197
	s_nop 1
	v_permlane16_swap_b32 v198, v196
	v_permlane16_swap_b32 v199, v197
	v_add_f32_e32 v196, v196, v198
	v_add_f32_e32 v197, v197, v199
	v_mov_b32_e32 v198, v196
	v_mov_b32_e32 v199, v197
	s_nop 1
	v_permlane32_swap_b32 v198, v196
	v_permlane32_swap_b32 v199, v197
	v_add_f32_e32 v196, v196, v198
	v_add_f32_e32 v197, v197, v199
	s_mov_b64 exec, 0xffff
	ds_write_b64 v134, v[196:197]
	s_mov_b64 exec, -1
	s_waitcnt lgkmcnt(0)
	s_barrier
; DI unsigned pk2(float lo, float hi) { const f32x2 v = {lo, hi}; const bf16x2_t b = __builtin_convertvector(v, bf16x2_t); return __builtin_bit_cast(unsigned, b); }
; DI size_t xb_off(int tok, int col) { return ((size_t)(((tok >> 7) * 32 + (col >> 5)) * 128 + (tok & 127))) * 32 + (col & 31); }
; DI void unit_O(const Params& p, char* lds, int l, int tile, int glu_tiles, int tile_b) {
;     ...
;         for (int mh = 0; mh < 2; ++mh) {
;             const int mt = half * 2 + mh, rl = mh * 16 + l15, row = mt * 16 + l15;
;             float s = 0.f, ss = 0.f;
; #pragma unroll
;             for (int w = 0; w < 4; ++w) { const f32x4 v = *(const f32x4*)&red[rl * 16 + 4 * w]; s += v[0] + v[2]; ss += v[1] + v[3]; }
;             const float mu = s * (1.f / 1024.f);
;             const float var = ss * (1.f / 1024.f) - mu * mu;
;             const float rs = rsqrtf(var + LN_EPS);
;             float* orow = xo + (r0 + row) * 1024 + wid * 128 + quad * 4;
;             bf16_t* brow = xbo + xb_off((int)r0 + row, wid * 128) + quad * 4;
;             const float* gp = GB + wid * 128 + quad * 4;
; #pragma unroll
;             for (int nt = 0; nt < 8; ++nt) {
;                 const f32x4 g = *(const f32x4*)(gp + nt * 16), bb = *(const f32x4*)(gp + 1024 + nt * 16);
;                 f32x4 o;
; #pragma unroll
;                 for (int i = 0; i < 4; ++i) o[i] = (acc[mt][nt][i] - mu) * rs * g[i] + bb[i];
;                 if (l == 0) *(u32x2*)(brow + (nt >> 1) * 4096 + (nt & 1) * 16) = (u32x2){pk2(o[0], o[1]), pk2(o[2], o[3])};
;                 else *(f32x4*)(orow + nt * 16) = o;
	ds_read_b128 v[160:163], v135 offset:0
	ds_read_b128 v[164:167], v135 offset:16
	ds_read_b128 v[168:171], v135 offset:32
	ds_read_b128 v[172:175], v135 offset:48
	s_waitcnt lgkmcnt(0)
	v_add_f32_e32 v160, v160, v162
	v_add_f32_e32 v161, v161, v163
	v_add_f32_e32 v164, v164, v166
	v_add_f32_e32 v165, v165, v167
	v_add_f32_e32 v168, v168, v170
	v_add_f32_e32 v169, v169, v171
	v_add_f32_e32 v172, v172, v174
	v_add_f32_e32 v173, v173, v175
	v_add_f32_e32 v160, v160, v164
	v_add_f32_e32 v161, v161, v165
	v_add_f32_e32 v168, v168, v172
	v_add_f32_e32 v169, v169, v173
	v_add_f32_e32 v160, v160, v168
	v_add_f32_e32 v161, v161, v169
	v_mul_f32_e32 v192, 0x3a800000, v160
	v_mul_f32_e32 v193, 0x3a800000, v161
	v_fma_f32 v193, -v192, v192, v193
	v_add_f32_e32 v193, 0x3727c5ac, v193
	v_rsq_f32_e32 v193, v193
	s_nop 0
	s_add_u32 s94, s78, 0x20000
	s_addc_u32 s95, s79, 0
	ds_read_b128 v[176:179], v136
	ds_read_b128 v[180:183], v136 offset:4096
	ds_read_b128 v[184:187], v136 offset:64
	ds_read_b128 v[188:191], v136 offset:4160
	s_waitcnt lgkmcnt(2)
	v_sub_f32_e32 v34, v34, v192
	v_mul_f32_e32 v34, v34, v193
	v_fma_f32 v34, v176, v34, v180
	v_sub_f32_e32 v35, v35, v192
	v_mul_f32_e32 v35, v35, v193
	v_fma_f32 v35, v177, v35, v181
	v_sub_f32_e32 v36, v36, v192
	v_mul_f32_e32 v36, v36, v193
	v_fma_f32 v36, v178, v36, v182
	v_sub_f32_e32 v37, v37, v192
	v_mul_f32_e32 v37, v37, v193
	v_fma_f32 v37, v179, v37, v183
	global_store_dwordx4 v137, v[34:37], s[94:95]
	ds_read_b128 v[176:179], v136 offset:128
	ds_read_b128 v[180:183], v136 offset:4224
	s_waitcnt lgkmcnt(2)
	v_sub_f32_e32 v30, v30, v192
	v_mul_f32_e32 v30, v30, v193
	v_fma_f32 v30, v184, v30, v188
	v_sub_f32_e32 v31, v31, v192
	v_mul_f32_e32 v31, v31, v193
	v_fma_f32 v31, v185, v31, v189
	v_sub_f32_e32 v32, v32, v192
	v_mul_f32_e32 v32, v32, v193
	v_fma_f32 v32, v186, v32, v190
	v_sub_f32_e32 v33, v33, v192
	v_mul_f32_e32 v33, v33, v193
	v_fma_f32 v33, v187, v33, v191
	global_store_dwordx4 v137, v[30:33], s[94:95] offset:64
	ds_read_b128 v[184:187], v136 offset:192
	ds_read_b128 v[188:191], v136 offset:4288
	s_waitcnt lgkmcnt(2)
	v_sub_f32_e32 v26, v26, v192
	v_mul_f32_e32 v26, v26, v193
	v_fma_f32 v26, v176, v26, v180
	v_sub_f32_e32 v27, v27, v192
	v_mul_f32_e32 v27, v27, v193
	v_fma_f32 v27, v177, v27, v181
	v_sub_f32_e32 v28, v28, v192
	v_mul_f32_e32 v28, v28, v193
	v_fma_f32 v28, v178, v28, v182
	v_sub_f32_e32 v29, v29, v192
	v_mul_f32_e32 v29, v29, v193
	v_fma_f32 v29, v179, v29, v183
	global_store_dwordx4 v137, v[26:29], s[94:95] offset:128
	ds_read_b128 v[176:179], v136 offset:256
	ds_read_b128 v[180:183], v136 offset:4352
	s_waitcnt lgkmcnt(2)
	v_sub_f32_e32 v22, v22, v192
	v_mul_f32_e32 v22, v22, v193
	v_fma_f32 v22, v184, v22, v188
	v_sub_f32_e32 v23, v23, v192
	v_mul_f32_e32 v23, v23, v193
	v_fma_f32 v23, v185, v23, v189
	v_sub_f32_e32 v24, v24, v192
	v_mul_f32_e32 v24, v24, v193
	v_fma_f32 v24, v186, v24, v190
	v_sub_f32_e32 v25, v25, v192
	v_mul_f32_e32 v25, v25, v193
	v_fma_f32 v25, v187, v25, v191
	global_store_dwordx4 v137, v[22:25], s[94:95] offset:192
	ds_read_b128 v[184:187], v136 offset:320
	ds_read_b128 v[188:191], v136 offset:4416
	s_waitcnt lgkmcnt(2)
	v_sub_f32_e32 v18, v18, v192
	v_mul_f32_e32 v18, v18, v193
	v_fma_f32 v18, v176, v18, v180
	v_sub_f32_e32 v19, v19, v192
	v_mul_f32_e32 v19, v19, v193
	v_fma_f32 v19, v177, v19, v181
	v_sub_f32_e32 v20, v20, v192
	v_mul_f32_e32 v20, v20, v193
	v_fma_f32 v20, v178, v20, v182
	v_sub_f32_e32 v21, v21, v192
	v_mul_f32_e32 v21, v21, v193
	v_fma_f32 v21, v179, v21, v183
	global_store_dwordx4 v137, v[18:21], s[94:95] offset:256
	ds_read_b128 v[176:179], v136 offset:384
	ds_read_b128 v[180:183], v136 offset:4480
	s_waitcnt lgkmcnt(2)
	v_sub_f32_e32 v14, v14, v192
	v_mul_f32_e32 v14, v14, v193
	v_fma_f32 v14, v184, v14, v188
	v_sub_f32_e32 v15, v15, v192
	v_mul_f32_e32 v15, v15, v193
	v_fma_f32 v15, v185, v15, v189
	v_sub_f32_e32 v16, v16, v192
	v_mul_f32_e32 v16, v16, v193
	v_fma_f32 v16, v186, v16, v190
	v_sub_f32_e32 v17, v17, v192
	v_mul_f32_e32 v17, v17, v193
	v_fma_f32 v17, v187, v17, v191
	global_store_dwordx4 v137, v[14:17], s[94:95] offset:320
	ds_read_b128 v[184:187], v136 offset:448
	ds_read_b128 v[188:191], v136 offset:4544
	s_waitcnt lgkmcnt(2)
	v_sub_f32_e32 v10, v10, v192
	v_mul_f32_e32 v10, v10, v193
	v_fma_f32 v10, v176, v10, v180
	v_sub_f32_e32 v11, v11, v192
	v_mul_f32_e32 v11, v11, v193
	v_fma_f32 v11, v177, v11, v181
	v_sub_f32_e32 v12, v12, v192
	v_mul_f32_e32 v12, v12, v193
	v_fma_f32 v12, v178, v12, v182
	v_sub_f32_e32 v13, v13, v192
	v_mul_f32_e32 v13, v13, v193
	v_fma_f32 v13, v179, v13, v183
	global_store_dwordx4 v137, v[10:13], s[94:95] offset:384
	s_waitcnt lgkmcnt(0)
	v_sub_f32_e32 v6, v6, v192
	v_mul_f32_e32 v6, v6, v193
	v_fma_f32 v6, v184, v6, v188
	v_sub_f32_e32 v7, v7, v192
	v_mul_f32_e32 v7, v7, v193
	v_fma_f32 v7, v185, v7, v189
	v_sub_f32_e32 v8, v8, v192
	v_mul_f32_e32 v8, v8, v193
	v_fma_f32 v8, v186, v8, v190
	v_sub_f32_e32 v9, v9, v192
	v_mul_f32_e32 v9, v9, v193
	v_fma_f32 v9, v187, v9, v191
	global_store_dwordx4 v137, v[6:9], s[94:95] offset:448
	s_waitcnt vmcnt(16) lgkmcnt(0)
	s_barrier
; DI float bf2f(unsigned b) { return __uint_as_float(b << 16); }
; DI void unit_O(const Params& p, char* lds, int l, int tile, int glu_tiles, int tile_b) {
;     ...
;         float s2[2], ss2[2];
; #pragma unroll
;         for (int mh = 0; mh < 2; ++mh) {
;             const int mt = half * 2 + mh, rl = mh * 16 + l15;
;             float s = 0.f, ss = 0.f;
; #pragma unroll
;             for (int nt = 0; nt < 8; ++nt) {
;                 f32x4 xr;
;                 if (l == 0) {
;                     const int chunk = wid * 32 + nt * 4 + quad;
;                     xr = *(const f32x4*)(XR + rl * 4096 + ((chunk ^ l15) << 4));
;                 } else {
;                     const u32x2 hb = *(const u32x2*)(XR + ((wid * 4 + (nt >> 1)) * 32 + rl) * 64 + (nt & 1) * 32 + quad * 8);
;                     xr = (f32x4){bf2f(hb[0] & 0xffffu), bf2f(hb[0] >> 16), bf2f(hb[1] & 0xffffu), bf2f(hb[1] >> 16)};
;                 }
; #pragma unroll
;                 for (int i = 0; i < 4; ++i) { const float v = acc[mt][nt][i] + DN_ALPHA * xr[i]; acc[mt][nt][i] = v; s += v; ss += v * v; }
;             }
;             s2[mh] = s; ss2[mh] = ss;
;         }
; #pragma unroll
;         for (int mh = 0; mh < 2; ++mh) { s2[mh] += __shfl_xor(s2[mh], 16); ss2[mh] += __shfl_xor(ss2[mh], 16); }
; #pragma unroll
;         for (int mh = 0; mh < 2; ++mh) { s2[mh] += __shfl_xor(s2[mh], 32); ss2[mh] += __shfl_xor(ss2[mh], 32); }
;         if (quad == 0) {
; #pragma unroll
;             for (int mh = 0; mh < 2; ++mh) *(f32x2*)&red[((mh * 16 + l15) * 8 + wid) * 2] = (f32x2){s2[mh], ss2[mh]};
;         }
;         __syncthreads();
	ds_read_b64 v[180:181], v133 offset:32768
	ds_read_b64 v[182:183], v133 offset:32800
	ds_read_b64 v[184:185], v133 offset:33792
	ds_read_b64 v[186:187], v133 offset:33824
	ds_read_b64 v[188:189], v133 offset:34816
	ds_read_b64 v[190:191], v133 offset:34848
	ds_read_b64 v[192:193], v133 offset:35840
	ds_read_b64 v[194:195], v133 offset:35872
	s_waitcnt lgkmcnt(7)
	v_lshlrev_b32_e32 v144, 16, v180
	v_and_b32_e32 v145, 0xffff0000, v180
	v_lshlrev_b32_e32 v146, 16, v181
	v_and_b32_e32 v147, 0xffff0000, v181
	v_fmac_f32_e32 v62, s58, v144
	v_fmac_f32_e32 v63, s58, v145
	v_fmac_f32_e32 v64, s58, v146
	v_fmac_f32_e32 v65, s58, v147
	v_mov_b32_e32 v196, v62
	v_mul_f32_e32 v197, v62, v62
	v_mov_b32_e32 v130, v63
	v_mul_f32_e32 v142, v63, v63
	v_add_f32_e32 v196, v196, v64
	v_fmac_f32_e32 v197, v64, v64
	v_add_f32_e32 v130, v130, v65
	v_fmac_f32_e32 v142, v65, v65
	s_waitcnt lgkmcnt(6)
	v_lshlrev_b32_e32 v148, 16, v182
	v_and_b32_e32 v149, 0xffff0000, v182
	v_lshlrev_b32_e32 v150, 16, v183
	v_and_b32_e32 v151, 0xffff0000, v183
	v_fmac_f32_e32 v58, s58, v148
	v_fmac_f32_e32 v59, s58, v149
	v_fmac_f32_e32 v60, s58, v150
	v_fmac_f32_e32 v61, s58, v151
	v_add_f32_e32 v196, v196, v58
	v_fmac_f32_e32 v197, v58, v58
	v_add_f32_e32 v130, v130, v59
	v_fmac_f32_e32 v142, v59, v59
	v_add_f32_e32 v196, v196, v60
	v_fmac_f32_e32 v197, v60, v60
	v_add_f32_e32 v130, v130, v61
	v_fmac_f32_e32 v142, v61, v61
	s_waitcnt lgkmcnt(5)
	v_lshlrev_b32_e32 v152, 16, v184
	v_and_b32_e32 v153, 0xffff0000, v184
	v_lshlrev_b32_e32 v154, 16, v185
	v_and_b32_e32 v155, 0xffff0000, v185
	v_fmac_f32_e32 v54, s58, v152
	v_fmac_f32_e32 v55, s58, v153
	v_fmac_f32_e32 v56, s58, v154
	v_fmac_f32_e32 v57, s58, v155
	v_add_f32_e32 v196, v196, v54
	v_fmac_f32_e32 v197, v54, v54
	v_add_f32_e32 v130, v130, v55
	v_fmac_f32_e32 v142, v55, v55
	v_add_f32_e32 v196, v196, v56
	v_fmac_f32_e32 v197, v56, v56
	v_add_f32_e32 v130, v130, v57
	v_fmac_f32_e32 v142, v57, v57
	s_waitcnt lgkmcnt(4)
	v_lshlrev_b32_e32 v156, 16, v186
	v_and_b32_e32 v157, 0xffff0000, v186
	v_lshlrev_b32_e32 v158, 16, v187
	v_and_b32_e32 v159, 0xffff0000, v187
	v_fmac_f32_e32 v50, s58, v156
	v_fmac_f32_e32 v51, s58, v157
	v_fmac_f32_e32 v52, s58, v158
	v_fmac_f32_e32 v53, s58, v159
	v_add_f32_e32 v196, v196, v50
	v_fmac_f32_e32 v197, v50, v50
	v_add_f32_e32 v130, v130, v51
	v_fmac_f32_e32 v142, v51, v51
	v_add_f32_e32 v196, v196, v52
	v_fmac_f32_e32 v197, v52, v52
	v_add_f32_e32 v130, v130, v53
	v_fmac_f32_e32 v142, v53, v53
	s_waitcnt lgkmcnt(3)
	v_lshlrev_b32_e32 v160, 16, v188
	v_and_b32_e32 v161, 0xffff0000, v188
	v_lshlrev_b32_e32 v162, 16, v189
	v_and_b32_e32 v163, 0xffff0000, v189
	v_fmac_f32_e32 v46, s58, v160
	v_fmac_f32_e32 v47, s58, v161
	v_fmac_f32_e32 v48, s58, v162
	v_fmac_f32_e32 v49, s58, v163
	v_add_f32_e32 v196, v196, v46
	v_fmac_f32_e32 v197, v46, v46
	v_add_f32_e32 v130, v130, v47
	v_fmac_f32_e32 v142, v47, v47
	v_add_f32_e32 v196, v196, v48
	v_fmac_f32_e32 v197, v48, v48
	v_add_f32_e32 v130, v130, v49
	v_fmac_f32_e32 v142, v49, v49
	s_waitcnt lgkmcnt(2)
	v_lshlrev_b32_e32 v164, 16, v190
	v_and_b32_e32 v165, 0xffff0000, v190
	v_lshlrev_b32_e32 v166, 16, v191
	v_and_b32_e32 v167, 0xffff0000, v191
	v_fmac_f32_e32 v42, s58, v164
	v_fmac_f32_e32 v43, s58, v165
	v_fmac_f32_e32 v44, s58, v166
	v_fmac_f32_e32 v45, s58, v167
	v_add_f32_e32 v196, v196, v42
	v_fmac_f32_e32 v197, v42, v42
	v_add_f32_e32 v130, v130, v43
	v_fmac_f32_e32 v142, v43, v43
	v_add_f32_e32 v196, v196, v44
	v_fmac_f32_e32 v197, v44, v44
	v_add_f32_e32 v130, v130, v45
	v_fmac_f32_e32 v142, v45, v45
	s_waitcnt lgkmcnt(1)
	v_lshlrev_b32_e32 v168, 16, v192
	v_and_b32_e32 v169, 0xffff0000, v192
	v_lshlrev_b32_e32 v170, 16, v193
	v_and_b32_e32 v171, 0xffff0000, v193
	v_fmac_f32_e32 v38, s58, v168
	v_fmac_f32_e32 v39, s58, v169
	v_fmac_f32_e32 v40, s58, v170
	v_fmac_f32_e32 v41, s58, v171
	v_add_f32_e32 v196, v196, v38
	v_fmac_f32_e32 v197, v38, v38
	v_add_f32_e32 v130, v130, v39
	v_fmac_f32_e32 v142, v39, v39
	v_add_f32_e32 v196, v196, v40
	v_fmac_f32_e32 v197, v40, v40
	v_add_f32_e32 v130, v130, v41
	v_fmac_f32_e32 v142, v41, v41
	s_waitcnt lgkmcnt(0)
	v_lshlrev_b32_e32 v172, 16, v194
	v_and_b32_e32 v173, 0xffff0000, v194
	v_lshlrev_b32_e32 v174, 16, v195
	v_and_b32_e32 v175, 0xffff0000, v195
	v_fmac_f32_e32 v2, s58, v172
	v_fmac_f32_e32 v3, s58, v173
	v_fmac_f32_e32 v4, s58, v174
	v_fmac_f32_e32 v5, s58, v175
	v_add_f32_e32 v196, v196, v2
	v_fmac_f32_e32 v197, v2, v2
	v_add_f32_e32 v130, v130, v3
	v_fmac_f32_e32 v142, v3, v3
	v_add_f32_e32 v196, v196, v4
	v_fmac_f32_e32 v197, v4, v4
	v_add_f32_e32 v130, v130, v5
	v_fmac_f32_e32 v142, v5, v5
	v_add_f32_e32 v196, v196, v130
	v_add_f32_e32 v197, v197, v142
	v_mov_b32_e32 v198, v196
	v_mov_b32_e32 v199, v197
	s_nop 1
	v_permlane16_swap_b32 v198, v196
	v_permlane16_swap_b32 v199, v197
	v_add_f32_e32 v196, v196, v198
	v_add_f32_e32 v197, v197, v199
	v_mov_b32_e32 v198, v196
	v_mov_b32_e32 v199, v197
	s_nop 1
	v_permlane32_swap_b32 v198, v196
	v_permlane32_swap_b32 v199, v197
	v_add_f32_e32 v196, v196, v198
	v_add_f32_e32 v197, v197, v199
	s_mov_b64 exec, 0xffff
	ds_write_b64 v134, v[196:197]
	s_mov_b64 exec, -1
	s_waitcnt lgkmcnt(0)
	s_barrier
; DI unsigned pk2(float lo, float hi) { const f32x2 v = {lo, hi}; const bf16x2_t b = __builtin_convertvector(v, bf16x2_t); return __builtin_bit_cast(unsigned, b); }
; DI size_t xb_off(int tok, int col) { return ((size_t)(((tok >> 7) * 32 + (col >> 5)) * 128 + (tok & 127))) * 32 + (col & 31); }
; DI void unit_O(const Params& p, char* lds, int l, int tile, int glu_tiles, int tile_b) {
;     ...
;             float s = 0.f, ss = 0.f;
; #pragma unroll
;             for (int w = 0; w < 4; ++w) { const f32x4 v = *(const f32x4*)&red[rl * 16 + 4 * w]; s += v[0] + v[2]; ss += v[1] + v[3]; }
;             const float mu = s * (1.f / 1024.f);
;             const float var = ss * (1.f / 1024.f) - mu * mu;
;             const float rs = rsqrtf(var + LN_EPS);
;             float* orow = xo + (r0 + row) * 1024 + wid * 128 + quad * 4;
;             bf16_t* brow = xbo + xb_off((int)r0 + row, wid * 128) + quad * 4;
;             const float* gp = GB + wid * 128 + quad * 4;
; #pragma unroll
;             for (int nt = 0; nt < 8; ++nt) {
;                 const f32x4 g = *(const f32x4*)(gp + nt * 16), bb = *(const f32x4*)(gp + 1024 + nt * 16);
;                 f32x4 o;
; #pragma unroll
;                 for (int i = 0; i < 4; ++i) o[i] = (acc[mt][nt][i] - mu) * rs * g[i] + bb[i];
;                 if (l == 0) *(u32x2*)(brow + (nt >> 1) * 4096 + (nt & 1) * 16) = (u32x2){pk2(o[0], o[1]), pk2(o[2], o[3])};
;                 else *(f32x4*)(orow + nt * 16) = o;
;             }
;         }
	ds_read_b128 v[160:163], v135 offset:0
	ds_read_b128 v[164:167], v135 offset:16
	ds_read_b128 v[168:171], v135 offset:32
	ds_read_b128 v[172:175], v135 offset:48
	s_waitcnt lgkmcnt(0)
	v_add_f32_e32 v160, v160, v162
	v_add_f32_e32 v161, v161, v163
	v_add_f32_e32 v164, v164, v166
	v_add_f32_e32 v165, v165, v167
	v_add_f32_e32 v168, v168, v170
	v_add_f32_e32 v169, v169, v171
	v_add_f32_e32 v172, v172, v174
	v_add_f32_e32 v173, v173, v175
	v_add_f32_e32 v160, v160, v164
	v_add_f32_e32 v161, v161, v165
	v_add_f32_e32 v168, v168, v172
	v_add_f32_e32 v169, v169, v173
	v_add_f32_e32 v160, v160, v168
	v_add_f32_e32 v161, v161, v169
	v_mul_f32_e32 v192, 0x3a800000, v160
	v_mul_f32_e32 v193, 0x3a800000, v161
	v_fma_f32 v193, -v192, v192, v193
	v_add_f32_e32 v193, 0x3727c5ac, v193
	v_rsq_f32_e32 v193, v193
	s_nop 0
	s_add_u32 s94, s78, 0x30000
	s_addc_u32 s95, s79, 0
	ds_read_b128 v[176:179], v136
	ds_read_b128 v[180:183], v136 offset:4096
	ds_read_b128 v[184:187], v136 offset:64
	ds_read_b128 v[188:191], v136 offset:4160
	s_waitcnt lgkmcnt(2)
	v_sub_f32_e32 v62, v62, v192
	v_mul_f32_e32 v62, v62, v193
	v_fma_f32 v62, v176, v62, v180
	v_sub_f32_e32 v63, v63, v192
	v_mul_f32_e32 v63, v63, v193
	v_fma_f32 v63, v177, v63, v181
	v_sub_f32_e32 v64, v64, v192
	v_mul_f32_e32 v64, v64, v193
	v_fma_f32 v64, v178, v64, v182
	v_sub_f32_e32 v65, v65, v192
	v_mul_f32_e32 v65, v65, v193
	v_fma_f32 v65, v179, v65, v183
	global_store_dwordx4 v137, v[62:65], s[94:95]
	ds_read_b128 v[176:179], v136 offset:128
	ds_read_b128 v[180:183], v136 offset:4224
	s_waitcnt lgkmcnt(2)
	v_sub_f32_e32 v58, v58, v192
	v_mul_f32_e32 v58, v58, v193
	v_fma_f32 v58, v184, v58, v188
	v_sub_f32_e32 v59, v59, v192
	v_mul_f32_e32 v59, v59, v193
	v_fma_f32 v59, v185, v59, v189
	v_sub_f32_e32 v60, v60, v192
	v_mul_f32_e32 v60, v60, v193
	v_fma_f32 v60, v186, v60, v190
	v_sub_f32_e32 v61, v61, v192
	v_mul_f32_e32 v61, v61, v193
	v_fma_f32 v61, v187, v61, v191
	global_store_dwordx4 v137, v[58:61], s[94:95] offset:64
	ds_read_b128 v[184:187], v136 offset:192
	ds_read_b128 v[188:191], v136 offset:4288
	s_waitcnt lgkmcnt(2)
	v_sub_f32_e32 v54, v54, v192
	v_mul_f32_e32 v54, v54, v193
	v_fma_f32 v54, v176, v54, v180
	v_sub_f32_e32 v55, v55, v192
	v_mul_f32_e32 v55, v55, v193
	v_fma_f32 v55, v177, v55, v181
	v_sub_f32_e32 v56, v56, v192
	v_mul_f32_e32 v56, v56, v193
	v_fma_f32 v56, v178, v56, v182
	v_sub_f32_e32 v57, v57, v192
	v_mul_f32_e32 v57, v57, v193
	v_fma_f32 v57, v179, v57, v183
	global_store_dwordx4 v137, v[54:57], s[94:95] offset:128
	ds_read_b128 v[176:179], v136 offset:256
	ds_read_b128 v[180:183], v136 offset:4352
	s_waitcnt lgkmcnt(2)
	v_sub_f32_e32 v50, v50, v192
	v_mul_f32_e32 v50, v50, v193
	v_fma_f32 v50, v184, v50, v188
	v_sub_f32_e32 v51, v51, v192
	v_mul_f32_e32 v51, v51, v193
	v_fma_f32 v51, v185, v51, v189
	v_sub_f32_e32 v52, v52, v192
	v_mul_f32_e32 v52, v52, v193
	v_fma_f32 v52, v186, v52, v190
	v_sub_f32_e32 v53, v53, v192
	v_mul_f32_e32 v53, v53, v193
	v_fma_f32 v53, v187, v53, v191
	global_store_dwordx4 v137, v[50:53], s[94:95] offset:192
	ds_read_b128 v[184:187], v136 offset:320
	ds_read_b128 v[188:191], v136 offset:4416
	s_waitcnt lgkmcnt(2)
	v_sub_f32_e32 v46, v46, v192
	v_mul_f32_e32 v46, v46, v193
	v_fma_f32 v46, v176, v46, v180
	v_sub_f32_e32 v47, v47, v192
	v_mul_f32_e32 v47, v47, v193
	v_fma_f32 v47, v177, v47, v181
	v_sub_f32_e32 v48, v48, v192
	v_mul_f32_e32 v48, v48, v193
	v_fma_f32 v48, v178, v48, v182
	v_sub_f32_e32 v49, v49, v192
	v_mul_f32_e32 v49, v49, v193
	v_fma_f32 v49, v179, v49, v183
	global_store_dwordx4 v137, v[46:49], s[94:95] offset:256
	ds_read_b128 v[176:179], v136 offset:384
	ds_read_b128 v[180:183], v136 offset:4480
	s_waitcnt lgkmcnt(2)
	v_sub_f32_e32 v42, v42, v192
	v_mul_f32_e32 v42, v42, v193
	v_fma_f32 v42, v184, v42, v188
	v_sub_f32_e32 v43, v43, v192
	v_mul_f32_e32 v43, v43, v193
	v_fma_f32 v43, v185, v43, v189
	v_sub_f32_e32 v44, v44, v192
	v_mul_f32_e32 v44, v44, v193
	v_fma_f32 v44, v186, v44, v190
	v_sub_f32_e32 v45, v45, v192
	v_mul_f32_e32 v45, v45, v193
	v_fma_f32 v45, v187, v45, v191
	global_store_dwordx4 v137, v[42:45], s[94:95] offset:320
	ds_read_b128 v[184:187], v136 offset:448
	ds_read_b128 v[188:191], v136 offset:4544
	s_waitcnt lgkmcnt(2)
	v_sub_f32_e32 v38, v38, v192
	v_mul_f32_e32 v38, v38, v193
	v_fma_f32 v38, v176, v38, v180
	v_sub_f32_e32 v39, v39, v192
	v_mul_f32_e32 v39, v39, v193
	v_fma_f32 v39, v177, v39, v181
	v_sub_f32_e32 v40, v40, v192
	v_mul_f32_e32 v40, v40, v193
	v_fma_f32 v40, v178, v40, v182
	v_sub_f32_e32 v41, v41, v192
	v_mul_f32_e32 v41, v41, v193
	v_fma_f32 v41, v179, v41, v183
	global_store_dwordx4 v137, v[38:41], s[94:95] offset:384
	s_waitcnt lgkmcnt(0)
	v_sub_f32_e32 v2, v2, v192
	v_mul_f32_e32 v2, v2, v193
	v_fma_f32 v2, v184, v2, v188
	v_sub_f32_e32 v3, v3, v192
	v_mul_f32_e32 v3, v3, v193
	v_fma_f32 v3, v185, v3, v189
	v_sub_f32_e32 v4, v4, v192
	v_mul_f32_e32 v4, v4, v193
	v_fma_f32 v4, v186, v4, v190
	v_sub_f32_e32 v5, v5, v192
	v_mul_f32_e32 v5, v5, v193
	v_fma_f32 v5, v187, v5, v191
	global_store_dwordx4 v137, v[2:5], s[94:95] offset:448
.Le2_done:
	s_branch .LBB0_85
